# PEER down+up phases restructured: table slices L2-resident per XCD (down pass-major with LDS accumulation, up column-sliced+pipelined, last layer pass-major with in-place final norm)
# speedup vs baseline: 1.1493x; 1.0849x over previous
; __device__ __forceinline__ void cvt_fp8(const Ctx& C, const float* src, unsigned char* dst, size_t n, float sc, const float* gain  ) {
;     int lane = threadIdx.x & 63; asm volatile("" : "+v"(lane));
;     const size_t nth = (size_t)C.ngw * 64, n16 = n / 16;
;     for (size_t i = (size_t)C.gw * 64 + lane; i < n16; i += 2 * nth) {
;         const size_t i2 = i + nth; const bool has2 = i2 < n16;
;         const f32x4* sp = (const f32x4*)(src + i * 16); const f32x4* sp2 = (const f32x4*)(src + (has2 ? i2 : i) * 16);
; __global__ void __launch_bounds__(512, 2) mk_fwd(Args a) {
;     ...
;             if (ph == 0 || l > 0) { cvt_fp8(C, a.in[16] + (size_t)l * NEXP * DM, EXP8, (size_t)NEXP * DM, EXP_SC_D, a.in[13] + l * DM); cvt_fp8(C, a.in[17] + (size_t)l * NEXP * DM, EXP8 + (size_t)NEXP * DM, (size_t)NEXP * DM, EXP_SC_U, nullptr); }
.LBB0_119:
	v_readlane_b32 s0, v247, 55
	s_cmp_lg_u32 s0, 1
	s_cselect_b64 s[8:9], -1, 0
	s_cmp_eq_u32 s0, 1
	v_readlane_b32 s10, v247, 56
	s_cselect_b64 s[0:1], -1, 0
	v_readlane_b32 s11, v247, 57
	s_cmp_lg_u32 s10, 0
	s_cselect_b64 s[10:11], -1, 0
	s_and_b64 s[0:1], s[0:1], s[10:11]
	s_or_b64 s[0:1], s[4:5], s[0:1]
	s_andn2_b64 vcc, exec, s[0:1]
	s_cbranch_vccnz .LBB0_133
	v_readlane_b32 s0, v247, 53
	v_readlane_b32 s1, v247, 54
	v_mov_b32_e32 v2, v177
	s_ashr_i32 s1, s0, 31
	v_writelane_b32 v247, s0, 53
	s_lshl_b64 s[10:11], s[0:1], 6
	v_ashrrev_i32_e32 v3, 31, v2
	v_writelane_b32 v247, s1, 54
	v_lshl_add_u64 v[0:1], s[10:11], 0, v[2:3]
	s_mov_b64 s[0:1], 0x100000
	v_cmp_gt_u64_e32 vcc, s[0:1], v[0:1]
	s_and_saveexec_b64 s[12:13], vcc
	s_cbranch_execz .LBB0_127
	s_lshl_b64 s[0:1], s[6:7], 2
	v_readlane_b32 s20, v249, 0
	v_readlane_b32 s21, v249, 1
	s_add_u32 s14, s20, s0
	v_readlane_b32 s18, v247, 56
	v_readlane_b32 s22, v249, 2
	v_readlane_b32 s23, v249, 3
	s_addc_u32 s15, s21, s1
	s_lshl_b32 s2, s18, 10
	v_readlane_b32 s36, v248, 45
	s_lshl_b64 s[0:1], s[2:3], 2
	v_readlane_b32 s46, v248, 55
	v_readlane_b32 s22, v247, 53
	v_readlane_b32 s19, v247, 57
	v_readlane_b32 s47, v248, 56
	s_add_u32 s16, s46, s0
	v_readlane_b32 s23, v247, 54
	s_addc_u32 s17, s47, s1
	s_lshl_b64 s[0:1], s[18:19], 26
	s_lshl_b64 s[18:19], s[22:23], 12
	s_add_u32 s0, s0, s18
	s_addc_u32 s1, s1, s19
	s_add_u32 s0, s20, s0
	v_readlane_b32 s37, v248, 46
	v_lshlrev_b64 v[4:5], 6, v[2:3]
	s_addc_u32 s1, s21, s1
	v_readlane_b32 s36, v247, 48
	v_lshl_add_u64 v[32:33], s[0:1], 0, v[4:5]
	s_lshl_b64 s[0:1], s[22:23], 10
	v_readlane_b32 s37, v247, 49
	v_lshl_add_u64 v[34:35], v[2:3], 4, s[0:1]
	s_add_u32 s0, s36, s10
	v_readlane_b32 s38, v248, 47
	v_readlane_b32 s39, v248, 48
	v_readlane_b32 s18, v249, 20
	s_addc_u32 s1, s37, s11
	v_readlane_b32 s38, v247, 50
	v_readlane_b32 s34, v247, 42
	v_readlane_b32 s19, v249, 21
	v_lshl_add_u64 v[2:3], s[0:1], 0, v[2:3]
	v_readlane_b32 s39, v247, 51
	v_readlane_b32 s35, v247, 43
	v_lshl_add_u64 v[36:37], s[18:19], 0, v[34:35]
	v_lshl_add_u64 v[38:39], v[2:3], 4, s[18:19]
	s_mov_b64 s[18:19], 0
	s_mov_b64 s[20:21], 0
	v_readlane_b32 s24, v249, 4
	v_readlane_b32 s25, v249, 5
	v_readlane_b32 s26, v249, 6
	v_readlane_b32 s27, v249, 7
	v_readlane_b32 s40, v248, 49
	v_readlane_b32 s41, v248, 50
	v_readlane_b32 s42, v248, 51
	v_readlane_b32 s43, v248, 52
	v_readlane_b32 s44, v248, 53
	v_readlane_b32 s45, v248, 54
	v_readlane_b32 s48, v248, 57
	v_readlane_b32 s49, v248, 58
	v_readlane_b32 s50, v248, 59
	v_readlane_b32 s51, v248, 60
	v_readlane_b32 s24, v249, 20
	v_readlane_b32 s25, v249, 21
	s_branch .LBB0_123

; __device__ __forceinline__ unsigned pack_fp8x4(f32x4 v, float sc) { int r = 0; r = __builtin_amdgcn_cvt_pk_fp8_f32(v.x * sc, v.y * sc, r, false); r = __builtin_amdgcn_cvt_pk_fp8_f32(v.z * sc, v.w * sc, r, true); return (unsigned)r; }
; __device__ __forceinline__ void cvt_fp8(const Ctx& C, const float* src, unsigned char* dst, size_t n, float sc, const float* gain  ) {
;     ...
;         if (gain) { const f32x4* gp = (const f32x4*)(gain + ((i * 16) & 1023)); a = a * gp[0]; b = b * gp[1]; c = c * gp[2]; d = d * gp[3];
;                     const f32x4* gq = (const f32x4*)(gain + (((has2 ? i2 : i) * 16) & 1023)); a2 = a2 * gq[0]; b2 = b2 * gq[1]; c2 = c2 * gq[2]; d2 = d2 * gq[3]; }
;         v4u o; o.x = pack_fp8x4(a, sc); o.y = pack_fp8x4(b, sc); o.z = pack_fp8x4(c, sc); o.w = pack_fp8x4(d, sc);
;         *(v4u*)(dst + i * 16) = o;
;         if (has2) { v4u o2; o2.x = pack_fp8x4(a2, sc); o2.y = pack_fp8x4(b2, sc); o2.z = pack_fp8x4(c2, sc); o2.w = pack_fp8x4(d2, sc); *(v4u*)(dst + i2 * 16) = o2; }
.LBB0_125:
	s_waitcnt vmcnt(0)
	v_mul_f32_e32 v35, 0x43800000, v28
	v_mul_f32_e32 v29, 0x43800000, v29
	v_mov_b32_e32 v28, v137
	v_cvt_pk_fp8_f32 v28, v35, v29
	v_mul_f32_e32 v30, 0x43800000, v30
	v_mul_f32_e32 v31, 0x43800000, v31
	v_mul_f32_e32 v24, 0x43800000, v24
	v_mul_f32_e32 v25, 0x43800000, v25
	v_mov_b32_e32 v29, v137
	v_cvt_pk_fp8_f32 v28, v30, v31 op_sel:[0,0,1]
	v_mul_f32_e32 v20, 0x43800000, v20
	v_mul_f32_e32 v21, 0x43800000, v21
	v_mov_b32_e32 v30, v137
	v_mul_f32_e32 v12, 0x43800000, v12
	v_mul_f32_e32 v13, 0x43800000, v13
	v_mov_b32_e32 v31, v137
	v_cvt_pk_fp8_f32 v29, v24, v25
	v_cvt_pk_fp8_f32 v30, v20, v21
	v_cvt_pk_fp8_f32 v31, v12, v13
	v_mul_f32_e32 v24, 0x43800000, v26
	v_mul_f32_e32 v25, 0x43800000, v27
	v_mul_f32_e32 v20, 0x43800000, v22
	v_mul_f32_e32 v21, 0x43800000, v23
	v_mul_f32_e32 v12, 0x43800000, v14
	v_mul_f32_e32 v13, 0x43800000, v15
	v_cvt_pk_fp8_f32 v29, v24, v25 op_sel:[0,0,1]
	v_cvt_pk_fp8_f32 v30, v20, v21 op_sel:[0,0,1]
	v_cvt_pk_fp8_f32 v31, v12, v13 op_sel:[0,0,1]
	v_lshl_add_u64 v[12:13], v[36:37], 0, s[20:21]
	s_cmp_lg_u32 s98, 0x800
	s_cbranch_scc1 .Lcvtd_skip1
	v_subrev_u32_e32 v52, s24, v12
	v_lshrrev_b32_e32 v53, 10, v52
	v_bfe_u32 v54, v52, 7, 3
	v_and_b32_e32 v52, 0x7f, v52
	v_lshl_or_b32 v52, v53, 7, v52
	v_lshl_or_b32 v52, v54, 21, v52
	v_mov_b32_e32 v53, 0
	v_lshl_add_u64 v[12:13], s[24:25], 0, v[52:53]
.Lcvtd_skip1:
	global_store_dwordx4 v[12:13], v[28:31], off
	s_and_saveexec_b64 s[22:23], s[0:1]
	s_cbranch_execz .LBB0_122
	v_mul_f32_e32 v13, 0x43800000, v16
	v_mul_f32_e32 v14, 0x43800000, v17
	v_mov_b32_e32 v12, v137
	v_cvt_pk_fp8_f32 v12, v13, v14
	v_mul_f32_e32 v14, 0x43800000, v18
	v_mul_f32_e32 v15, 0x43800000, v19
	v_mul_f32_e32 v8, 0x43800000, v8
	v_mul_f32_e32 v9, 0x43800000, v9
	v_mov_b32_e32 v13, v137
	v_cvt_pk_fp8_f32 v12, v14, v15 op_sel:[0,0,1]
	v_mul_f32_e32 v4, 0x43800000, v4
	v_mul_f32_e32 v5, 0x43800000, v5
	v_mov_b32_e32 v14, v137
	v_mul_f32_e32 v0, 0x43800000, v0
	v_mul_f32_e32 v1, 0x43800000, v1
	v_mov_b32_e32 v15, v137
	v_cvt_pk_fp8_f32 v13, v8, v9
	v_cvt_pk_fp8_f32 v14, v4, v5
	v_cvt_pk_fp8_f32 v15, v0, v1
	v_mul_f32_e32 v8, 0x43800000, v10
	v_mul_f32_e32 v9, 0x43800000, v11
	v_mul_f32_e32 v4, 0x43800000, v6
	v_mul_f32_e32 v5, 0x43800000, v7
	v_mul_f32_e32 v0, 0x43800000, v2
	v_mul_f32_e32 v1, 0x43800000, v3
	v_cvt_pk_fp8_f32 v13, v8, v9 op_sel:[0,0,1]
	v_cvt_pk_fp8_f32 v14, v4, v5 op_sel:[0,0,1]
	v_cvt_pk_fp8_f32 v15, v0, v1 op_sel:[0,0,1]
	v_lshl_add_u64 v[0:1], v[38:39], 0, s[20:21]
	s_cmp_lg_u32 s98, 0x800
	s_cbranch_scc1 .Lcvtd_skip2
	v_subrev_u32_e32 v52, s24, v0
	v_lshrrev_b32_e32 v53, 10, v52
	v_bfe_u32 v54, v52, 7, 3
	v_and_b32_e32 v52, 0x7f, v52
	v_lshl_or_b32 v52, v53, 7, v52
	v_lshl_or_b32 v52, v54, 21, v52
	v_mov_b32_e32 v53, 0
	v_lshl_add_u64 v[0:1], s[24:25], 0, v[52:53]
.Lcvtd_skip2:
	global_store_dwordx4 v[0:1], v[12:15], off
	s_branch .LBB0_122

; __device__ __forceinline__ unsigned pack_fp8x4(f32x4 v, float sc) { int r = 0; r = __builtin_amdgcn_cvt_pk_fp8_f32(v.x * sc, v.y * sc, r, false); r = __builtin_amdgcn_cvt_pk_fp8_f32(v.z * sc, v.w * sc, r, true); return (unsigned)r; }
; __device__ __forceinline__ void cvt_fp8(const Ctx& C, const float* src, unsigned char* dst, size_t n, float sc, const float* gain  ) {
;     ...
;         v4u o; o.x = pack_fp8x4(a, sc); o.y = pack_fp8x4(b, sc); o.z = pack_fp8x4(c, sc); o.w = pack_fp8x4(d, sc);
;         *(v4u*)(dst + i * 16) = o;
;         if (has2) { v4u o2; o2.x = pack_fp8x4(a2, sc); o2.y = pack_fp8x4(b2, sc); o2.z = pack_fp8x4(c2, sc); o2.w = pack_fp8x4(d2, sc); *(v4u*)(dst + i2 * 16) = o2; }
.LBB0_130:
	v_lshl_add_u64 v[26:27], v[0:1], 0, s[36:37]
	s_mov_b64 s[14:15], 0x100000
	v_cmp_gt_u64_e32 vcc, s[14:15], v[26:27]
	s_nop 1
	v_cndmask_b32_e32 v1, v1, v27, vcc
	v_cndmask_b32_e32 v0, v0, v26, vcc
	v_lshlrev_b64 v[0:1], 6, v[0:1]
	v_lshl_add_u64 v[16:17], s[6:7], 0, v[0:1]
	global_load_dwordx4 v[0:3], v[20:21], off offset:48
	global_load_dwordx4 v[28:31], v[20:21], off offset:32
	global_load_dwordx4 v[32:35], v[20:21], off offset:16
	global_load_dwordx4 v[36:39], v[20:21], off
	global_load_dwordx4 v[4:7], v[16:17], off offset:48
	s_waitcnt lgkmcnt(0)
	global_load_dwordx4 v[8:11], v[16:17], off offset:32
	global_load_dwordx4 v[12:15], v[16:17], off offset:16
	s_nop 0
	global_load_dwordx4 v[16:19], v[16:17], off
	s_waitcnt vmcnt(0)
	v_mul_f32_e32 v0, 0x42800000, v0
	v_mul_f32_e32 v28, 0x42800000, v28
	v_mul_f32_e32 v32, 0x42800000, v32
	v_mul_f32_e32 v40, 0x42800000, v36
	v_mul_f32_e32 v37, 0x42800000, v37
	v_mov_b32_e32 v36, v137
	v_cvt_pk_fp8_f32 v36, v40, v37
	v_mul_f32_e32 v37, 0x42800000, v38
	v_mul_f32_e32 v38, 0x42800000, v39
	v_mul_f32_e32 v33, 0x42800000, v33
	v_cvt_pk_fp8_f32 v36, v37, v38 op_sel:[0,0,1]
	v_mov_b32_e32 v37, v137
	v_mul_f32_e32 v29, 0x42800000, v29
	v_mov_b32_e32 v38, v137
	v_mul_f32_e32 v1, 0x42800000, v1
	v_mov_b32_e32 v39, v137
	v_cvt_pk_fp8_f32 v37, v32, v33
	v_cvt_pk_fp8_f32 v38, v28, v29
	v_cvt_pk_fp8_f32 v39, v0, v1
	v_mul_f32_e32 v32, 0x42800000, v34
	v_mul_f32_e32 v33, 0x42800000, v35
	v_mul_f32_e32 v28, 0x42800000, v30
	v_mul_f32_e32 v29, 0x42800000, v31
	v_mul_f32_e32 v0, 0x42800000, v2
	v_mul_f32_e32 v1, 0x42800000, v3
	v_cvt_pk_fp8_f32 v37, v32, v33 op_sel:[0,0,1]
	v_cvt_pk_fp8_f32 v38, v28, v29 op_sel:[0,0,1]
	v_cvt_pk_fp8_f32 v39, v0, v1 op_sel:[0,0,1]
	v_lshl_add_u64 v[0:1], s[12:13], 0, v[22:23]
	s_cmp_lt_u32 s18, 3
	s_cbranch_scc1 .Lcvt_do1
	s_cmp_lg_u32 s98, 0x800
	s_cbranch_scc1 .Lcvt_skip1
.Lcvt_do1:
	v_subrev_u32_e32 v42, s16, v0
	v_lshrrev_b32_e32 v43, 10, v42
	v_bfe_u32 v44, v42, 7, 3
	v_and_b32_e32 v42, 0x7f, v42
	v_lshl_or_b32 v42, v43, 7, v42
	v_lshl_or_b32 v42, v44, 21, v42
	v_mov_b32_e32 v43, 0
	v_lshl_add_u64 v[0:1], s[16:17], 0, v[42:43]
.Lcvt_skip1:
	global_store_dwordx4 v[0:1], v[36:39], off
	s_and_saveexec_b64 s[14:15], vcc
	s_cbranch_execz .LBB0_129
	v_mul_f32_e32 v1, 0x42800000, v16
	v_mul_f32_e32 v2, 0x42800000, v17
	v_mov_b32_e32 v0, v137
	v_cvt_pk_fp8_f32 v0, v1, v2
	v_mul_f32_e32 v12, 0x42800000, v12
	v_mul_f32_e32 v13, 0x42800000, v13
	v_mov_b32_e32 v1, v137
	v_cvt_pk_fp8_f32 v1, v12, v13
	v_mul_f32_e32 v2, 0x42800000, v18
	v_mul_f32_e32 v3, 0x42800000, v19
	v_cvt_pk_fp8_f32 v0, v2, v3 op_sel:[0,0,1]
	v_mul_f32_e32 v2, 0x42800000, v14
	v_mul_f32_e32 v3, 0x42800000, v15
	v_cvt_pk_fp8_f32 v1, v2, v3 op_sel:[0,0,1]
	v_mul_f32_e32 v3, 0x42800000, v8
	v_mul_f32_e32 v8, 0x42800000, v9
	v_mov_b32_e32 v2, v137
	v_cvt_pk_fp8_f32 v2, v3, v8
	v_mul_f32_e32 v4, 0x42800000, v4
	v_mul_f32_e32 v5, 0x42800000, v5
	v_mov_b32_e32 v3, v137
	v_cvt_pk_fp8_f32 v3, v4, v5
	v_mul_f32_e32 v8, 0x42800000, v10
	v_mul_f32_e32 v9, 0x42800000, v11
	v_mul_f32_e32 v4, 0x42800000, v6
	v_mul_f32_e32 v5, 0x42800000, v7
	v_cvt_pk_fp8_f32 v2, v8, v9 op_sel:[0,0,1]
	v_cvt_pk_fp8_f32 v3, v4, v5 op_sel:[0,0,1]
	v_lshl_add_u64 v[4:5], s[12:13], 0, v[24:25]
	s_cmp_lt_u32 s18, 3
	s_cbranch_scc1 .Lcvt_do2
	s_cmp_lg_u32 s98, 0x800
	s_cbranch_scc1 .Lcvt_skip2
.Lcvt_do2:
	v_subrev_u32_e32 v42, s16, v4
	v_lshrrev_b32_e32 v43, 10, v42
	v_bfe_u32 v44, v42, 7, 3
	v_and_b32_e32 v42, 0x7f, v42
	v_lshl_or_b32 v42, v43, 7, v42
	v_lshl_or_b32 v42, v44, 21, v42
	v_mov_b32_e32 v43, 0
	v_lshl_add_u64 v[4:5], s[16:17], 0, v[42:43]

; __device__ __forceinline__ void peer_down_phase(const Ctx& C, const unsigned char* ED, const bf16* HB, const float* RSS, float* SELG, const int* SELI) {
;     int gl = threadIdx.x & 63; asm volatile("" : "+v"(gl));
;     for (int wtile = C.gw; wtile < MTOK / 16; wtile += C.ngw) {
;         const int tok0 = wtile * 16;
;         int nvi0 = SELI[(size_t)tok0 * 128 + gl], nvi1 = SELI[(size_t)tok0 * 128 + 64 + gl]; float nvg0 = SELG[(size_t)tok0 * 128 + gl], nvg1 = SELG[(size_t)tok0 * 128 + 64 + gl];
;         v4u nh0 = __builtin_nontemporal_load((const v4u*)(HB + (size_t)tok0 * DM + 16 * gl)), nh1 = __builtin_nontemporal_load((const v4u*)(HB + (size_t)tok0 * DM + 16 * gl + 8));
;         float nrs = gl < 16 ? RSS[(size_t)tok0 * 16 + gl] : 0.f;
.LBB0_205:
	v_readlane_b32 s0, v247, 53
	v_mov_b32_e32 v104, v177
	s_cmpk_gt_i32 s0, 0xfff
	v_readlane_b32 s1, v247, 54
	s_cbranch_scc1 .LBB0_226
	s_cmp_eq_u32 s98, 0x800
	s_cbranch_scc1 .Ldn_new
	v_and_b32_e32 v2, 64, v181
	v_add_u32_e32 v2, 64, v2
	v_xor_b32_e32 v3, 1, v181
	v_cmp_lt_i32_e32 vcc, v3, v2
	v_lshlrev_b32_e32 v0, 4, v104
	v_readlane_b32 s0, v249, 20
	v_cndmask_b32_e32 v3, v181, v3, vcc
	v_lshlrev_b32_e32 v134, 2, v3
	v_xor_b32_e32 v3, 2, v181
	v_cmp_lt_i32_e32 vcc, v3, v2
	v_ashrrev_i32_e32 v1, 31, v0
	v_readlane_b32 s1, v249, 21
	v_cndmask_b32_e32 v3, v181, v3, vcc
	v_lshlrev_b32_e32 v135, 2, v3
	v_xor_b32_e32 v3, 4, v181
	v_cmp_lt_i32_e32 vcc, v3, v2
	v_lshl_add_u64 v[106:107], v[0:1], 1, s[60:61]
	v_lshl_add_u64 v[110:111], s[0:1], 0, v[0:1]
	v_cndmask_b32_e32 v3, v181, v3, vcc
	v_lshlrev_b32_e32 v136, 2, v3
	v_xor_b32_e32 v3, 8, v181
	v_cmp_lt_i32_e32 vcc, v3, v2
	v_and_b32_e32 v0, 32, v104
	v_cmp_eq_u32_e64 s[40:41], 0, v0
	v_cndmask_b32_e32 v3, v181, v3, vcc
	v_lshlrev_b32_e32 v139, 2, v3
	v_xor_b32_e32 v3, 16, v181
	v_cmp_lt_i32_e32 vcc, v3, v2
	v_and_b32_e32 v0, 16, v104
	v_cmp_eq_u32_e64 s[42:43], 0, v0
	v_cndmask_b32_e32 v3, v181, v3, vcc
	v_and_b32_e32 v0, 8, v104
	v_lshlrev_b32_e32 v141, 2, v3
	v_xor_b32_e32 v3, 32, v181
	v_cmp_eq_u32_e64 s[44:45], 0, v0
	v_ashrrev_i32_e32 v0, 3, v104
	v_and_b32_e32 v1, 7, v104
	v_readlane_b32 s0, v247, 35
	v_cmp_lt_i32_e32 vcc, v3, v2
	v_cmp_eq_u32_e64 s[46:47], 0, v1
	v_ashrrev_i32_e32 v1, 31, v0
	v_readlane_b32 s1, v247, 36
	v_ashrrev_i32_e32 v105, 31, v104
	v_cndmask_b32_e32 v2, v181, v3, vcc
	v_lshl_add_u64 v[112:113], v[0:1], 2, s[0:1]
	v_readlane_b32 s0, v247, 53
	v_cmp_gt_i32_e64 s[38:39], 16, v104
	v_lshl_add_u64 v[108:109], v[104:105], 2, s[92:93]
	v_lshlrev_b32_e32 v142, 2, v2
	v_and_b32_e32 v143, 7, v0
	s_lshl_b32 s6, s0, 4
	s_mov_b32 s2, s0
	v_readlane_b32 s1, v247, 54
	s_branch .LBB0_208

; __device__ __forceinline__ void peer_down_phase(const Ctx& C, const unsigned char* ED, const bf16* HB, const float* RSS, float* SELG, const int* SELI) {
;     int gl = threadIdx.x & 63; asm volatile("" : "+v"(gl));
;     for (int wtile = C.gw; wtile < MTOK / 16; wtile += C.ngw) {
;         const int tok0 = wtile * 16;
;         int nvi0 = SELI[(size_t)tok0 * 128 + gl], nvi1 = SELI[(size_t)tok0 * 128 + 64 + gl]; float nvg0 = SELG[(size_t)tok0 * 128 + gl], nvg1 = SELG[(size_t)tok0 * 128 + 64 + gl];
;         v4u nh0 = __builtin_nontemporal_load((const v4u*)(HB + (size_t)tok0 * DM + 16 * gl)), nh1 = __builtin_nontemporal_load((const v4u*)(HB + (size_t)tok0 * DM + 16 * gl + 8));
;         float nrs = gl < 16 ? RSS[(size_t)tok0 * 16 + gl] : 0.f;
;         for (int ti = 0; ti < 16; ++ti) {
;             const size_t tok = (size_t)tok0 + ti;
;             const int vi0 = nvi0, vi1 = nvi1; const float vg0 = nvg0, vg1 = nvg1; const v4u h0 = nh0, h1 = nh1;
;             const float rstd_h = 1.0f / sqrtf(wave_sum(nrs) * (1.f / DM) + RMS_EPS);
;             if (ti + 1 < 16) { const size_t tn = tok + 1;
;                 nvi0 = SELI[tn * 128 + gl]; nvi1 = SELI[tn * 128 + 64 + gl]; nvg0 = SELG[tn * 128 + gl]; nvg1 = SELG[tn * 128 + 64 + gl];
;                 nh0 = __builtin_nontemporal_load((const v4u*)(HB + tn * DM + 16 * gl)); nh1 = __builtin_nontemporal_load((const v4u*)(HB + tn * DM + 16 * gl + 8));
;                 nrs = gl < 16 ? RSS[tn * 16 + gl] : 0.f; }
;             v2f hf[8];
; #pragma unroll
;             for (int w = 0; w < 4; ++w) { hf[w] = (v2f){bflo(h0[w]), bfhi(h0[w])}; hf[4 + w] = (v2f){bflo(h1[w]), bfhi(h1[w])}; }
;             v4u dnA[8], dnB[8]; int eidA[8], eidB[8];
; #pragma unroll
;             for (int k = 0; k < 8; ++k) { eidA[k] = __builtin_amdgcn_readlane(vi0, k); dnA[k] = *(const v4u*)(ED + (size_t)eidA[k] * DM + 16 * gl); }
; #pragma unroll
;             for (int k = 0; k < 8; ++k) { eidB[k] = __builtin_amdgcn_readlane(vi0, 8 + k); dnB[k] = *(const v4u*)(ED + (size_t)eidB[k] * DM + 16 * gl); }
.Ldn_new:
	v_readlane_b32 s0, v247, 53
	v_readlane_b32 s6, v249, 8
	v_readlane_b32 s7, v249, 9
	s_and_b32 s2, s0, 7
	s_lshl_b32 s40, s0, 5
	s_lshl_b32 s1, s2, 14
	s_lshl_b32 s41, s2, 9
	s_add_i32 s41, s41, 0x20000
	s_add_u32 s42, s6, 0x5600000
	s_addc_u32 s43, s7, 0
	s_add_u32 s44, s6, 0x2b600000
	s_addc_u32 s45, s7, 0
	s_add_u32 s6, s6, 0x2d600000
	s_addc_u32 s7, s7, 0
	v_and_b32_e32 v1, 7, v177
	v_lshlrev_b32_e32 v5, 5, v1
	v_lshlrev_b32_e32 v1, 4, v1
	v_lshrrev_b32_e32 v2, 3, v177
	v_lshl_add_u32 v2, v2, 2, s41
	v_lshlrev_b32_e32 v4, 2, v177
	v_add_u32_e32 v3, s41, v4
	v_add_u32_e32 v130, s1, v4
	v_lshlrev_b32_e32 v128, 4, v177
	v_add_u32_e32 v128, s1, v128
	v_mov_b32_e32 v132, 0
	v_mov_b32_e32 v133, 0
	v_mov_b32_e32 v134, 0
	v_mov_b32_e32 v135, 0
	ds_write_b128 v128, v[132:135]
	ds_write_b128 v128, v[132:135] offset:1024
	ds_write_b128 v128, v[132:135] offset:2048
	ds_write_b128 v128, v[132:135] offset:3072
	ds_write_b128 v128, v[132:135] offset:4096
	ds_write_b128 v128, v[132:135] offset:5120
	ds_write_b128 v128, v[132:135] offset:6144
	ds_write_b128 v128, v[132:135] offset:7168
	ds_write_b128 v128, v[132:135] offset:8192
	ds_write_b128 v128, v[132:135] offset:9216
	ds_write_b128 v128, v[132:135] offset:10240
	ds_write_b128 v128, v[132:135] offset:11264
	ds_write_b128 v128, v[132:135] offset:12288
	ds_write_b128 v128, v[132:135] offset:13312
	ds_write_b128 v128, v[132:135] offset:14336
	ds_write_b128 v128, v[132:135] offset:15360
	s_mov_b32 s46, 0x01010101
	s_mov_b32 s47, 0x01010101
	s_mov_b32 s38, 0
.Ldn_pass:
	s_lshl_b32 s0, s38, 21
	s_add_u32 s8, s42, s0
	s_addc_u32 s9, s43, 0
	s_lshl_b32 s0, s38, 8
	s_add_u32 s10, s60, s0
	s_addc_u32 s11, s61, 0
	s_mov_b32 s39, 0
	s_lshl_b32 s0, s40, 9
	s_add_u32 s12, s6, s0
	s_addc_u32 s13, s7, 0
	global_load_dword v6, v4, s[12:13]
	global_load_dword v7, v4, s[12:13] offset:256
.Ldn_tok:
	s_add_i32 s0, s40, s39
	s_lshl_b32 s0, s0, 11
	s_add_u32 s14, s10, s0
	s_addc_u32 s15, s11, 0
	s_waitcnt vmcnt(0)
	ds_write_b32 v3, v6
	ds_write_b32 v3, v7 offset:256
	global_load_dwordx4 v[8:11], v5, s[14:15]
	global_load_dwordx4 v[12:15], v5, s[14:15] offset:16
	s_add_i32 s0, s39, 1
	s_and_b32 s0, s0, 31
	s_add_i32 s0, s0, s40
	s_lshl_b32 s0, s0, 9
	s_add_u32 s12, s6, s0
	s_addc_u32 s13, s7, 0
	global_load_dword v6, v4, s[12:13]
	global_load_dword v7, v4, s[12:13] offset:256
	ds_read_b32 v32, v2
	ds_read_b32 v33, v2 offset:32
	ds_read_b32 v34, v2 offset:64
	ds_read_b32 v35, v2 offset:96
	ds_read_b32 v36, v2 offset:128
	ds_read_b32 v37, v2 offset:160
	ds_read_b32 v38, v2 offset:192
	ds_read_b32 v39, v2 offset:224
	ds_read_b32 v40, v2 offset:256
	ds_read_b32 v41, v2 offset:288
	ds_read_b32 v42, v2 offset:320
	ds_read_b32 v43, v2 offset:352
	ds_read_b32 v44, v2 offset:384
	ds_read_b32 v45, v2 offset:416
	ds_read_b32 v46, v2 offset:448
	ds_read_b32 v47, v2 offset:480
	s_waitcnt lgkmcnt(8)
	v_lshl_add_u32 v32, v32, 7, v1
	global_load_dwordx4 v[48:51], v32, s[8:9]
	v_lshl_add_u32 v33, v33, 7, v1
	global_load_dwordx4 v[52:55], v33, s[8:9]
	v_lshl_add_u32 v34, v34, 7, v1
	global_load_dwordx4 v[56:59], v34, s[8:9]
	v_lshl_add_u32 v35, v35, 7, v1
	global_load_dwordx4 v[60:63], v35, s[8:9]
	v_lshl_add_u32 v36, v36, 7, v1
	global_load_dwordx4 v[64:67], v36, s[8:9]
	v_lshl_add_u32 v37, v37, 7, v1
	global_load_dwordx4 v[68:71], v37, s[8:9]
	v_lshl_add_u32 v38, v38, 7, v1
	global_load_dwordx4 v[72:75], v38, s[8:9]
	v_lshl_add_u32 v39, v39, 7, v1
	global_load_dwordx4 v[76:79], v39, s[8:9]
	s_waitcnt lgkmcnt(0)
	v_lshl_add_u32 v40, v40, 7, v1
	global_load_dwordx4 v[80:83], v40, s[8:9]
	v_lshl_add_u32 v41, v41, 7, v1
	global_load_dwordx4 v[84:87], v41, s[8:9]
	v_lshl_add_u32 v42, v42, 7, v1
	global_load_dwordx4 v[88:91], v42, s[8:9]
	v_lshl_add_u32 v43, v43, 7, v1
	global_load_dwordx4 v[92:95], v43, s[8:9]
	v_lshl_add_u32 v44, v44, 7, v1
	global_load_dwordx4 v[96:99], v44, s[8:9]
	v_lshl_add_u32 v45, v45, 7, v1
	global_load_dwordx4 v[100:103], v45, s[8:9]
	v_lshl_add_u32 v46, v46, 7, v1
	global_load_dwordx4 v[108:111], v46, s[8:9]
	v_lshl_add_u32 v47, v47, 7, v1
	global_load_dwordx4 v[112:115], v47, s[8:9]
	s_waitcnt vmcnt(18)
	v_lshlrev_b32_e32 v16, 16, v8
	v_and_b32_e32 v17, 0xffff0000, v8
	v_lshlrev_b32_e32 v18, 16, v9
	v_and_b32_e32 v19, 0xffff0000, v9
	v_lshlrev_b32_e32 v20, 16, v10
	v_and_b32_e32 v21, 0xffff0000, v10
	v_lshlrev_b32_e32 v22, 16, v11
	v_and_b32_e32 v23, 0xffff0000, v11
	v_lshlrev_b32_e32 v24, 16, v12
	v_and_b32_e32 v25, 0xffff0000, v12
	v_lshlrev_b32_e32 v26, 16, v13
	v_and_b32_e32 v27, 0xffff0000, v13
	v_lshlrev_b32_e32 v28, 16, v14
	v_and_b32_e32 v29, 0xffff0000, v14
	v_lshlrev_b32_e32 v30, 16, v15
	v_and_b32_e32 v31, 0xffff0000, v15
	s_waitcnt vmcnt(15)
	v_cvt_pk_f32_fp8_e32 v[142:143], v48
	v_cvt_pk_f32_fp8_sdwa v[144:145], v48 src0_sel:WORD_1
	v_cvt_pk_f32_fp8_e32 v[146:147], v49
	v_cvt_pk_f32_fp8_sdwa v[148:149], v49 src0_sel:WORD_1
	v_cvt_pk_f32_fp8_e32 v[150:151], v50
	v_cvt_pk_f32_fp8_sdwa v[152:153], v50 src0_sel:WORD_1
	v_cvt_pk_f32_fp8_e32 v[154:155], v51
	v_cvt_pk_f32_fp8_sdwa v[156:157], v51 src0_sel:WORD_1
	v_pk_mul_f32 v[124:125], v[142:143], v[16:17]
	v_pk_mul_f32 v[126:127], v[144:145], v[18:19]
	v_pk_fma_f32 v[124:125], v[146:147], v[20:21], v[124:125]
	v_pk_fma_f32 v[126:127], v[148:149], v[22:23], v[126:127]
	v_pk_fma_f32 v[124:125], v[150:151], v[24:25], v[124:125]
	v_pk_fma_f32 v[126:127], v[152:153], v[26:27], v[126:127]
	v_pk_fma_f32 v[124:125], v[154:155], v[28:29], v[124:125]
	v_pk_fma_f32 v[126:127], v[156:157], v[30:31], v[126:127]
	v_pk_add_f32 v[124:125], v[124:125], v[126:127]
	v_add_f32_e32 v116, v124, v125
	s_waitcnt vmcnt(14)
	v_cvt_pk_f32_fp8_e32 v[142:143], v52
	v_cvt_pk_f32_fp8_sdwa v[144:145], v52 src0_sel:WORD_1
	v_cvt_pk_f32_fp8_e32 v[146:147], v53
	v_cvt_pk_f32_fp8_sdwa v[148:149], v53 src0_sel:WORD_1
	v_cvt_pk_f32_fp8_e32 v[150:151], v54
	v_cvt_pk_f32_fp8_sdwa v[152:153], v54 src0_sel:WORD_1
	v_cvt_pk_f32_fp8_e32 v[154:155], v55
	v_cvt_pk_f32_fp8_sdwa v[156:157], v55 src0_sel:WORD_1
	v_pk_mul_f32 v[124:125], v[142:143], v[16:17]
	v_pk_mul_f32 v[126:127], v[144:145], v[18:19]
	v_pk_fma_f32 v[124:125], v[146:147], v[20:21], v[124:125]
	v_pk_fma_f32 v[126:127], v[148:149], v[22:23], v[126:127]
	v_pk_fma_f32 v[124:125], v[150:151], v[24:25], v[124:125]
	v_pk_fma_f32 v[126:127], v[152:153], v[26:27], v[126:127]
	v_pk_fma_f32 v[124:125], v[154:155], v[28:29], v[124:125]
	v_pk_fma_f32 v[126:127], v[156:157], v[30:31], v[126:127]
	v_pk_add_f32 v[124:125], v[124:125], v[126:127]
	v_add_f32_e32 v117, v124, v125
	s_waitcnt vmcnt(13)
	v_cvt_pk_f32_fp8_e32 v[142:143], v56
	v_cvt_pk_f32_fp8_sdwa v[144:145], v56 src0_sel:WORD_1
	v_cvt_pk_f32_fp8_e32 v[146:147], v57
	v_cvt_pk_f32_fp8_sdwa v[148:149], v57 src0_sel:WORD_1
	v_cvt_pk_f32_fp8_e32 v[150:151], v58
	v_cvt_pk_f32_fp8_sdwa v[152:153], v58 src0_sel:WORD_1
	v_cvt_pk_f32_fp8_e32 v[154:155], v59
	v_cvt_pk_f32_fp8_sdwa v[156:157], v59 src0_sel:WORD_1
	v_pk_mul_f32 v[124:125], v[142:143], v[16:17]
	v_pk_mul_f32 v[126:127], v[144:145], v[18:19]
	v_pk_fma_f32 v[124:125], v[146:147], v[20:21], v[124:125]
	v_pk_fma_f32 v[126:127], v[148:149], v[22:23], v[126:127]
	v_pk_fma_f32 v[124:125], v[150:151], v[24:25], v[124:125]
	v_pk_fma_f32 v[126:127], v[152:153], v[26:27], v[126:127]
	v_pk_fma_f32 v[124:125], v[154:155], v[28:29], v[124:125]
	v_pk_fma_f32 v[126:127], v[156:157], v[30:31], v[126:127]
	v_pk_add_f32 v[124:125], v[124:125], v[126:127]
	v_add_f32_e32 v118, v124, v125
	s_waitcnt vmcnt(12)
	v_cvt_pk_f32_fp8_e32 v[142:143], v60
	v_cvt_pk_f32_fp8_sdwa v[144:145], v60 src0_sel:WORD_1
	v_cvt_pk_f32_fp8_e32 v[146:147], v61
	v_cvt_pk_f32_fp8_sdwa v[148:149], v61 src0_sel:WORD_1
	v_cvt_pk_f32_fp8_e32 v[150:151], v62
	v_cvt_pk_f32_fp8_sdwa v[152:153], v62 src0_sel:WORD_1
	v_cvt_pk_f32_fp8_e32 v[154:155], v63
	v_cvt_pk_f32_fp8_sdwa v[156:157], v63 src0_sel:WORD_1
	v_pk_mul_f32 v[124:125], v[142:143], v[16:17]
	v_pk_mul_f32 v[126:127], v[144:145], v[18:19]
	v_pk_fma_f32 v[124:125], v[146:147], v[20:21], v[124:125]
	v_pk_fma_f32 v[126:127], v[148:149], v[22:23], v[126:127]
	v_pk_fma_f32 v[124:125], v[150:151], v[24:25], v[124:125]
	v_pk_fma_f32 v[126:127], v[152:153], v[26:27], v[126:127]
	v_pk_fma_f32 v[124:125], v[154:155], v[28:29], v[124:125]
	v_pk_fma_f32 v[126:127], v[156:157], v[30:31], v[126:127]
	v_pk_add_f32 v[124:125], v[124:125], v[126:127]
	v_add_f32_e32 v119, v124, v125
	s_waitcnt vmcnt(11)
	v_cvt_pk_f32_fp8_e32 v[142:143], v64
	v_cvt_pk_f32_fp8_sdwa v[144:145], v64 src0_sel:WORD_1
	v_cvt_pk_f32_fp8_e32 v[146:147], v65
	v_cvt_pk_f32_fp8_sdwa v[148:149], v65 src0_sel:WORD_1
	v_cvt_pk_f32_fp8_e32 v[150:151], v66
	v_cvt_pk_f32_fp8_sdwa v[152:153], v66 src0_sel:WORD_1
	v_cvt_pk_f32_fp8_e32 v[154:155], v67
	v_cvt_pk_f32_fp8_sdwa v[156:157], v67 src0_sel:WORD_1
	v_pk_mul_f32 v[124:125], v[142:143], v[16:17]
	v_pk_mul_f32 v[126:127], v[144:145], v[18:19]
	v_pk_fma_f32 v[124:125], v[146:147], v[20:21], v[124:125]
	v_pk_fma_f32 v[126:127], v[148:149], v[22:23], v[126:127]
	v_pk_fma_f32 v[124:125], v[150:151], v[24:25], v[124:125]
	v_pk_fma_f32 v[126:127], v[152:153], v[26:27], v[126:127]
	v_pk_fma_f32 v[124:125], v[154:155], v[28:29], v[124:125]
	v_pk_fma_f32 v[126:127], v[156:157], v[30:31], v[126:127]
	v_pk_add_f32 v[124:125], v[124:125], v[126:127]
	v_add_f32_e32 v120, v124, v125
	s_waitcnt vmcnt(10)
	v_cvt_pk_f32_fp8_e32 v[142:143], v68
	v_cvt_pk_f32_fp8_sdwa v[144:145], v68 src0_sel:WORD_1
	v_cvt_pk_f32_fp8_e32 v[146:147], v69
	v_cvt_pk_f32_fp8_sdwa v[148:149], v69 src0_sel:WORD_1
	v_cvt_pk_f32_fp8_e32 v[150:151], v70
	v_cvt_pk_f32_fp8_sdwa v[152:153], v70 src0_sel:WORD_1
	v_cvt_pk_f32_fp8_e32 v[154:155], v71
	v_cvt_pk_f32_fp8_sdwa v[156:157], v71 src0_sel:WORD_1
	v_pk_mul_f32 v[124:125], v[142:143], v[16:17]
	v_pk_mul_f32 v[126:127], v[144:145], v[18:19]
	v_pk_fma_f32 v[124:125], v[146:147], v[20:21], v[124:125]
	v_pk_fma_f32 v[126:127], v[148:149], v[22:23], v[126:127]
	v_pk_fma_f32 v[124:125], v[150:151], v[24:25], v[124:125]
	v_pk_fma_f32 v[126:127], v[152:153], v[26:27], v[126:127]
	v_pk_fma_f32 v[124:125], v[154:155], v[28:29], v[124:125]
	v_pk_fma_f32 v[126:127], v[156:157], v[30:31], v[126:127]
	v_pk_add_f32 v[124:125], v[124:125], v[126:127]
	v_add_f32_e32 v121, v124, v125
	s_waitcnt vmcnt(9)
	v_cvt_pk_f32_fp8_e32 v[142:143], v72
	v_cvt_pk_f32_fp8_sdwa v[144:145], v72 src0_sel:WORD_1
	v_cvt_pk_f32_fp8_e32 v[146:147], v73
	v_cvt_pk_f32_fp8_sdwa v[148:149], v73 src0_sel:WORD_1
	v_cvt_pk_f32_fp8_e32 v[150:151], v74
	v_cvt_pk_f32_fp8_sdwa v[152:153], v74 src0_sel:WORD_1
	v_cvt_pk_f32_fp8_e32 v[154:155], v75
	v_cvt_pk_f32_fp8_sdwa v[156:157], v75 src0_sel:WORD_1
	v_pk_mul_f32 v[124:125], v[142:143], v[16:17]
	v_pk_mul_f32 v[126:127], v[144:145], v[18:19]
	v_pk_fma_f32 v[124:125], v[146:147], v[20:21], v[124:125]
	v_pk_fma_f32 v[126:127], v[148:149], v[22:23], v[126:127]
	v_pk_fma_f32 v[124:125], v[150:151], v[24:25], v[124:125]
	v_pk_fma_f32 v[126:127], v[152:153], v[26:27], v[126:127]
	v_pk_fma_f32 v[124:125], v[154:155], v[28:29], v[124:125]
	v_pk_fma_f32 v[126:127], v[156:157], v[30:31], v[126:127]
	v_pk_add_f32 v[124:125], v[124:125], v[126:127]
	v_add_f32_e32 v122, v124, v125
	s_waitcnt vmcnt(8)
	v_cvt_pk_f32_fp8_e32 v[142:143], v76
	v_cvt_pk_f32_fp8_sdwa v[144:145], v76 src0_sel:WORD_1
	v_cvt_pk_f32_fp8_e32 v[146:147], v77
	v_cvt_pk_f32_fp8_sdwa v[148:149], v77 src0_sel:WORD_1
	v_cvt_pk_f32_fp8_e32 v[150:151], v78
	v_cvt_pk_f32_fp8_sdwa v[152:153], v78 src0_sel:WORD_1
	v_cvt_pk_f32_fp8_e32 v[154:155], v79
	v_cvt_pk_f32_fp8_sdwa v[156:157], v79 src0_sel:WORD_1
	v_pk_mul_f32 v[124:125], v[142:143], v[16:17]
	v_pk_mul_f32 v[126:127], v[144:145], v[18:19]
	v_pk_fma_f32 v[124:125], v[146:147], v[20:21], v[124:125]
	v_pk_fma_f32 v[126:127], v[148:149], v[22:23], v[126:127]
	v_pk_fma_f32 v[124:125], v[150:151], v[24:25], v[124:125]
	v_pk_fma_f32 v[126:127], v[152:153], v[26:27], v[126:127]
	v_pk_fma_f32 v[124:125], v[154:155], v[28:29], v[124:125]
	v_pk_fma_f32 v[126:127], v[156:157], v[30:31], v[126:127]
	v_pk_add_f32 v[124:125], v[124:125], v[126:127]
	v_add_f32_e32 v123, v124, v125
	s_nop 1
	v_add_f32_dpp v116, v116, v116 quad_perm:[1,0,3,2] row_mask:0xf bank_mask:0xf
	v_add_f32_dpp v117, v117, v117 quad_perm:[1,0,3,2] row_mask:0xf bank_mask:0xf
	v_add_f32_dpp v118, v118, v118 quad_perm:[1,0,3,2] row_mask:0xf bank_mask:0xf
	v_add_f32_dpp v119, v119, v119 quad_perm:[1,0,3,2] row_mask:0xf bank_mask:0xf
	v_add_f32_dpp v120, v120, v120 quad_perm:[1,0,3,2] row_mask:0xf bank_mask:0xf
	v_add_f32_dpp v121, v121, v121 quad_perm:[1,0,3,2] row_mask:0xf bank_mask:0xf
	v_add_f32_dpp v122, v122, v122 quad_perm:[1,0,3,2] row_mask:0xf bank_mask:0xf
	v_add_f32_dpp v123, v123, v123 quad_perm:[1,0,3,2] row_mask:0xf bank_mask:0xf
	v_add_f32_dpp v116, v116, v116 quad_perm:[2,3,0,1] row_mask:0xf bank_mask:0xf
	v_add_f32_dpp v117, v117, v117 quad_perm:[2,3,0,1] row_mask:0xf bank_mask:0xf
	v_add_f32_dpp v118, v118, v118 quad_perm:[2,3,0,1] row_mask:0xf bank_mask:0xf
	v_add_f32_dpp v119, v119, v119 quad_perm:[2,3,0,1] row_mask:0xf bank_mask:0xf
	v_add_f32_dpp v120, v120, v120 quad_perm:[2,3,0,1] row_mask:0xf bank_mask:0xf
	v_add_f32_dpp v121, v121, v121 quad_perm:[2,3,0,1] row_mask:0xf bank_mask:0xf
	v_add_f32_dpp v122, v122, v122 quad_perm:[2,3,0,1] row_mask:0xf bank_mask:0xf
	v_add_f32_dpp v123, v123, v123 quad_perm:[2,3,0,1] row_mask:0xf bank_mask:0xf
	v_add_f32_dpp v116, v116, v116 row_half_mirror row_mask:0xf bank_mask:0xf
	v_add_f32_dpp v117, v117, v117 row_half_mirror row_mask:0xf bank_mask:0xf
	v_add_f32_dpp v118, v118, v118 row_half_mirror row_mask:0xf bank_mask:0xf
	v_add_f32_dpp v119, v119, v119 row_half_mirror row_mask:0xf bank_mask:0xf
	v_add_f32_dpp v120, v120, v120 row_half_mirror row_mask:0xf bank_mask:0xf
	v_add_f32_dpp v121, v121, v121 row_half_mirror row_mask:0xf bank_mask:0xf
	v_add_f32_dpp v122, v122, v122 row_half_mirror row_mask:0xf bank_mask:0xf
	v_add_f32_dpp v123, v123, v123 row_half_mirror row_mask:0xf bank_mask:0xf
	v_mov_b32_e32 v129, v116
	s_lshl_b64 s[0:1], s[46:47], 1
	v_cndmask_b32_e64 v129, v129, v117, s[0:1]
	s_lshl_b64 s[0:1], s[46:47], 2
	v_cndmask_b32_e64 v129, v129, v118, s[0:1]
	s_lshl_b64 s[0:1], s[46:47], 3
	v_cndmask_b32_e64 v129, v129, v119, s[0:1]
	s_lshl_b64 s[0:1], s[46:47], 4
	v_cndmask_b32_e64 v129, v129, v120, s[0:1]
	s_lshl_b64 s[0:1], s[46:47], 5
	v_cndmask_b32_e64 v129, v129, v121, s[0:1]
	s_lshl_b64 s[0:1], s[46:47], 6
	v_cndmask_b32_e64 v129, v129, v122, s[0:1]
	s_lshl_b64 s[0:1], s[46:47], 7
	v_cndmask_b32_e64 v129, v129, v123, s[0:1]
	s_waitcnt vmcnt(7)
	v_cvt_pk_f32_fp8_e32 v[142:143], v80
	v_cvt_pk_f32_fp8_sdwa v[144:145], v80 src0_sel:WORD_1
	v_cvt_pk_f32_fp8_e32 v[146:147], v81
	v_cvt_pk_f32_fp8_sdwa v[148:149], v81 src0_sel:WORD_1
	v_cvt_pk_f32_fp8_e32 v[150:151], v82
	v_cvt_pk_f32_fp8_sdwa v[152:153], v82 src0_sel:WORD_1
	v_cvt_pk_f32_fp8_e32 v[154:155], v83
	v_cvt_pk_f32_fp8_sdwa v[156:157], v83 src0_sel:WORD_1
	v_pk_mul_f32 v[124:125], v[142:143], v[16:17]
	v_pk_mul_f32 v[126:127], v[144:145], v[18:19]
	v_pk_fma_f32 v[124:125], v[146:147], v[20:21], v[124:125]
	v_pk_fma_f32 v[126:127], v[148:149], v[22:23], v[126:127]
	v_pk_fma_f32 v[124:125], v[150:151], v[24:25], v[124:125]
	v_pk_fma_f32 v[126:127], v[152:153], v[26:27], v[126:127]
	v_pk_fma_f32 v[124:125], v[154:155], v[28:29], v[124:125]
	v_pk_fma_f32 v[126:127], v[156:157], v[30:31], v[126:127]
	v_pk_add_f32 v[124:125], v[124:125], v[126:127]
	v_add_f32_e32 v116, v124, v125
	s_waitcnt vmcnt(6)
	v_cvt_pk_f32_fp8_e32 v[142:143], v84
	v_cvt_pk_f32_fp8_sdwa v[144:145], v84 src0_sel:WORD_1
	v_cvt_pk_f32_fp8_e32 v[146:147], v85
	v_cvt_pk_f32_fp8_sdwa v[148:149], v85 src0_sel:WORD_1
	v_cvt_pk_f32_fp8_e32 v[150:151], v86
	v_cvt_pk_f32_fp8_sdwa v[152:153], v86 src0_sel:WORD_1
	v_cvt_pk_f32_fp8_e32 v[154:155], v87
	v_cvt_pk_f32_fp8_sdwa v[156:157], v87 src0_sel:WORD_1
	v_pk_mul_f32 v[124:125], v[142:143], v[16:17]
	v_pk_mul_f32 v[126:127], v[144:145], v[18:19]
	v_pk_fma_f32 v[124:125], v[146:147], v[20:21], v[124:125]
	v_pk_fma_f32 v[126:127], v[148:149], v[22:23], v[126:127]
	v_pk_fma_f32 v[124:125], v[150:151], v[24:25], v[124:125]
	v_pk_fma_f32 v[126:127], v[152:153], v[26:27], v[126:127]
	v_pk_fma_f32 v[124:125], v[154:155], v[28:29], v[124:125]
	v_pk_fma_f32 v[126:127], v[156:157], v[30:31], v[126:127]
	v_pk_add_f32 v[124:125], v[124:125], v[126:127]
	v_add_f32_e32 v117, v124, v125
	s_waitcnt vmcnt(5)
	v_cvt_pk_f32_fp8_e32 v[142:143], v88
	v_cvt_pk_f32_fp8_sdwa v[144:145], v88 src0_sel:WORD_1
	v_cvt_pk_f32_fp8_e32 v[146:147], v89
	v_cvt_pk_f32_fp8_sdwa v[148:149], v89 src0_sel:WORD_1
	v_cvt_pk_f32_fp8_e32 v[150:151], v90
	v_cvt_pk_f32_fp8_sdwa v[152:153], v90 src0_sel:WORD_1
	v_cvt_pk_f32_fp8_e32 v[154:155], v91
	v_cvt_pk_f32_fp8_sdwa v[156:157], v91 src0_sel:WORD_1
	v_pk_mul_f32 v[124:125], v[142:143], v[16:17]
	v_pk_mul_f32 v[126:127], v[144:145], v[18:19]
	v_pk_fma_f32 v[124:125], v[146:147], v[20:21], v[124:125]
	v_pk_fma_f32 v[126:127], v[148:149], v[22:23], v[126:127]
	v_pk_fma_f32 v[124:125], v[150:151], v[24:25], v[124:125]
	v_pk_fma_f32 v[126:127], v[152:153], v[26:27], v[126:127]
	v_pk_fma_f32 v[124:125], v[154:155], v[28:29], v[124:125]
	v_pk_fma_f32 v[126:127], v[156:157], v[30:31], v[126:127]
	v_pk_add_f32 v[124:125], v[124:125], v[126:127]
	v_add_f32_e32 v118, v124, v125
	s_waitcnt vmcnt(4)
	v_cvt_pk_f32_fp8_e32 v[142:143], v92
	v_cvt_pk_f32_fp8_sdwa v[144:145], v92 src0_sel:WORD_1
	v_cvt_pk_f32_fp8_e32 v[146:147], v93
	v_cvt_pk_f32_fp8_sdwa v[148:149], v93 src0_sel:WORD_1
	v_cvt_pk_f32_fp8_e32 v[150:151], v94
	v_cvt_pk_f32_fp8_sdwa v[152:153], v94 src0_sel:WORD_1
	v_cvt_pk_f32_fp8_e32 v[154:155], v95
	v_cvt_pk_f32_fp8_sdwa v[156:157], v95 src0_sel:WORD_1
	v_pk_mul_f32 v[124:125], v[142:143], v[16:17]
	v_pk_mul_f32 v[126:127], v[144:145], v[18:19]
	v_pk_fma_f32 v[124:125], v[146:147], v[20:21], v[124:125]
	v_pk_fma_f32 v[126:127], v[148:149], v[22:23], v[126:127]
	v_pk_fma_f32 v[124:125], v[150:151], v[24:25], v[124:125]
	v_pk_fma_f32 v[126:127], v[152:153], v[26:27], v[126:127]
	v_pk_fma_f32 v[124:125], v[154:155], v[28:29], v[124:125]
	v_pk_fma_f32 v[126:127], v[156:157], v[30:31], v[126:127]
	v_pk_add_f32 v[124:125], v[124:125], v[126:127]
	v_add_f32_e32 v119, v124, v125
	s_waitcnt vmcnt(3)
	v_cvt_pk_f32_fp8_e32 v[142:143], v96
	v_cvt_pk_f32_fp8_sdwa v[144:145], v96 src0_sel:WORD_1
	v_cvt_pk_f32_fp8_e32 v[146:147], v97
	v_cvt_pk_f32_fp8_sdwa v[148:149], v97 src0_sel:WORD_1
	v_cvt_pk_f32_fp8_e32 v[150:151], v98
	v_cvt_pk_f32_fp8_sdwa v[152:153], v98 src0_sel:WORD_1
	v_cvt_pk_f32_fp8_e32 v[154:155], v99
	v_cvt_pk_f32_fp8_sdwa v[156:157], v99 src0_sel:WORD_1
	v_pk_mul_f32 v[124:125], v[142:143], v[16:17]
	v_pk_mul_f32 v[126:127], v[144:145], v[18:19]
	v_pk_fma_f32 v[124:125], v[146:147], v[20:21], v[124:125]
	v_pk_fma_f32 v[126:127], v[148:149], v[22:23], v[126:127]
	v_pk_fma_f32 v[124:125], v[150:151], v[24:25], v[124:125]
	v_pk_fma_f32 v[126:127], v[152:153], v[26:27], v[126:127]
	v_pk_fma_f32 v[124:125], v[154:155], v[28:29], v[124:125]
	v_pk_fma_f32 v[126:127], v[156:157], v[30:31], v[126:127]
	v_pk_add_f32 v[124:125], v[124:125], v[126:127]
	v_add_f32_e32 v120, v124, v125
	s_waitcnt vmcnt(2)
	v_cvt_pk_f32_fp8_e32 v[142:143], v100
	v_cvt_pk_f32_fp8_sdwa v[144:145], v100 src0_sel:WORD_1
	v_cvt_pk_f32_fp8_e32 v[146:147], v101
	v_cvt_pk_f32_fp8_sdwa v[148:149], v101 src0_sel:WORD_1
	v_cvt_pk_f32_fp8_e32 v[150:151], v102
	v_cvt_pk_f32_fp8_sdwa v[152:153], v102 src0_sel:WORD_1
	v_cvt_pk_f32_fp8_e32 v[154:155], v103
	v_cvt_pk_f32_fp8_sdwa v[156:157], v103 src0_sel:WORD_1
	v_pk_mul_f32 v[124:125], v[142:143], v[16:17]
	v_pk_mul_f32 v[126:127], v[144:145], v[18:19]
	v_pk_fma_f32 v[124:125], v[146:147], v[20:21], v[124:125]
	v_pk_fma_f32 v[126:127], v[148:149], v[22:23], v[126:127]
	v_pk_fma_f32 v[124:125], v[150:151], v[24:25], v[124:125]
	v_pk_fma_f32 v[126:127], v[152:153], v[26:27], v[126:127]
	v_pk_fma_f32 v[124:125], v[154:155], v[28:29], v[124:125]
	v_pk_fma_f32 v[126:127], v[156:157], v[30:31], v[126:127]
	v_pk_add_f32 v[124:125], v[124:125], v[126:127]
	v_add_f32_e32 v121, v124, v125
	s_waitcnt vmcnt(1)
	v_cvt_pk_f32_fp8_e32 v[142:143], v108
	v_cvt_pk_f32_fp8_sdwa v[144:145], v108 src0_sel:WORD_1
	v_cvt_pk_f32_fp8_e32 v[146:147], v109
	v_cvt_pk_f32_fp8_sdwa v[148:149], v109 src0_sel:WORD_1
	v_cvt_pk_f32_fp8_e32 v[150:151], v110
	v_cvt_pk_f32_fp8_sdwa v[152:153], v110 src0_sel:WORD_1
	v_cvt_pk_f32_fp8_e32 v[154:155], v111
	v_cvt_pk_f32_fp8_sdwa v[156:157], v111 src0_sel:WORD_1
	v_pk_mul_f32 v[124:125], v[142:143], v[16:17]
	v_pk_mul_f32 v[126:127], v[144:145], v[18:19]
	v_pk_fma_f32 v[124:125], v[146:147], v[20:21], v[124:125]
	v_pk_fma_f32 v[126:127], v[148:149], v[22:23], v[126:127]
	v_pk_fma_f32 v[124:125], v[150:151], v[24:25], v[124:125]
	v_pk_fma_f32 v[126:127], v[152:153], v[26:27], v[126:127]
	v_pk_fma_f32 v[124:125], v[154:155], v[28:29], v[124:125]
	v_pk_fma_f32 v[126:127], v[156:157], v[30:31], v[126:127]
	v_pk_add_f32 v[124:125], v[124:125], v[126:127]
	v_add_f32_e32 v122, v124, v125
	s_waitcnt vmcnt(0)
	v_cvt_pk_f32_fp8_e32 v[142:143], v112
	v_cvt_pk_f32_fp8_sdwa v[144:145], v112 src0_sel:WORD_1
	v_cvt_pk_f32_fp8_e32 v[146:147], v113
	v_cvt_pk_f32_fp8_sdwa v[148:149], v113 src0_sel:WORD_1
	v_cvt_pk_f32_fp8_e32 v[150:151], v114
	v_cvt_pk_f32_fp8_sdwa v[152:153], v114 src0_sel:WORD_1
	v_cvt_pk_f32_fp8_e32 v[154:155], v115
	v_cvt_pk_f32_fp8_sdwa v[156:157], v115 src0_sel:WORD_1
	v_pk_mul_f32 v[124:125], v[142:143], v[16:17]
	v_pk_mul_f32 v[126:127], v[144:145], v[18:19]
	v_pk_fma_f32 v[124:125], v[146:147], v[20:21], v[124:125]
	v_pk_fma_f32 v[126:127], v[148:149], v[22:23], v[126:127]
	v_pk_fma_f32 v[124:125], v[150:151], v[24:25], v[124:125]
	v_pk_fma_f32 v[126:127], v[152:153], v[26:27], v[126:127]
	v_pk_fma_f32 v[124:125], v[154:155], v[28:29], v[124:125]
	v_pk_fma_f32 v[126:127], v[156:157], v[30:31], v[126:127]
	v_pk_add_f32 v[124:125], v[124:125], v[126:127]
	v_add_f32_e32 v123, v124, v125
	s_nop 1
	v_add_f32_dpp v116, v116, v116 quad_perm:[1,0,3,2] row_mask:0xf bank_mask:0xf
	v_add_f32_dpp v117, v117, v117 quad_perm:[1,0,3,2] row_mask:0xf bank_mask:0xf
	v_add_f32_dpp v118, v118, v118 quad_perm:[1,0,3,2] row_mask:0xf bank_mask:0xf
	v_add_f32_dpp v119, v119, v119 quad_perm:[1,0,3,2] row_mask:0xf bank_mask:0xf
	v_add_f32_dpp v120, v120, v120 quad_perm:[1,0,3,2] row_mask:0xf bank_mask:0xf
	v_add_f32_dpp v121, v121, v121 quad_perm:[1,0,3,2] row_mask:0xf bank_mask:0xf
	v_add_f32_dpp v122, v122, v122 quad_perm:[1,0,3,2] row_mask:0xf bank_mask:0xf
	v_add_f32_dpp v123, v123, v123 quad_perm:[1,0,3,2] row_mask:0xf bank_mask:0xf
	v_add_f32_dpp v116, v116, v116 quad_perm:[2,3,0,1] row_mask:0xf bank_mask:0xf
	v_add_f32_dpp v117, v117, v117 quad_perm:[2,3,0,1] row_mask:0xf bank_mask:0xf
	v_add_f32_dpp v118, v118, v118 quad_perm:[2,3,0,1] row_mask:0xf bank_mask:0xf
	v_add_f32_dpp v119, v119, v119 quad_perm:[2,3,0,1] row_mask:0xf bank_mask:0xf
	v_add_f32_dpp v120, v120, v120 quad_perm:[2,3,0,1] row_mask:0xf bank_mask:0xf
	v_add_f32_dpp v121, v121, v121 quad_perm:[2,3,0,1] row_mask:0xf bank_mask:0xf
	v_add_f32_dpp v122, v122, v122 quad_perm:[2,3,0,1] row_mask:0xf bank_mask:0xf
	v_add_f32_dpp v123, v123, v123 quad_perm:[2,3,0,1] row_mask:0xf bank_mask:0xf
	v_add_f32_dpp v116, v116, v116 row_half_mirror row_mask:0xf bank_mask:0xf
	v_add_f32_dpp v117, v117, v117 row_half_mirror row_mask:0xf bank_mask:0xf
	v_add_f32_dpp v118, v118, v118 row_half_mirror row_mask:0xf bank_mask:0xf
	v_add_f32_dpp v119, v119, v119 row_half_mirror row_mask:0xf bank_mask:0xf
	v_add_f32_dpp v120, v120, v120 row_half_mirror row_mask:0xf bank_mask:0xf
	v_add_f32_dpp v121, v121, v121 row_half_mirror row_mask:0xf bank_mask:0xf
	v_add_f32_dpp v122, v122, v122 row_half_mirror row_mask:0xf bank_mask:0xf
	v_add_f32_dpp v123, v123, v123 row_half_mirror row_mask:0xf bank_mask:0xf
	v_mov_b32_e32 v131, v116
	s_lshl_b64 s[0:1], s[46:47], 1
	v_cndmask_b32_e64 v131, v131, v117, s[0:1]
	s_lshl_b64 s[0:1], s[46:47], 2
	v_cndmask_b32_e64 v131, v131, v118, s[0:1]
	s_lshl_b64 s[0:1], s[46:47], 3
	v_cndmask_b32_e64 v131, v131, v119, s[0:1]
	s_lshl_b64 s[0:1], s[46:47], 4
	v_cndmask_b32_e64 v131, v131, v120, s[0:1]
	s_lshl_b64 s[0:1], s[46:47], 5
	v_cndmask_b32_e64 v131, v131, v121, s[0:1]
	s_lshl_b64 s[0:1], s[46:47], 6
	v_cndmask_b32_e64 v131, v131, v122, s[0:1]
	s_lshl_b64 s[0:1], s[46:47], 7
	v_cndmask_b32_e64 v131, v131, v123, s[0:1]
	s_lshl_b32 s0, s39, 9
	v_add_u32_e32 v136, s0, v130
	ds_add_f32 v136, v129
	ds_add_f32 v136, v131 offset:256
	s_add_i32 s39, s39, 1
	s_cmp_lt_u32 s39, 32
	s_cbranch_scc1 .Ldn_tok
	s_add_i32 s38, s38, 1
	s_cmp_lt_u32 s38, 8
	s_cbranch_scc1 .Ldn_pass
	v_and_b32_e32 v8, 7, v177
	v_lshrrev_b32_e32 v9, 3, v177
	v_lshl_add_u32 v8, v8, 3, v9
	v_lshlrev_b32_e32 v8, 2, v8
	v_and_b32_e32 v9, 15, v177
	v_lshlrev_b32_e32 v9, 2, v9
	s_mov_b32 s39, 0
.Ldn_fin:
	s_add_i32 s0, s40, s39
	s_lshl_b32 s1, s0, 9
	s_add_u32 s12, s44, s1
	s_addc_u32 s13, s45, 0
	s_lshl_b32 s1, s0, 6
	s_add_u32 s14, s92, s1
	s_addc_u32 s15, s93, 0
	global_load_dword v10, v8, s[12:13]
	global_load_dword v11, v8, s[12:13] offset:256
	global_load_dword v12, v9, s[14:15]
	s_lshl_b32 s0, s39, 9
	v_add_u32_e32 v136, s0, v130
	ds_read_b32 v13, v136
	ds_read_b32 v14, v136 offset:256
	s_waitcnt vmcnt(0)
	s_nop 0
	v_add_f32_dpp v12, v12, v12 quad_perm:[1,0,3,2] row_mask:0xf bank_mask:0xf
	s_nop 1
	v_add_f32_dpp v12, v12, v12 quad_perm:[2,3,0,1] row_mask:0xf bank_mask:0xf
	s_nop 1
	v_add_f32_dpp v12, v12, v12 row_half_mirror row_mask:0xf bank_mask:0xf
	s_nop 1
	v_add_f32_dpp v12, v12, v12 row_mirror row_mask:0xf bank_mask:0xf
	v_mov_b32_e32 v15, 0x358637bd
	v_fmac_f32_e32 v15, 0x3a800000, v12
	v_rsq_f32_e32 v15, v15
	s_waitcnt lgkmcnt(0)
	v_mul_f32_e32 v15, 0x3b800000, v15
	v_mul_f32_e32 v16, v15, v13
	v_mul_f32_e32 v17, 0x3d372713, v16
	v_mul_f32_e32 v17, v16, v17
	v_mul_f32_e32 v18, 0.5, v16
	v_fma_f32 v17, v16, v17, v16
	v_mul_f32_e32 v17, 0x3f4c422a, v17
	v_mul_f32_e32 v17, 0x4038aa3b, v17
	v_exp_f32_e32 v17, v17
	s_nop 0
	v_add_f32_e32 v17, 1.0, v17
	v_rcp_f32_e32 v17, v17
	s_nop 0
	v_fma_f32 v17, v17, -2.0, 1.0
	v_add_f32_e32 v17, 1.0, v17
	v_mul_f32_e32 v17, v18, v17
	v_mul_f32_e32 v17, 0x3c800000, v17
	v_mul_f32_e32 v10, v17, v10
	v_mul_f32_e32 v16, v15, v14
	v_mul_f32_e32 v17, 0x3d372713, v16
	v_mul_f32_e32 v17, v16, v17
	v_mul_f32_e32 v18, 0.5, v16
	v_fma_f32 v17, v16, v17, v16
	v_mul_f32_e32 v17, 0x3f4c422a, v17
	v_mul_f32_e32 v17, 0x4038aa3b, v17
	v_exp_f32_e32 v17, v17
	s_nop 0
	v_add_f32_e32 v17, 1.0, v17
	v_rcp_f32_e32 v17, v17
	s_nop 0
	v_fma_f32 v17, v17, -2.0, 1.0
	v_add_f32_e32 v17, 1.0, v17
	v_mul_f32_e32 v17, v18, v17
	v_mul_f32_e32 v17, 0x3c800000, v17
	v_mul_f32_e32 v11, v17, v11
	global_store_dword v8, v10, s[12:13]
	global_store_dword v8, v11, s[12:13] offset:256
	s_add_i32 s39, s39, 1
	s_cmp_lt_u32 s39, 32
	s_cbranch_scc1 .Ldn_fin

; __device__ __forceinline__ void peer_up_phase(const Ctx& C, const unsigned char* EU, bf16* XBN, float* RSS, float* xio, const float* gfinal, bool last, const float* SELG, const int* SELI) {
;     int gl = threadIdx.x & 63; asm volatile("" : "+v"(gl));
;     for (int wtile = C.gw; wtile < MTOK / 16; wtile += C.ngw) {
;         const int tok0 = wtile * 16;
;         int nvi0 = SELI[(size_t)tok0 * 128 + gl], nvi1 = SELI[(size_t)tok0 * 128 + 64 + gl]; float nvg0 = SELG[(size_t)tok0 * 128 + gl], nvg1 = SELG[(size_t)tok0 * 128 + 64 + gl];
;         for (int ti = 0; ti < 16; ++ti) {
;             const size_t tok = (size_t)tok0 + ti;
;             const int vi0 = nvi0, vi1 = nvi1; const float vg0 = nvg0, vg1 = nvg1;
;             if (ti + 1 < 16) { const size_t tn = tok + 1; nvi0 = SELI[tn * 128 + gl]; nvi1 = SELI[tn * 128 + 64 + gl]; nvg0 = SELG[tn * 128 + gl]; nvg1 = SELG[tn * 128 + 64 + gl]; }
.LBB0_337:
	v_readlane_b32 s0, v247, 53
	v_mov_b32_e32 v142, v177
	s_cmpk_gt_i32 s0, 0xfff
	v_readlane_b32 s1, v247, 54
	s_cbranch_scc1 .LBB0_357
	v_readlane_b32 s0, v247, 56
	s_cmp_lt_u32 s0, 3
	s_cbranch_scc1 .Lup_new
	s_cmp_eq_u32 s98, 0x800
	s_cbranch_scc1 .Lupl_new
	v_readlane_b32 s0, v247, 56
	v_readlane_b32 s1, v247, 57
	s_cmp_lg_u32 s0, 3
	v_lshlrev_b32_e32 v0, 4, v142
	v_readlane_b32 s0, v249, 37
	v_ashrrev_i32_e32 v1, 31, v0
	v_readlane_b32 s1, v249, 38
	v_readlane_b32 s8, v249, 0
	v_ashrrev_i32_e32 v143, 31, v142
	v_lshl_add_u64 v[144:145], v[0:1], 1, s[60:61]
	v_lshl_add_u64 v[146:147], s[0:1], 0, v[0:1]
	v_lshlrev_b64 v[0:1], 2, v[0:1]
	v_readlane_b32 s12, v249, 4
	v_readlane_b32 s13, v249, 5
	v_readlane_b32 s14, v249, 6
	v_readlane_b32 s15, v249, 7
	s_mov_b64 s[0:1], 0xc0
	s_cselect_b64 s[4:5], -1, 0
	s_waitcnt lgkmcnt(0)
	v_lshl_add_u64 v[148:149], v[142:143], 2, s[92:93]
	v_lshl_add_u64 v[150:151], s[14:15], 0, v[0:1]
	v_lshl_add_u64 v[152:153], v[142:143], 0, s[74:75]
	v_lshl_add_u64 v[154:155], v[142:143], 0, s[0:1]
	v_cmp_gt_i32_e64 s[38:39], 16, v142
	v_cmp_eq_u32_e64 s[40:41], 0, v142
	v_lshl_add_u64 v[156:157], s[12:13], 0, v[0:1]
	v_readlane_b32 s0, v247, 53
	v_readlane_b32 s9, v249, 1
	v_readlane_b32 s10, v249, 2
	v_readlane_b32 s11, v249, 3
	v_readlane_b32 s1, v247, 54
	s_branch .LBB0_340

; __device__ __forceinline__ void peer_up_phase(const Ctx& C, const unsigned char* EU, bf16* XBN, float* RSS, float* xio, const float* gfinal, bool last, const float* SELG, const int* SELI) {
;     int gl = threadIdx.x & 63; asm volatile("" : "+v"(gl));
;     for (int wtile = C.gw; wtile < MTOK / 16; wtile += C.ngw) {
;         const int tok0 = wtile * 16;
;         int nvi0 = SELI[(size_t)tok0 * 128 + gl], nvi1 = SELI[(size_t)tok0 * 128 + 64 + gl]; float nvg0 = SELG[(size_t)tok0 * 128 + gl], nvg1 = SELG[(size_t)tok0 * 128 + 64 + gl];
;         for (int ti = 0; ti < 16; ++ti) {
;             const size_t tok = (size_t)tok0 + ti;
;             const int vi0 = nvi0, vi1 = nvi1; const float vg0 = nvg0, vg1 = nvg1;
;             if (ti + 1 < 16) { const size_t tn = tok + 1; nvi0 = SELI[tn * 128 + gl]; nvi1 = SELI[tn * 128 + 64 + gl]; nvg0 = SELG[tn * 128 + gl]; nvg1 = SELG[tn * 128 + 64 + gl]; }
;             bf16* xr16 = XBN + tok * DM + 16 * gl;
;             const v4u xw0 = __builtin_nontemporal_load((const v4u*)xr16), xw1 = __builtin_nontemporal_load((const v4u*)(xr16 + 8));
;             v2f y[8];
; #pragma unroll
;             for (int k = 0; k < 8; ++k) y[k] = (v2f){0.f, 0.f};
;             v4u upA[8], upB[8];
; #pragma unroll
;             for (int k = 0; k < 8; ++k) { const int e = __builtin_amdgcn_readlane(vi0, k); upA[k] = *(const v4u*)(EU + (size_t)e * DM + 16 * gl); }
; #pragma unroll
;             for (int k = 0; k < 8; ++k) { const int e = __builtin_amdgcn_readlane(vi0, 8 + k); upB[k] = *(const v4u*)(EU + (size_t)e * DM + 16 * gl); }
.Lup_new:
	v_readlane_b32 s0, v247, 53
	v_readlane_b32 s4, v249, 8
	v_readlane_b32 s5, v249, 9
	s_lshr_b32 s1, s0, 3
	s_and_b32 s2, s0, 7
	s_and_b32 s17, s1, 7
	s_lshr_b32 s1, s1, 3
	s_lshr_b32 s15, s98, 6
	s_cmp_ge_u32 s1, s15
	s_cbranch_scc1 .Lup_done
	s_lshl_b32 s14, s1, 3
	s_add_i32 s14, s14, s2
	s_lshl_b32 s15, s15, 3
	s_lshl_b32 s16, s2, 11
	s_add_u32 s6, s4, 0x2b600000
	s_addc_u32 s7, s5, 0
	s_add_u32 s8, s4, 0x6600000
	s_addc_u32 s9, s5, 0
	s_lshl_b32 s0, s17, 21
	s_add_u32 s8, s8, s0
	s_addc_u32 s9, s9, 0
	s_add_u32 s4, s4, 0x2d600000
	s_addc_u32 s5, s5, 0
	s_lshl_b32 s0, s17, 8
	s_add_u32 s10, s60, s0
	s_addc_u32 s11, s61, 0
	s_lshl_b32 s0, s17, 2
	s_add_u32 s12, s92, s0
	s_addc_u32 s13, s93, 0
	v_and_b32_e32 v1, 7, v177
	v_lshlrev_b32_e32 v1, 4, v1
	v_lshrrev_b32_e32 v2, 3, v177
	v_lshlrev_b32_e32 v3, 3, v177
	v_add_u32_e32 v3, s16, v3
	v_lshl_add_u32 v2, v2, 3, s16
	v_lshlrev_b32_e32 v4, 2, v177
	v_and_b32_e32 v5, 7, v177
	v_lshlrev_b32_e32 v5, 5, v5
	v_bfe_u32 v44, v177, 5, 1
	v_lshl_or_b32 v5, v44, 4, v5
	v_bfe_u32 v44, v177, 4, 1
	v_lshl_or_b32 v5, v44, 3, v5
	v_mov_b32_e32 v160, 0
	s_cmp_eq_u32 s98, 0x800
	s_cbranch_scc1 .Lupp_start
	s_lshl_b32 s2, s14, 9
	s_add_u32 s0, s6, s2
	s_addc_u32 s1, s7, 0
	global_load_dword v6, v4, s[0:1]
	global_load_dword v8, v4, s[0:1] offset:256
	s_add_u32 s0, s4, s2
	s_addc_u32 s1, s5, 0
	global_load_dword v7, v4, s[0:1]
	global_load_dword v9, v4, s[0:1] offset:256

; __device__ __forceinline__ void peer_up_phase(const Ctx& C, const unsigned char* EU, bf16* XBN, float* RSS, float* xio, const float* gfinal, bool last, const float* SELG, const int* SELI) {
;     ...
;             v4u upA[8], upB[8];
; #pragma unroll
;             for (int k = 0; k < 8; ++k) { const int e = __builtin_amdgcn_readlane(vi0, k); upA[k] = *(const v4u*)(EU + (size_t)e * DM + 16 * gl); }
; #pragma unroll
;             for (int k = 0; k < 8; ++k) { const int e = __builtin_amdgcn_readlane(vi0, 8 + k); upB[k] = *(const v4u*)(EU + (size_t)e * DM + 16 * gl); }
.Lup_nopf:
	ds_read_b64 v[12:13], v2
	ds_read_b64 v[14:15], v2 offset:64
	ds_read_b64 v[16:17], v2 offset:128
	ds_read_b64 v[18:19], v2 offset:192
	ds_read_b64 v[20:21], v2 offset:256
	ds_read_b64 v[22:23], v2 offset:320
	ds_read_b64 v[24:25], v2 offset:384
	ds_read_b64 v[26:27], v2 offset:448
	ds_read_b64 v[28:29], v2 offset:512
	ds_read_b64 v[30:31], v2 offset:576
	ds_read_b64 v[32:33], v2 offset:640
	ds_read_b64 v[34:35], v2 offset:704
	ds_read_b64 v[36:37], v2 offset:768
	ds_read_b64 v[38:39], v2 offset:832
	ds_read_b64 v[40:41], v2 offset:896
	ds_read_b64 v[42:43], v2 offset:960
	v_mov_b64_e32 v[112:113], 0
	v_mov_b64_e32 v[114:115], 0
	v_mov_b64_e32 v[116:117], 0
	v_mov_b64_e32 v[118:119], 0
	v_mov_b64_e32 v[120:121], 0
	v_mov_b64_e32 v[122:123], 0
	v_mov_b64_e32 v[124:125], 0
	v_mov_b64_e32 v[126:127], 0
	s_waitcnt lgkmcnt(8)
	v_lshl_add_u32 v13, v13, 7, v1
	global_load_dwordx4 v[48:51], v13, s[8:9]
	v_lshl_add_u32 v15, v15, 7, v1
	global_load_dwordx4 v[52:55], v15, s[8:9]
	v_lshl_add_u32 v17, v17, 7, v1
	global_load_dwordx4 v[56:59], v17, s[8:9]
	v_lshl_add_u32 v19, v19, 7, v1
	global_load_dwordx4 v[60:63], v19, s[8:9]
	v_lshl_add_u32 v21, v21, 7, v1
	global_load_dwordx4 v[64:67], v21, s[8:9]
	v_lshl_add_u32 v23, v23, 7, v1
	global_load_dwordx4 v[68:71], v23, s[8:9]
	v_lshl_add_u32 v25, v25, 7, v1
	global_load_dwordx4 v[72:75], v25, s[8:9]
	v_lshl_add_u32 v27, v27, 7, v1
	global_load_dwordx4 v[76:79], v27, s[8:9]
	s_waitcnt lgkmcnt(0)
	v_lshl_add_u32 v29, v29, 7, v1
	global_load_dwordx4 v[80:83], v29, s[8:9]
	v_lshl_add_u32 v31, v31, 7, v1
	global_load_dwordx4 v[84:87], v31, s[8:9]
	v_lshl_add_u32 v33, v33, 7, v1
	global_load_dwordx4 v[88:91], v33, s[8:9]
	v_lshl_add_u32 v35, v35, 7, v1
	global_load_dwordx4 v[92:95], v35, s[8:9]
	v_lshl_add_u32 v37, v37, 7, v1
	global_load_dwordx4 v[96:99], v37, s[8:9]
	v_lshl_add_u32 v39, v39, 7, v1
	global_load_dwordx4 v[100:103], v39, s[8:9]
	v_lshl_add_u32 v41, v41, 7, v1
	global_load_dwordx4 v[104:107], v41, s[8:9]
	v_lshl_add_u32 v43, v43, 7, v1
	global_load_dwordx4 v[108:111], v43, s[8:9]
	s_waitcnt vmcnt(15)
	v_cvt_pk_f32_fp8_e32 v[144:145], v48
	v_cvt_pk_f32_fp8_sdwa v[146:147], v48 src0_sel:WORD_1
	v_cvt_pk_f32_fp8_e32 v[148:149], v49
	v_cvt_pk_f32_fp8_sdwa v[150:151], v49 src0_sel:WORD_1
	v_cvt_pk_f32_fp8_e32 v[152:153], v50
	v_cvt_pk_f32_fp8_sdwa v[154:155], v50 src0_sel:WORD_1
	v_cvt_pk_f32_fp8_e32 v[156:157], v51
	v_cvt_pk_f32_fp8_sdwa v[158:159], v51 src0_sel:WORD_1
	v_pk_fma_f32 v[112:113], v[144:145], v[12:13], v[112:113] op_sel_hi:[1,0,1]
	v_pk_fma_f32 v[114:115], v[146:147], v[12:13], v[114:115] op_sel_hi:[1,0,1]
	v_pk_fma_f32 v[116:117], v[148:149], v[12:13], v[116:117] op_sel_hi:[1,0,1]
	v_pk_fma_f32 v[118:119], v[150:151], v[12:13], v[118:119] op_sel_hi:[1,0,1]
	v_pk_fma_f32 v[120:121], v[152:153], v[12:13], v[120:121] op_sel_hi:[1,0,1]
	v_pk_fma_f32 v[122:123], v[154:155], v[12:13], v[122:123] op_sel_hi:[1,0,1]
	v_pk_fma_f32 v[124:125], v[156:157], v[12:13], v[124:125] op_sel_hi:[1,0,1]
	v_pk_fma_f32 v[126:127], v[158:159], v[12:13], v[126:127] op_sel_hi:[1,0,1]
	s_waitcnt vmcnt(14)
	v_cvt_pk_f32_fp8_e32 v[144:145], v52
	v_cvt_pk_f32_fp8_sdwa v[146:147], v52 src0_sel:WORD_1
	v_cvt_pk_f32_fp8_e32 v[148:149], v53
	v_cvt_pk_f32_fp8_sdwa v[150:151], v53 src0_sel:WORD_1
	v_cvt_pk_f32_fp8_e32 v[152:153], v54
	v_cvt_pk_f32_fp8_sdwa v[154:155], v54 src0_sel:WORD_1
	v_cvt_pk_f32_fp8_e32 v[156:157], v55
	v_cvt_pk_f32_fp8_sdwa v[158:159], v55 src0_sel:WORD_1
	v_pk_fma_f32 v[112:113], v[144:145], v[14:15], v[112:113] op_sel_hi:[1,0,1]
	v_pk_fma_f32 v[114:115], v[146:147], v[14:15], v[114:115] op_sel_hi:[1,0,1]
	v_pk_fma_f32 v[116:117], v[148:149], v[14:15], v[116:117] op_sel_hi:[1,0,1]
	v_pk_fma_f32 v[118:119], v[150:151], v[14:15], v[118:119] op_sel_hi:[1,0,1]
	v_pk_fma_f32 v[120:121], v[152:153], v[14:15], v[120:121] op_sel_hi:[1,0,1]
	v_pk_fma_f32 v[122:123], v[154:155], v[14:15], v[122:123] op_sel_hi:[1,0,1]
	v_pk_fma_f32 v[124:125], v[156:157], v[14:15], v[124:125] op_sel_hi:[1,0,1]
	v_pk_fma_f32 v[126:127], v[158:159], v[14:15], v[126:127] op_sel_hi:[1,0,1]
	s_waitcnt vmcnt(13)
	v_cvt_pk_f32_fp8_e32 v[144:145], v56
	v_cvt_pk_f32_fp8_sdwa v[146:147], v56 src0_sel:WORD_1
	v_cvt_pk_f32_fp8_e32 v[148:149], v57
	v_cvt_pk_f32_fp8_sdwa v[150:151], v57 src0_sel:WORD_1
	v_cvt_pk_f32_fp8_e32 v[152:153], v58
	v_cvt_pk_f32_fp8_sdwa v[154:155], v58 src0_sel:WORD_1
	v_cvt_pk_f32_fp8_e32 v[156:157], v59
	v_cvt_pk_f32_fp8_sdwa v[158:159], v59 src0_sel:WORD_1
	v_pk_fma_f32 v[112:113], v[144:145], v[16:17], v[112:113] op_sel_hi:[1,0,1]
	v_pk_fma_f32 v[114:115], v[146:147], v[16:17], v[114:115] op_sel_hi:[1,0,1]
	v_pk_fma_f32 v[116:117], v[148:149], v[16:17], v[116:117] op_sel_hi:[1,0,1]
	v_pk_fma_f32 v[118:119], v[150:151], v[16:17], v[118:119] op_sel_hi:[1,0,1]
	v_pk_fma_f32 v[120:121], v[152:153], v[16:17], v[120:121] op_sel_hi:[1,0,1]
	v_pk_fma_f32 v[122:123], v[154:155], v[16:17], v[122:123] op_sel_hi:[1,0,1]
	v_pk_fma_f32 v[124:125], v[156:157], v[16:17], v[124:125] op_sel_hi:[1,0,1]
	v_pk_fma_f32 v[126:127], v[158:159], v[16:17], v[126:127] op_sel_hi:[1,0,1]
	s_waitcnt vmcnt(12)
	v_cvt_pk_f32_fp8_e32 v[144:145], v60
	v_cvt_pk_f32_fp8_sdwa v[146:147], v60 src0_sel:WORD_1
	v_cvt_pk_f32_fp8_e32 v[148:149], v61
	v_cvt_pk_f32_fp8_sdwa v[150:151], v61 src0_sel:WORD_1
	v_cvt_pk_f32_fp8_e32 v[152:153], v62
	v_cvt_pk_f32_fp8_sdwa v[154:155], v62 src0_sel:WORD_1
	v_cvt_pk_f32_fp8_e32 v[156:157], v63
	v_cvt_pk_f32_fp8_sdwa v[158:159], v63 src0_sel:WORD_1
	v_pk_fma_f32 v[112:113], v[144:145], v[18:19], v[112:113] op_sel_hi:[1,0,1]
	v_pk_fma_f32 v[114:115], v[146:147], v[18:19], v[114:115] op_sel_hi:[1,0,1]
	v_pk_fma_f32 v[116:117], v[148:149], v[18:19], v[116:117] op_sel_hi:[1,0,1]
	v_pk_fma_f32 v[118:119], v[150:151], v[18:19], v[118:119] op_sel_hi:[1,0,1]
	v_pk_fma_f32 v[120:121], v[152:153], v[18:19], v[120:121] op_sel_hi:[1,0,1]
	v_pk_fma_f32 v[122:123], v[154:155], v[18:19], v[122:123] op_sel_hi:[1,0,1]
	v_pk_fma_f32 v[124:125], v[156:157], v[18:19], v[124:125] op_sel_hi:[1,0,1]
	v_pk_fma_f32 v[126:127], v[158:159], v[18:19], v[126:127] op_sel_hi:[1,0,1]
	s_waitcnt vmcnt(11)
	v_cvt_pk_f32_fp8_e32 v[144:145], v64
	v_cvt_pk_f32_fp8_sdwa v[146:147], v64 src0_sel:WORD_1
	v_cvt_pk_f32_fp8_e32 v[148:149], v65
	v_cvt_pk_f32_fp8_sdwa v[150:151], v65 src0_sel:WORD_1
	v_cvt_pk_f32_fp8_e32 v[152:153], v66
	v_cvt_pk_f32_fp8_sdwa v[154:155], v66 src0_sel:WORD_1
	v_cvt_pk_f32_fp8_e32 v[156:157], v67
	v_cvt_pk_f32_fp8_sdwa v[158:159], v67 src0_sel:WORD_1
	v_pk_fma_f32 v[112:113], v[144:145], v[20:21], v[112:113] op_sel_hi:[1,0,1]
	v_pk_fma_f32 v[114:115], v[146:147], v[20:21], v[114:115] op_sel_hi:[1,0,1]
	v_pk_fma_f32 v[116:117], v[148:149], v[20:21], v[116:117] op_sel_hi:[1,0,1]
	v_pk_fma_f32 v[118:119], v[150:151], v[20:21], v[118:119] op_sel_hi:[1,0,1]
	v_pk_fma_f32 v[120:121], v[152:153], v[20:21], v[120:121] op_sel_hi:[1,0,1]
	v_pk_fma_f32 v[122:123], v[154:155], v[20:21], v[122:123] op_sel_hi:[1,0,1]
	v_pk_fma_f32 v[124:125], v[156:157], v[20:21], v[124:125] op_sel_hi:[1,0,1]
	v_pk_fma_f32 v[126:127], v[158:159], v[20:21], v[126:127] op_sel_hi:[1,0,1]
	s_waitcnt vmcnt(10)
	v_cvt_pk_f32_fp8_e32 v[144:145], v68
	v_cvt_pk_f32_fp8_sdwa v[146:147], v68 src0_sel:WORD_1
	v_cvt_pk_f32_fp8_e32 v[148:149], v69
	v_cvt_pk_f32_fp8_sdwa v[150:151], v69 src0_sel:WORD_1
	v_cvt_pk_f32_fp8_e32 v[152:153], v70
	v_cvt_pk_f32_fp8_sdwa v[154:155], v70 src0_sel:WORD_1
	v_cvt_pk_f32_fp8_e32 v[156:157], v71
	v_cvt_pk_f32_fp8_sdwa v[158:159], v71 src0_sel:WORD_1
	v_pk_fma_f32 v[112:113], v[144:145], v[22:23], v[112:113] op_sel_hi:[1,0,1]
	v_pk_fma_f32 v[114:115], v[146:147], v[22:23], v[114:115] op_sel_hi:[1,0,1]
	v_pk_fma_f32 v[116:117], v[148:149], v[22:23], v[116:117] op_sel_hi:[1,0,1]
	v_pk_fma_f32 v[118:119], v[150:151], v[22:23], v[118:119] op_sel_hi:[1,0,1]
	v_pk_fma_f32 v[120:121], v[152:153], v[22:23], v[120:121] op_sel_hi:[1,0,1]
	v_pk_fma_f32 v[122:123], v[154:155], v[22:23], v[122:123] op_sel_hi:[1,0,1]
	v_pk_fma_f32 v[124:125], v[156:157], v[22:23], v[124:125] op_sel_hi:[1,0,1]
	v_pk_fma_f32 v[126:127], v[158:159], v[22:23], v[126:127] op_sel_hi:[1,0,1]
	s_waitcnt vmcnt(9)
	v_cvt_pk_f32_fp8_e32 v[144:145], v72
	v_cvt_pk_f32_fp8_sdwa v[146:147], v72 src0_sel:WORD_1
	v_cvt_pk_f32_fp8_e32 v[148:149], v73
	v_cvt_pk_f32_fp8_sdwa v[150:151], v73 src0_sel:WORD_1
	v_cvt_pk_f32_fp8_e32 v[152:153], v74
	v_cvt_pk_f32_fp8_sdwa v[154:155], v74 src0_sel:WORD_1
	v_cvt_pk_f32_fp8_e32 v[156:157], v75
	v_cvt_pk_f32_fp8_sdwa v[158:159], v75 src0_sel:WORD_1
	v_pk_fma_f32 v[112:113], v[144:145], v[24:25], v[112:113] op_sel_hi:[1,0,1]
	v_pk_fma_f32 v[114:115], v[146:147], v[24:25], v[114:115] op_sel_hi:[1,0,1]
	v_pk_fma_f32 v[116:117], v[148:149], v[24:25], v[116:117] op_sel_hi:[1,0,1]
	v_pk_fma_f32 v[118:119], v[150:151], v[24:25], v[118:119] op_sel_hi:[1,0,1]
	v_pk_fma_f32 v[120:121], v[152:153], v[24:25], v[120:121] op_sel_hi:[1,0,1]
	v_pk_fma_f32 v[122:123], v[154:155], v[24:25], v[122:123] op_sel_hi:[1,0,1]
	v_pk_fma_f32 v[124:125], v[156:157], v[24:25], v[124:125] op_sel_hi:[1,0,1]
	v_pk_fma_f32 v[126:127], v[158:159], v[24:25], v[126:127] op_sel_hi:[1,0,1]
	s_waitcnt vmcnt(8)
	v_cvt_pk_f32_fp8_e32 v[144:145], v76
	v_cvt_pk_f32_fp8_sdwa v[146:147], v76 src0_sel:WORD_1
	v_cvt_pk_f32_fp8_e32 v[148:149], v77
	v_cvt_pk_f32_fp8_sdwa v[150:151], v77 src0_sel:WORD_1
	v_cvt_pk_f32_fp8_e32 v[152:153], v78
	v_cvt_pk_f32_fp8_sdwa v[154:155], v78 src0_sel:WORD_1
	v_cvt_pk_f32_fp8_e32 v[156:157], v79
	v_cvt_pk_f32_fp8_sdwa v[158:159], v79 src0_sel:WORD_1
	v_pk_fma_f32 v[112:113], v[144:145], v[26:27], v[112:113] op_sel_hi:[1,0,1]
	v_pk_fma_f32 v[114:115], v[146:147], v[26:27], v[114:115] op_sel_hi:[1,0,1]
	v_pk_fma_f32 v[116:117], v[148:149], v[26:27], v[116:117] op_sel_hi:[1,0,1]
	v_pk_fma_f32 v[118:119], v[150:151], v[26:27], v[118:119] op_sel_hi:[1,0,1]
	v_pk_fma_f32 v[120:121], v[152:153], v[26:27], v[120:121] op_sel_hi:[1,0,1]
	v_pk_fma_f32 v[122:123], v[154:155], v[26:27], v[122:123] op_sel_hi:[1,0,1]
	v_pk_fma_f32 v[124:125], v[156:157], v[26:27], v[124:125] op_sel_hi:[1,0,1]
	v_pk_fma_f32 v[126:127], v[158:159], v[26:27], v[126:127] op_sel_hi:[1,0,1]
	s_waitcnt vmcnt(7)
	v_cvt_pk_f32_fp8_e32 v[144:145], v80
	v_cvt_pk_f32_fp8_sdwa v[146:147], v80 src0_sel:WORD_1
	v_cvt_pk_f32_fp8_e32 v[148:149], v81
	v_cvt_pk_f32_fp8_sdwa v[150:151], v81 src0_sel:WORD_1
	v_cvt_pk_f32_fp8_e32 v[152:153], v82
	v_cvt_pk_f32_fp8_sdwa v[154:155], v82 src0_sel:WORD_1
	v_cvt_pk_f32_fp8_e32 v[156:157], v83
	v_cvt_pk_f32_fp8_sdwa v[158:159], v83 src0_sel:WORD_1
	v_pk_fma_f32 v[112:113], v[144:145], v[28:29], v[112:113] op_sel_hi:[1,0,1]
	v_pk_fma_f32 v[114:115], v[146:147], v[28:29], v[114:115] op_sel_hi:[1,0,1]
	v_pk_fma_f32 v[116:117], v[148:149], v[28:29], v[116:117] op_sel_hi:[1,0,1]
	v_pk_fma_f32 v[118:119], v[150:151], v[28:29], v[118:119] op_sel_hi:[1,0,1]
	v_pk_fma_f32 v[120:121], v[152:153], v[28:29], v[120:121] op_sel_hi:[1,0,1]
	v_pk_fma_f32 v[122:123], v[154:155], v[28:29], v[122:123] op_sel_hi:[1,0,1]
	v_pk_fma_f32 v[124:125], v[156:157], v[28:29], v[124:125] op_sel_hi:[1,0,1]
	v_pk_fma_f32 v[126:127], v[158:159], v[28:29], v[126:127] op_sel_hi:[1,0,1]
	s_waitcnt vmcnt(6)
	v_cvt_pk_f32_fp8_e32 v[144:145], v84
	v_cvt_pk_f32_fp8_sdwa v[146:147], v84 src0_sel:WORD_1
	v_cvt_pk_f32_fp8_e32 v[148:149], v85
	v_cvt_pk_f32_fp8_sdwa v[150:151], v85 src0_sel:WORD_1
	v_cvt_pk_f32_fp8_e32 v[152:153], v86
	v_cvt_pk_f32_fp8_sdwa v[154:155], v86 src0_sel:WORD_1
	v_cvt_pk_f32_fp8_e32 v[156:157], v87
	v_cvt_pk_f32_fp8_sdwa v[158:159], v87 src0_sel:WORD_1
	v_pk_fma_f32 v[112:113], v[144:145], v[30:31], v[112:113] op_sel_hi:[1,0,1]
	v_pk_fma_f32 v[114:115], v[146:147], v[30:31], v[114:115] op_sel_hi:[1,0,1]
	v_pk_fma_f32 v[116:117], v[148:149], v[30:31], v[116:117] op_sel_hi:[1,0,1]
	v_pk_fma_f32 v[118:119], v[150:151], v[30:31], v[118:119] op_sel_hi:[1,0,1]
	v_pk_fma_f32 v[120:121], v[152:153], v[30:31], v[120:121] op_sel_hi:[1,0,1]
	v_pk_fma_f32 v[122:123], v[154:155], v[30:31], v[122:123] op_sel_hi:[1,0,1]
	v_pk_fma_f32 v[124:125], v[156:157], v[30:31], v[124:125] op_sel_hi:[1,0,1]
	v_pk_fma_f32 v[126:127], v[158:159], v[30:31], v[126:127] op_sel_hi:[1,0,1]
	s_waitcnt vmcnt(5)
	v_cvt_pk_f32_fp8_e32 v[144:145], v88
	v_cvt_pk_f32_fp8_sdwa v[146:147], v88 src0_sel:WORD_1
	v_cvt_pk_f32_fp8_e32 v[148:149], v89
	v_cvt_pk_f32_fp8_sdwa v[150:151], v89 src0_sel:WORD_1
	v_cvt_pk_f32_fp8_e32 v[152:153], v90
	v_cvt_pk_f32_fp8_sdwa v[154:155], v90 src0_sel:WORD_1
	v_cvt_pk_f32_fp8_e32 v[156:157], v91
	v_cvt_pk_f32_fp8_sdwa v[158:159], v91 src0_sel:WORD_1
	v_pk_fma_f32 v[112:113], v[144:145], v[32:33], v[112:113] op_sel_hi:[1,0,1]
	v_pk_fma_f32 v[114:115], v[146:147], v[32:33], v[114:115] op_sel_hi:[1,0,1]
	v_pk_fma_f32 v[116:117], v[148:149], v[32:33], v[116:117] op_sel_hi:[1,0,1]
	v_pk_fma_f32 v[118:119], v[150:151], v[32:33], v[118:119] op_sel_hi:[1,0,1]
	v_pk_fma_f32 v[120:121], v[152:153], v[32:33], v[120:121] op_sel_hi:[1,0,1]
	v_pk_fma_f32 v[122:123], v[154:155], v[32:33], v[122:123] op_sel_hi:[1,0,1]
	v_pk_fma_f32 v[124:125], v[156:157], v[32:33], v[124:125] op_sel_hi:[1,0,1]
	v_pk_fma_f32 v[126:127], v[158:159], v[32:33], v[126:127] op_sel_hi:[1,0,1]
	s_waitcnt vmcnt(4)
	v_cvt_pk_f32_fp8_e32 v[144:145], v92
	v_cvt_pk_f32_fp8_sdwa v[146:147], v92 src0_sel:WORD_1
	v_cvt_pk_f32_fp8_e32 v[148:149], v93
	v_cvt_pk_f32_fp8_sdwa v[150:151], v93 src0_sel:WORD_1
	v_cvt_pk_f32_fp8_e32 v[152:153], v94
	v_cvt_pk_f32_fp8_sdwa v[154:155], v94 src0_sel:WORD_1
	v_cvt_pk_f32_fp8_e32 v[156:157], v95
	v_cvt_pk_f32_fp8_sdwa v[158:159], v95 src0_sel:WORD_1
	v_pk_fma_f32 v[112:113], v[144:145], v[34:35], v[112:113] op_sel_hi:[1,0,1]
	v_pk_fma_f32 v[114:115], v[146:147], v[34:35], v[114:115] op_sel_hi:[1,0,1]
	v_pk_fma_f32 v[116:117], v[148:149], v[34:35], v[116:117] op_sel_hi:[1,0,1]
	v_pk_fma_f32 v[118:119], v[150:151], v[34:35], v[118:119] op_sel_hi:[1,0,1]
	v_pk_fma_f32 v[120:121], v[152:153], v[34:35], v[120:121] op_sel_hi:[1,0,1]
	v_pk_fma_f32 v[122:123], v[154:155], v[34:35], v[122:123] op_sel_hi:[1,0,1]
	v_pk_fma_f32 v[124:125], v[156:157], v[34:35], v[124:125] op_sel_hi:[1,0,1]
	v_pk_fma_f32 v[126:127], v[158:159], v[34:35], v[126:127] op_sel_hi:[1,0,1]
	s_waitcnt vmcnt(3)
	v_cvt_pk_f32_fp8_e32 v[144:145], v96
	v_cvt_pk_f32_fp8_sdwa v[146:147], v96 src0_sel:WORD_1
	v_cvt_pk_f32_fp8_e32 v[148:149], v97
	v_cvt_pk_f32_fp8_sdwa v[150:151], v97 src0_sel:WORD_1
	v_cvt_pk_f32_fp8_e32 v[152:153], v98
	v_cvt_pk_f32_fp8_sdwa v[154:155], v98 src0_sel:WORD_1
	v_cvt_pk_f32_fp8_e32 v[156:157], v99
	v_cvt_pk_f32_fp8_sdwa v[158:159], v99 src0_sel:WORD_1
	v_pk_fma_f32 v[112:113], v[144:145], v[36:37], v[112:113] op_sel_hi:[1,0,1]
	v_pk_fma_f32 v[114:115], v[146:147], v[36:37], v[114:115] op_sel_hi:[1,0,1]
	v_pk_fma_f32 v[116:117], v[148:149], v[36:37], v[116:117] op_sel_hi:[1,0,1]
	v_pk_fma_f32 v[118:119], v[150:151], v[36:37], v[118:119] op_sel_hi:[1,0,1]
	v_pk_fma_f32 v[120:121], v[152:153], v[36:37], v[120:121] op_sel_hi:[1,0,1]
	v_pk_fma_f32 v[122:123], v[154:155], v[36:37], v[122:123] op_sel_hi:[1,0,1]
	v_pk_fma_f32 v[124:125], v[156:157], v[36:37], v[124:125] op_sel_hi:[1,0,1]
	v_pk_fma_f32 v[126:127], v[158:159], v[36:37], v[126:127] op_sel_hi:[1,0,1]
	s_waitcnt vmcnt(2)
	v_cvt_pk_f32_fp8_e32 v[144:145], v100
	v_cvt_pk_f32_fp8_sdwa v[146:147], v100 src0_sel:WORD_1
	v_cvt_pk_f32_fp8_e32 v[148:149], v101
	v_cvt_pk_f32_fp8_sdwa v[150:151], v101 src0_sel:WORD_1
	v_cvt_pk_f32_fp8_e32 v[152:153], v102
	v_cvt_pk_f32_fp8_sdwa v[154:155], v102 src0_sel:WORD_1
	v_cvt_pk_f32_fp8_e32 v[156:157], v103
	v_cvt_pk_f32_fp8_sdwa v[158:159], v103 src0_sel:WORD_1
	v_pk_fma_f32 v[112:113], v[144:145], v[38:39], v[112:113] op_sel_hi:[1,0,1]
	v_pk_fma_f32 v[114:115], v[146:147], v[38:39], v[114:115] op_sel_hi:[1,0,1]
	v_pk_fma_f32 v[116:117], v[148:149], v[38:39], v[116:117] op_sel_hi:[1,0,1]
	v_pk_fma_f32 v[118:119], v[150:151], v[38:39], v[118:119] op_sel_hi:[1,0,1]
	v_pk_fma_f32 v[120:121], v[152:153], v[38:39], v[120:121] op_sel_hi:[1,0,1]
	v_pk_fma_f32 v[122:123], v[154:155], v[38:39], v[122:123] op_sel_hi:[1,0,1]
	v_pk_fma_f32 v[124:125], v[156:157], v[38:39], v[124:125] op_sel_hi:[1,0,1]
	v_pk_fma_f32 v[126:127], v[158:159], v[38:39], v[126:127] op_sel_hi:[1,0,1]
	s_waitcnt vmcnt(1)
	v_cvt_pk_f32_fp8_e32 v[144:145], v104
	v_cvt_pk_f32_fp8_sdwa v[146:147], v104 src0_sel:WORD_1
	v_cvt_pk_f32_fp8_e32 v[148:149], v105
	v_cvt_pk_f32_fp8_sdwa v[150:151], v105 src0_sel:WORD_1
	v_cvt_pk_f32_fp8_e32 v[152:153], v106
	v_cvt_pk_f32_fp8_sdwa v[154:155], v106 src0_sel:WORD_1
	v_cvt_pk_f32_fp8_e32 v[156:157], v107
	v_cvt_pk_f32_fp8_sdwa v[158:159], v107 src0_sel:WORD_1
	v_pk_fma_f32 v[112:113], v[144:145], v[40:41], v[112:113] op_sel_hi:[1,0,1]
	v_pk_fma_f32 v[114:115], v[146:147], v[40:41], v[114:115] op_sel_hi:[1,0,1]
	v_pk_fma_f32 v[116:117], v[148:149], v[40:41], v[116:117] op_sel_hi:[1,0,1]
	v_pk_fma_f32 v[118:119], v[150:151], v[40:41], v[118:119] op_sel_hi:[1,0,1]
	v_pk_fma_f32 v[120:121], v[152:153], v[40:41], v[120:121] op_sel_hi:[1,0,1]
	v_pk_fma_f32 v[122:123], v[154:155], v[40:41], v[122:123] op_sel_hi:[1,0,1]
	v_pk_fma_f32 v[124:125], v[156:157], v[40:41], v[124:125] op_sel_hi:[1,0,1]
	v_pk_fma_f32 v[126:127], v[158:159], v[40:41], v[126:127] op_sel_hi:[1,0,1]
	s_waitcnt vmcnt(0)
; __device__ __forceinline__ void peer_up_phase(const Ctx& C, const unsigned char* EU, bf16* XBN, float* RSS, float* xio, const float* gfinal, bool last, const float* SELG, const int* SELI) {
;     ...
; #pragma unroll 1
;             for (int grp = 0; grp < 16; grp += 2) { USTEP(upA, grp); USTEP(upB, grp + 1); }
;     ...
;             f32x4 x0 = (f32x4){bflo(xw0[0]), bfhi(xw0[0]), bflo(xw0[1]), bfhi(xw0[1])}, x1 = (f32x4){bflo(xw0[2]), bfhi(xw0[2]), bflo(xw0[3]), bfhi(xw0[3])};
;             f32x4 x2 = (f32x4){bflo(xw1[0]), bfhi(xw1[0]), bflo(xw1[1]), bfhi(xw1[1])}, x3 = (f32x4){bflo(xw1[2]), bfhi(xw1[2]), bflo(xw1[3]), bfhi(xw1[3])};
;             x0 += (f32x4){y[0].x, y[0].y, y[1].x, y[1].y}; x1 += (f32x4){y[2].x, y[2].y, y[3].x, y[3].y}; x2 += (f32x4){y[4].x, y[4].y, y[5].x, y[5].y}; x3 += (f32x4){y[6].x, y[6].y, y[7].x, y[7].y};
;             if (last) {
;                 const float ss = (x0.x * x0.x + x0.y * x0.y) + (x0.z * x0.z + x0.w * x0.w) + (x1.x * x1.x + x1.y * x1.y) + (x1.z * x1.z + x1.w * x1.w)
;                                + (x2.x * x2.x + x2.y * x2.y) + (x2.z * x2.z + x2.w * x2.w) + (x3.x * x3.x + x3.y * x3.y) + (x3.z * x3.z + x3.w * x3.w);
;                 const float rstd = 1.0f / sqrtf(wave_sum(ss) * (1.f / DM) + RMS_EPS);
;                 float* xr = xio + tok * DM + 16 * gl;
;                 const float* gp = gfinal + 16 * gl;
;                 const f32x4 g0 = *(const f32x4*)gp, g1 = *(const f32x4*)(gp + 4), g2 = *(const f32x4*)(gp + 8), g3 = *(const f32x4*)(gp + 12);
;                 __builtin_nontemporal_store(x0 * rstd * g0, (f32x4*)xr); __builtin_nontemporal_store(x1 * rstd * g1, (f32x4*)(xr + 4)); __builtin_nontemporal_store(x2 * rstd * g2, (f32x4*)(xr + 8)); __builtin_nontemporal_store(x3 * rstd * g3, (f32x4*)(xr + 12));
;             } else {
;                 v4u w0, w1; w0.x = pk2(x0.x, x0.y); w0.y = pk2(x0.z, x0.w); w0.z = pk2(x1.x, x1.y); w0.w = pk2(x1.z, x1.w);
;                 w1.x = pk2(x2.x, x2.y); w1.y = pk2(x2.z, x2.w); w1.z = pk2(x3.x, x3.y); w1.w = pk2(x3.z, x3.w);
;                 float ss = 0.f;
; #pragma unroll
;                 for (int w = 0; w < 4; ++w) { const float a0 = bflo(w0[w]), a1 = bfhi(w0[w]), b0 = bflo(w1[w]), b1 = bfhi(w1[w]); ss += (a0 * a0 + a1 * a1) + (b0 * b0 + b1 * b1); }
;                 const float sst = wave_sum(ss);
;                 *(v4u*)xr16 = w0; *(v4u*)(xr16 + 8) = w1;
	v_cvt_pk_f32_fp8_e32 v[144:145], v108
	v_cvt_pk_f32_fp8_sdwa v[146:147], v108 src0_sel:WORD_1
	v_cvt_pk_f32_fp8_e32 v[148:149], v109
	v_cvt_pk_f32_fp8_sdwa v[150:151], v109 src0_sel:WORD_1
	v_cvt_pk_f32_fp8_e32 v[152:153], v110
	v_cvt_pk_f32_fp8_sdwa v[154:155], v110 src0_sel:WORD_1
	v_cvt_pk_f32_fp8_e32 v[156:157], v111
	v_cvt_pk_f32_fp8_sdwa v[158:159], v111 src0_sel:WORD_1
	v_pk_fma_f32 v[112:113], v[144:145], v[42:43], v[112:113] op_sel_hi:[1,0,1]
	v_pk_fma_f32 v[114:115], v[146:147], v[42:43], v[114:115] op_sel_hi:[1,0,1]
	v_pk_fma_f32 v[116:117], v[148:149], v[42:43], v[116:117] op_sel_hi:[1,0,1]
	v_pk_fma_f32 v[118:119], v[150:151], v[42:43], v[118:119] op_sel_hi:[1,0,1]
	v_pk_fma_f32 v[120:121], v[152:153], v[42:43], v[120:121] op_sel_hi:[1,0,1]
	v_pk_fma_f32 v[122:123], v[154:155], v[42:43], v[122:123] op_sel_hi:[1,0,1]
	v_pk_fma_f32 v[124:125], v[156:157], v[42:43], v[124:125] op_sel_hi:[1,0,1]
	v_pk_fma_f32 v[126:127], v[158:159], v[42:43], v[126:127] op_sel_hi:[1,0,1]
	s_nop 1
	v_permlane32_swap_b32_e32 v112, v120
	v_permlane32_swap_b32_e32 v113, v121
	v_permlane32_swap_b32_e32 v114, v122
	v_permlane32_swap_b32_e32 v115, v123
	v_permlane32_swap_b32_e32 v116, v124
	v_permlane32_swap_b32_e32 v117, v125
	v_permlane32_swap_b32_e32 v118, v126
	v_permlane32_swap_b32_e32 v119, v127
	v_add_f32_e32 v112, v112, v120
	v_add_f32_e32 v113, v113, v121
	v_add_f32_e32 v114, v114, v122
	v_add_f32_e32 v115, v115, v123
	v_add_f32_e32 v116, v116, v124
	v_add_f32_e32 v117, v117, v125
	v_add_f32_e32 v118, v118, v126
	v_add_f32_e32 v119, v119, v127
	s_nop 1
	v_permlane16_swap_b32_e32 v112, v116
	v_permlane16_swap_b32_e32 v113, v117
	v_permlane16_swap_b32_e32 v114, v118
	v_permlane16_swap_b32_e32 v115, v119
	v_add_f32_e32 v112, v112, v116
	v_add_f32_e32 v113, v113, v117
	v_add_f32_e32 v114, v114, v118
	v_add_f32_e32 v115, v115, v119
	s_nop 1
	v_add_f32_dpp v112, v112, v112 row_ror:8 row_mask:0xf bank_mask:0xf
	v_add_f32_dpp v113, v113, v113 row_ror:8 row_mask:0xf bank_mask:0xf
	v_add_f32_dpp v114, v114, v114 row_ror:8 row_mask:0xf bank_mask:0xf
	v_add_f32_dpp v115, v115, v115 row_ror:8 row_mask:0xf bank_mask:0xf
	v_lshlrev_b32_e32 v44, 16, v10
	v_and_b32_e32 v45, 0xffff0000, v10
	v_lshlrev_b32_e32 v46, 16, v11
	v_and_b32_e32 v47, 0xffff0000, v11
	v_add_f32_e32 v44, v44, v112
	v_add_f32_e32 v45, v45, v113
	v_add_f32_e32 v46, v46, v114
	v_add_f32_e32 v47, v47, v115
	v_cvt_pk_bf16_f32 v10, v44, v45
	v_cvt_pk_bf16_f32 v11, v46, v47
	s_lshl_b32 s2, s14, 6
	s_add_u32 s0, s12, s2
	s_addc_u32 s1, s13, 0
	global_store_dwordx2 v5, v[10:11], s[18:19]
	v_lshlrev_b32_e32 v44, 16, v10
	v_and_b32_e32 v45, 0xffff0000, v10
	v_lshlrev_b32_e32 v46, 16, v11
	v_and_b32_e32 v47, 0xffff0000, v11
	v_mul_f32_e32 v44, v44, v44
	v_fmac_f32_e32 v44, v45, v45
	v_fmac_f32_e32 v44, v46, v46
	v_fmac_f32_e32 v44, v47, v47
	s_nop 1
	v_add_f32_dpp v44, v44, v44 quad_perm:[1,0,3,2] row_mask:0xf bank_mask:0xf
	s_nop 1
	v_add_f32_dpp v44, v44, v44 quad_perm:[2,3,0,1] row_mask:0xf bank_mask:0xf
	s_nop 1
	v_add_f32_dpp v44, v44, v44 row_half_mirror row_mask:0xf bank_mask:0xf
	v_mov_b32_e32 v45, v44
	s_nop 1
	v_permlane16_swap_b32_e32 v44, v45
	v_add_f32_e32 v44, v44, v45
	v_mov_b32_e32 v45, v44
	s_nop 1
	v_permlane32_swap_b32_e32 v44, v45
	v_add_f32_e32 v44, v44, v45
	s_mov_b64 exec, 1
	global_store_dword v160, v44, s[0:1]
	global_store_dword v160, v160, s[0:1] offset:32
	s_mov_b64 exec, -1
	s_add_i32 s14, s14, s15
	s_cmp_lt_u32 s14, 0x10000
	s_cbranch_scc1 .Lup_tok
	s_branch .Lup_done
.Lupp_start:
	s_mov_b32 s20, 0
	s_mov_b32 s15, 0
	s_mov_b32 s17, 0
	s_lshl_b32 s2, s17, 8
	s_add_i32 s2, s2, s14
	s_lshl_b32 s2, s2, 9
	s_add_u32 s0, s6, s2
	s_addc_u32 s1, s7, 0
	global_load_dword v6, v4, s[0:1]
	global_load_dword v8, v4, s[0:1] offset:256
	s_add_u32 s0, s4, s2
	s_addc_u32 s1, s5, 0
	global_load_dword v7, v4, s[0:1]
	global_load_dword v9, v4, s[0:1] offset:256
	s_waitcnt vmcnt(0)
	v_add_u32_e32 v161, s15, v3
	ds_write_b64 v161, v[6:7]
	ds_write_b64 v161, v[8:9] offset:512
	s_mov_b32 s17, 1
	s_lshl_b32 s2, s17, 8
	s_add_i32 s2, s2, s14
	s_lshl_b32 s2, s2, 9
	s_add_u32 s0, s6, s2
	s_addc_u32 s1, s7, 0
	global_load_dword v6, v4, s[0:1]
	global_load_dword v8, v4, s[0:1] offset:256
	s_add_u32 s0, s4, s2
	s_addc_u32 s1, s5, 0
	global_load_dword v7, v4, s[0:1]
	global_load_dword v9, v4, s[0:1] offset:256
	s_waitcnt vmcnt(0)
	s_movk_i32 s16, 0x400
	v_add_u32_e32 v161, s16, v3
	ds_write_b64 v161, v[6:7]
	ds_write_b64 v161, v[8:9] offset:512
	v_add_u32_e32 v162, s15, v2
	ds_read_b64 v[12:13], v162
	ds_read_b64 v[14:15], v162 offset:64
	ds_read_b64 v[16:17], v162 offset:128
	ds_read_b64 v[18:19], v162 offset:192
	ds_read_b64 v[20:21], v162 offset:256
	ds_read_b64 v[22:23], v162 offset:320
	ds_read_b64 v[24:25], v162 offset:384
	ds_read_b64 v[26:27], v162 offset:448
	v_add_u32_e32 v162, s15, v2
	ds_read_b64 v[28:29], v162 offset:512
	ds_read_b64 v[30:31], v162 offset:576
	ds_read_b64 v[32:33], v162 offset:640
	ds_read_b64 v[34:35], v162 offset:704
	ds_read_b64 v[36:37], v162 offset:768
	ds_read_b64 v[38:39], v162 offset:832
	ds_read_b64 v[40:41], v162 offset:896
	ds_read_b64 v[42:43], v162 offset:960
	s_waitcnt lgkmcnt(4)
	v_lshl_add_u32 v13, v13, 7, v1
	global_load_dwordx4 v[48:51], v13, s[8:9]
	v_lshl_add_u32 v15, v15, 7, v1
	global_load_dwordx4 v[52:55], v15, s[8:9]
	v_lshl_add_u32 v17, v17, 7, v1
	global_load_dwordx4 v[56:59], v17, s[8:9]
	v_lshl_add_u32 v19, v19, 7, v1
	global_load_dwordx4 v[60:63], v19, s[8:9]
	s_waitcnt lgkmcnt(0)
	v_lshl_add_u32 v21, v21, 7, v1
	global_load_dwordx4 v[64:67], v21, s[8:9]
	v_lshl_add_u32 v23, v23, 7, v1
	global_load_dwordx4 v[68:71], v23, s[8:9]
	v_lshl_add_u32 v25, v25, 7, v1
	global_load_dwordx4 v[72:75], v25, s[8:9]
	v_lshl_add_u32 v27, v27, 7, v1
	global_load_dwordx4 v[76:79], v27, s[8:9]
	s_waitcnt lgkmcnt(4)
	v_lshl_add_u32 v29, v29, 7, v1
	global_load_dwordx4 v[80:83], v29, s[8:9]
	v_lshl_add_u32 v31, v31, 7, v1
	global_load_dwordx4 v[84:87], v31, s[8:9]
	v_lshl_add_u32 v33, v33, 7, v1
	global_load_dwordx4 v[88:91], v33, s[8:9]
	v_lshl_add_u32 v35, v35, 7, v1
	global_load_dwordx4 v[92:95], v35, s[8:9]
	s_waitcnt lgkmcnt(0)
	v_lshl_add_u32 v37, v37, 7, v1
	global_load_dwordx4 v[96:99], v37, s[8:9]
	v_lshl_add_u32 v39, v39, 7, v1
	global_load_dwordx4 v[100:103], v39, s[8:9]
	v_lshl_add_u32 v41, v41, 7, v1
	global_load_dwordx4 v[104:107], v41, s[8:9]
	v_lshl_add_u32 v43, v43, 7, v1
	global_load_dwordx4 v[108:111], v43, s[8:9]
	global_load_dword v163, v4, s[6:7]
	global_load_dword v163, v4, s[6:7]
	global_load_dword v163, v4, s[6:7]
	s_mov_b32 s17, 0
	s_lshl_b32 s2, s17, 8
	s_add_i32 s2, s2, s14
	s_lshl_b32 s2, s2, 11
	s_add_u32 s18, s10, s2
	s_addc_u32 s19, s11, 0
	global_load_dwordx2 v[10:11], v5, s[18:19]
	s_mov_b32 s17, 2
	s_lshl_b32 s2, s17, 8
	s_add_i32 s2, s2, s14
	s_lshl_b32 s2, s2, 9
	s_add_u32 s0, s6, s2
	s_addc_u32 s1, s7, 0
	global_load_dword v6, v4, s[0:1]
	global_load_dword v8, v4, s[0:1] offset:256
	s_add_u32 s0, s4, s2
	s_addc_u32 s1, s5, 0
	global_load_dword v7, v4, s[0:1]
	global_load_dword v9, v4, s[0:1] offset:256
; __device__ __forceinline__ void peer_up_phase(const Ctx& C, const unsigned char* EU, bf16* XBN, float* RSS, float* xio, const float* gfinal, bool last, const float* SELG, const int* SELI) {
;     ...
; #pragma unroll 1
;             for (int grp = 0; grp < 16; grp += 2) { USTEP(upA, grp); USTEP(upB, grp + 1); }
.Lupp_tok:
	v_mov_b64_e32 v[112:113], 0
	v_mov_b64_e32 v[114:115], 0
	v_mov_b64_e32 v[116:117], 0
	v_mov_b64_e32 v[118:119], 0
	v_mov_b64_e32 v[120:121], 0
	v_mov_b64_e32 v[122:123], 0
	v_mov_b64_e32 v[124:125], 0
	v_mov_b64_e32 v[126:127], 0
	s_xor_b32 s16, s15, 0x400
	s_waitcnt vmcnt(23)
	v_cvt_pk_f32_fp8_e32 v[144:145], v48
	v_cvt_pk_f32_fp8_sdwa v[146:147], v48 src0_sel:WORD_1
	v_cvt_pk_f32_fp8_e32 v[148:149], v49
	v_cvt_pk_f32_fp8_sdwa v[150:151], v49 src0_sel:WORD_1
	v_cvt_pk_f32_fp8_e32 v[152:153], v50
	v_cvt_pk_f32_fp8_sdwa v[154:155], v50 src0_sel:WORD_1
	v_cvt_pk_f32_fp8_e32 v[156:157], v51
	v_cvt_pk_f32_fp8_sdwa v[158:159], v51 src0_sel:WORD_1
	v_pk_fma_f32 v[112:113], v[144:145], v[12:13], v[112:113] op_sel_hi:[1,0,1]
	v_pk_fma_f32 v[114:115], v[146:147], v[12:13], v[114:115] op_sel_hi:[1,0,1]
	v_pk_fma_f32 v[116:117], v[148:149], v[12:13], v[116:117] op_sel_hi:[1,0,1]
	v_pk_fma_f32 v[118:119], v[150:151], v[12:13], v[118:119] op_sel_hi:[1,0,1]
	v_pk_fma_f32 v[120:121], v[152:153], v[12:13], v[120:121] op_sel_hi:[1,0,1]
	v_pk_fma_f32 v[122:123], v[154:155], v[12:13], v[122:123] op_sel_hi:[1,0,1]
	v_pk_fma_f32 v[124:125], v[156:157], v[12:13], v[124:125] op_sel_hi:[1,0,1]
	v_pk_fma_f32 v[126:127], v[158:159], v[12:13], v[126:127] op_sel_hi:[1,0,1]
	s_waitcnt vmcnt(22)
	v_cvt_pk_f32_fp8_e32 v[144:145], v52
	v_cvt_pk_f32_fp8_sdwa v[146:147], v52 src0_sel:WORD_1
	v_cvt_pk_f32_fp8_e32 v[148:149], v53
	v_cvt_pk_f32_fp8_sdwa v[150:151], v53 src0_sel:WORD_1
	v_cvt_pk_f32_fp8_e32 v[152:153], v54
	v_cvt_pk_f32_fp8_sdwa v[154:155], v54 src0_sel:WORD_1
	v_cvt_pk_f32_fp8_e32 v[156:157], v55
	v_cvt_pk_f32_fp8_sdwa v[158:159], v55 src0_sel:WORD_1
	v_pk_fma_f32 v[112:113], v[144:145], v[14:15], v[112:113] op_sel_hi:[1,0,1]
	v_pk_fma_f32 v[114:115], v[146:147], v[14:15], v[114:115] op_sel_hi:[1,0,1]
	v_pk_fma_f32 v[116:117], v[148:149], v[14:15], v[116:117] op_sel_hi:[1,0,1]
	v_pk_fma_f32 v[118:119], v[150:151], v[14:15], v[118:119] op_sel_hi:[1,0,1]
	v_pk_fma_f32 v[120:121], v[152:153], v[14:15], v[120:121] op_sel_hi:[1,0,1]
	v_pk_fma_f32 v[122:123], v[154:155], v[14:15], v[122:123] op_sel_hi:[1,0,1]
	v_pk_fma_f32 v[124:125], v[156:157], v[14:15], v[124:125] op_sel_hi:[1,0,1]
	v_pk_fma_f32 v[126:127], v[158:159], v[14:15], v[126:127] op_sel_hi:[1,0,1]
	s_waitcnt vmcnt(21)
	v_cvt_pk_f32_fp8_e32 v[144:145], v56
	v_cvt_pk_f32_fp8_sdwa v[146:147], v56 src0_sel:WORD_1
	v_cvt_pk_f32_fp8_e32 v[148:149], v57
	v_cvt_pk_f32_fp8_sdwa v[150:151], v57 src0_sel:WORD_1
	v_cvt_pk_f32_fp8_e32 v[152:153], v58
	v_cvt_pk_f32_fp8_sdwa v[154:155], v58 src0_sel:WORD_1
	v_cvt_pk_f32_fp8_e32 v[156:157], v59
	v_cvt_pk_f32_fp8_sdwa v[158:159], v59 src0_sel:WORD_1
	v_pk_fma_f32 v[112:113], v[144:145], v[16:17], v[112:113] op_sel_hi:[1,0,1]
	v_pk_fma_f32 v[114:115], v[146:147], v[16:17], v[114:115] op_sel_hi:[1,0,1]
	v_pk_fma_f32 v[116:117], v[148:149], v[16:17], v[116:117] op_sel_hi:[1,0,1]
	v_pk_fma_f32 v[118:119], v[150:151], v[16:17], v[118:119] op_sel_hi:[1,0,1]
	v_pk_fma_f32 v[120:121], v[152:153], v[16:17], v[120:121] op_sel_hi:[1,0,1]
	v_pk_fma_f32 v[122:123], v[154:155], v[16:17], v[122:123] op_sel_hi:[1,0,1]
	v_pk_fma_f32 v[124:125], v[156:157], v[16:17], v[124:125] op_sel_hi:[1,0,1]
	v_pk_fma_f32 v[126:127], v[158:159], v[16:17], v[126:127] op_sel_hi:[1,0,1]
	s_waitcnt vmcnt(20)
	v_cvt_pk_f32_fp8_e32 v[144:145], v60
	v_cvt_pk_f32_fp8_sdwa v[146:147], v60 src0_sel:WORD_1
	v_cvt_pk_f32_fp8_e32 v[148:149], v61
	v_cvt_pk_f32_fp8_sdwa v[150:151], v61 src0_sel:WORD_1
	v_cvt_pk_f32_fp8_e32 v[152:153], v62
	v_cvt_pk_f32_fp8_sdwa v[154:155], v62 src0_sel:WORD_1
	v_cvt_pk_f32_fp8_e32 v[156:157], v63
	v_cvt_pk_f32_fp8_sdwa v[158:159], v63 src0_sel:WORD_1
	v_pk_fma_f32 v[112:113], v[144:145], v[18:19], v[112:113] op_sel_hi:[1,0,1]
	v_pk_fma_f32 v[114:115], v[146:147], v[18:19], v[114:115] op_sel_hi:[1,0,1]
	v_pk_fma_f32 v[116:117], v[148:149], v[18:19], v[116:117] op_sel_hi:[1,0,1]
	v_pk_fma_f32 v[118:119], v[150:151], v[18:19], v[118:119] op_sel_hi:[1,0,1]
	v_pk_fma_f32 v[120:121], v[152:153], v[18:19], v[120:121] op_sel_hi:[1,0,1]
	v_pk_fma_f32 v[122:123], v[154:155], v[18:19], v[122:123] op_sel_hi:[1,0,1]
	v_pk_fma_f32 v[124:125], v[156:157], v[18:19], v[124:125] op_sel_hi:[1,0,1]
	v_pk_fma_f32 v[126:127], v[158:159], v[18:19], v[126:127] op_sel_hi:[1,0,1]
	s_waitcnt vmcnt(19)
	v_cvt_pk_f32_fp8_e32 v[144:145], v64
	v_cvt_pk_f32_fp8_sdwa v[146:147], v64 src0_sel:WORD_1
	v_cvt_pk_f32_fp8_e32 v[148:149], v65
	v_cvt_pk_f32_fp8_sdwa v[150:151], v65 src0_sel:WORD_1
	v_cvt_pk_f32_fp8_e32 v[152:153], v66
	v_cvt_pk_f32_fp8_sdwa v[154:155], v66 src0_sel:WORD_1
	v_cvt_pk_f32_fp8_e32 v[156:157], v67
	v_cvt_pk_f32_fp8_sdwa v[158:159], v67 src0_sel:WORD_1
	v_pk_fma_f32 v[112:113], v[144:145], v[20:21], v[112:113] op_sel_hi:[1,0,1]
	v_pk_fma_f32 v[114:115], v[146:147], v[20:21], v[114:115] op_sel_hi:[1,0,1]
	v_pk_fma_f32 v[116:117], v[148:149], v[20:21], v[116:117] op_sel_hi:[1,0,1]
	v_pk_fma_f32 v[118:119], v[150:151], v[20:21], v[118:119] op_sel_hi:[1,0,1]
	v_pk_fma_f32 v[120:121], v[152:153], v[20:21], v[120:121] op_sel_hi:[1,0,1]
	v_pk_fma_f32 v[122:123], v[154:155], v[20:21], v[122:123] op_sel_hi:[1,0,1]
	v_pk_fma_f32 v[124:125], v[156:157], v[20:21], v[124:125] op_sel_hi:[1,0,1]
	v_pk_fma_f32 v[126:127], v[158:159], v[20:21], v[126:127] op_sel_hi:[1,0,1]
	s_waitcnt vmcnt(18)
; __device__ __forceinline__ void peer_up_phase(const Ctx& C, const unsigned char* EU, bf16* XBN, float* RSS, float* xio, const float* gfinal, bool last, const float* SELG, const int* SELI) {
;     ...
;             for (int k = 0; k < 8; ++k) { const int e = __builtin_amdgcn_readlane(vi0, k); upA[k] = *(const v4u*)(EU + (size_t)e * DM + 16 * gl); }
; #pragma unroll
;             for (int k = 0; k < 8; ++k) { const int e = __builtin_amdgcn_readlane(vi0, 8 + k); upB[k] = *(const v4u*)(EU + (size_t)e * DM + 16 * gl); }
;     ...
; #pragma unroll 1
;             for (int grp = 0; grp < 16; grp += 2) { USTEP(upA, grp); USTEP(upB, grp + 1); }
	v_cvt_pk_f32_fp8_e32 v[144:145], v68
	v_cvt_pk_f32_fp8_sdwa v[146:147], v68 src0_sel:WORD_1
	v_cvt_pk_f32_fp8_e32 v[148:149], v69
	v_cvt_pk_f32_fp8_sdwa v[150:151], v69 src0_sel:WORD_1
	v_cvt_pk_f32_fp8_e32 v[152:153], v70
	v_cvt_pk_f32_fp8_sdwa v[154:155], v70 src0_sel:WORD_1
	v_cvt_pk_f32_fp8_e32 v[156:157], v71
	v_cvt_pk_f32_fp8_sdwa v[158:159], v71 src0_sel:WORD_1
	v_pk_fma_f32 v[112:113], v[144:145], v[22:23], v[112:113] op_sel_hi:[1,0,1]
	v_pk_fma_f32 v[114:115], v[146:147], v[22:23], v[114:115] op_sel_hi:[1,0,1]
	v_pk_fma_f32 v[116:117], v[148:149], v[22:23], v[116:117] op_sel_hi:[1,0,1]
	v_pk_fma_f32 v[118:119], v[150:151], v[22:23], v[118:119] op_sel_hi:[1,0,1]
	v_pk_fma_f32 v[120:121], v[152:153], v[22:23], v[120:121] op_sel_hi:[1,0,1]
	v_pk_fma_f32 v[122:123], v[154:155], v[22:23], v[122:123] op_sel_hi:[1,0,1]
	v_pk_fma_f32 v[124:125], v[156:157], v[22:23], v[124:125] op_sel_hi:[1,0,1]
	v_pk_fma_f32 v[126:127], v[158:159], v[22:23], v[126:127] op_sel_hi:[1,0,1]
	s_waitcnt vmcnt(17)
	v_cvt_pk_f32_fp8_e32 v[144:145], v72
	v_cvt_pk_f32_fp8_sdwa v[146:147], v72 src0_sel:WORD_1
	v_cvt_pk_f32_fp8_e32 v[148:149], v73
	v_cvt_pk_f32_fp8_sdwa v[150:151], v73 src0_sel:WORD_1
	v_cvt_pk_f32_fp8_e32 v[152:153], v74
	v_cvt_pk_f32_fp8_sdwa v[154:155], v74 src0_sel:WORD_1
	v_cvt_pk_f32_fp8_e32 v[156:157], v75
	v_cvt_pk_f32_fp8_sdwa v[158:159], v75 src0_sel:WORD_1
	v_pk_fma_f32 v[112:113], v[144:145], v[24:25], v[112:113] op_sel_hi:[1,0,1]
	v_pk_fma_f32 v[114:115], v[146:147], v[24:25], v[114:115] op_sel_hi:[1,0,1]
	v_pk_fma_f32 v[116:117], v[148:149], v[24:25], v[116:117] op_sel_hi:[1,0,1]
	v_pk_fma_f32 v[118:119], v[150:151], v[24:25], v[118:119] op_sel_hi:[1,0,1]
	v_pk_fma_f32 v[120:121], v[152:153], v[24:25], v[120:121] op_sel_hi:[1,0,1]
	v_pk_fma_f32 v[122:123], v[154:155], v[24:25], v[122:123] op_sel_hi:[1,0,1]
	v_pk_fma_f32 v[124:125], v[156:157], v[24:25], v[124:125] op_sel_hi:[1,0,1]
	v_pk_fma_f32 v[126:127], v[158:159], v[24:25], v[126:127] op_sel_hi:[1,0,1]
	s_waitcnt vmcnt(16)
	v_cvt_pk_f32_fp8_e32 v[144:145], v76
	v_cvt_pk_f32_fp8_sdwa v[146:147], v76 src0_sel:WORD_1
	v_cvt_pk_f32_fp8_e32 v[148:149], v77
	v_cvt_pk_f32_fp8_sdwa v[150:151], v77 src0_sel:WORD_1
	v_cvt_pk_f32_fp8_e32 v[152:153], v78
	v_cvt_pk_f32_fp8_sdwa v[154:155], v78 src0_sel:WORD_1
	v_cvt_pk_f32_fp8_e32 v[156:157], v79
	v_cvt_pk_f32_fp8_sdwa v[158:159], v79 src0_sel:WORD_1
	v_pk_fma_f32 v[112:113], v[144:145], v[26:27], v[112:113] op_sel_hi:[1,0,1]
	v_pk_fma_f32 v[114:115], v[146:147], v[26:27], v[114:115] op_sel_hi:[1,0,1]
	v_pk_fma_f32 v[116:117], v[148:149], v[26:27], v[116:117] op_sel_hi:[1,0,1]
	v_pk_fma_f32 v[118:119], v[150:151], v[26:27], v[118:119] op_sel_hi:[1,0,1]
	v_pk_fma_f32 v[120:121], v[152:153], v[26:27], v[120:121] op_sel_hi:[1,0,1]
	v_pk_fma_f32 v[122:123], v[154:155], v[26:27], v[122:123] op_sel_hi:[1,0,1]
	v_pk_fma_f32 v[124:125], v[156:157], v[26:27], v[124:125] op_sel_hi:[1,0,1]
	v_pk_fma_f32 v[126:127], v[158:159], v[26:27], v[126:127] op_sel_hi:[1,0,1]
	v_add_u32_e32 v162, s16, v2
	ds_read_b64 v[12:13], v162
	ds_read_b64 v[14:15], v162 offset:64
	ds_read_b64 v[16:17], v162 offset:128
	ds_read_b64 v[18:19], v162 offset:192
	ds_read_b64 v[20:21], v162 offset:256
	ds_read_b64 v[22:23], v162 offset:320
	ds_read_b64 v[24:25], v162 offset:384
	ds_read_b64 v[26:27], v162 offset:448
	s_waitcnt lgkmcnt(4)
	v_lshl_add_u32 v13, v13, 7, v1
	global_load_dwordx4 v[48:51], v13, s[8:9]
	v_lshl_add_u32 v15, v15, 7, v1
	global_load_dwordx4 v[52:55], v15, s[8:9]
	v_lshl_add_u32 v17, v17, 7, v1
	global_load_dwordx4 v[56:59], v17, s[8:9]
	v_lshl_add_u32 v19, v19, 7, v1
	global_load_dwordx4 v[60:63], v19, s[8:9]
	s_waitcnt lgkmcnt(0)
	v_lshl_add_u32 v21, v21, 7, v1
	global_load_dwordx4 v[64:67], v21, s[8:9]
	v_lshl_add_u32 v23, v23, 7, v1
	global_load_dwordx4 v[68:71], v23, s[8:9]
	v_lshl_add_u32 v25, v25, 7, v1
	global_load_dwordx4 v[72:75], v25, s[8:9]
	v_lshl_add_u32 v27, v27, 7, v1
	global_load_dwordx4 v[76:79], v27, s[8:9]
	s_waitcnt vmcnt(23)
	v_cvt_pk_f32_fp8_e32 v[144:145], v80
	v_cvt_pk_f32_fp8_sdwa v[146:147], v80 src0_sel:WORD_1
	v_cvt_pk_f32_fp8_e32 v[148:149], v81
	v_cvt_pk_f32_fp8_sdwa v[150:151], v81 src0_sel:WORD_1
	v_cvt_pk_f32_fp8_e32 v[152:153], v82
	v_cvt_pk_f32_fp8_sdwa v[154:155], v82 src0_sel:WORD_1
	v_cvt_pk_f32_fp8_e32 v[156:157], v83
	v_cvt_pk_f32_fp8_sdwa v[158:159], v83 src0_sel:WORD_1
	v_pk_fma_f32 v[112:113], v[144:145], v[28:29], v[112:113] op_sel_hi:[1,0,1]
	v_pk_fma_f32 v[114:115], v[146:147], v[28:29], v[114:115] op_sel_hi:[1,0,1]
	v_pk_fma_f32 v[116:117], v[148:149], v[28:29], v[116:117] op_sel_hi:[1,0,1]
	v_pk_fma_f32 v[118:119], v[150:151], v[28:29], v[118:119] op_sel_hi:[1,0,1]
	v_pk_fma_f32 v[120:121], v[152:153], v[28:29], v[120:121] op_sel_hi:[1,0,1]
	v_pk_fma_f32 v[122:123], v[154:155], v[28:29], v[122:123] op_sel_hi:[1,0,1]
	v_pk_fma_f32 v[124:125], v[156:157], v[28:29], v[124:125] op_sel_hi:[1,0,1]
	v_pk_fma_f32 v[126:127], v[158:159], v[28:29], v[126:127] op_sel_hi:[1,0,1]
	s_waitcnt vmcnt(22)
	v_cvt_pk_f32_fp8_e32 v[144:145], v84
	v_cvt_pk_f32_fp8_sdwa v[146:147], v84 src0_sel:WORD_1
	v_cvt_pk_f32_fp8_e32 v[148:149], v85
	v_cvt_pk_f32_fp8_sdwa v[150:151], v85 src0_sel:WORD_1
	v_cvt_pk_f32_fp8_e32 v[152:153], v86
	v_cvt_pk_f32_fp8_sdwa v[154:155], v86 src0_sel:WORD_1
	v_cvt_pk_f32_fp8_e32 v[156:157], v87
	v_cvt_pk_f32_fp8_sdwa v[158:159], v87 src0_sel:WORD_1
	v_pk_fma_f32 v[112:113], v[144:145], v[30:31], v[112:113] op_sel_hi:[1,0,1]
	v_pk_fma_f32 v[114:115], v[146:147], v[30:31], v[114:115] op_sel_hi:[1,0,1]
	v_pk_fma_f32 v[116:117], v[148:149], v[30:31], v[116:117] op_sel_hi:[1,0,1]
	v_pk_fma_f32 v[118:119], v[150:151], v[30:31], v[118:119] op_sel_hi:[1,0,1]
	v_pk_fma_f32 v[120:121], v[152:153], v[30:31], v[120:121] op_sel_hi:[1,0,1]
	v_pk_fma_f32 v[122:123], v[154:155], v[30:31], v[122:123] op_sel_hi:[1,0,1]
	v_pk_fma_f32 v[124:125], v[156:157], v[30:31], v[124:125] op_sel_hi:[1,0,1]
	v_pk_fma_f32 v[126:127], v[158:159], v[30:31], v[126:127] op_sel_hi:[1,0,1]
	s_waitcnt vmcnt(21)
; __device__ __forceinline__ void peer_up_phase(const Ctx& C, const unsigned char* EU, bf16* XBN, float* RSS, float* xio, const float* gfinal, bool last, const float* SELG, const int* SELI) {
;     ...
; #pragma unroll 1
;             for (int grp = 0; grp < 16; grp += 2) { USTEP(upA, grp); USTEP(upB, grp + 1); }
	v_cvt_pk_f32_fp8_e32 v[144:145], v88
	v_cvt_pk_f32_fp8_sdwa v[146:147], v88 src0_sel:WORD_1
	v_cvt_pk_f32_fp8_e32 v[148:149], v89
	v_cvt_pk_f32_fp8_sdwa v[150:151], v89 src0_sel:WORD_1
	v_cvt_pk_f32_fp8_e32 v[152:153], v90
	v_cvt_pk_f32_fp8_sdwa v[154:155], v90 src0_sel:WORD_1
	v_cvt_pk_f32_fp8_e32 v[156:157], v91
	v_cvt_pk_f32_fp8_sdwa v[158:159], v91 src0_sel:WORD_1
	v_pk_fma_f32 v[112:113], v[144:145], v[32:33], v[112:113] op_sel_hi:[1,0,1]
	v_pk_fma_f32 v[114:115], v[146:147], v[32:33], v[114:115] op_sel_hi:[1,0,1]
	v_pk_fma_f32 v[116:117], v[148:149], v[32:33], v[116:117] op_sel_hi:[1,0,1]
	v_pk_fma_f32 v[118:119], v[150:151], v[32:33], v[118:119] op_sel_hi:[1,0,1]
	v_pk_fma_f32 v[120:121], v[152:153], v[32:33], v[120:121] op_sel_hi:[1,0,1]
	v_pk_fma_f32 v[122:123], v[154:155], v[32:33], v[122:123] op_sel_hi:[1,0,1]
	v_pk_fma_f32 v[124:125], v[156:157], v[32:33], v[124:125] op_sel_hi:[1,0,1]
	v_pk_fma_f32 v[126:127], v[158:159], v[32:33], v[126:127] op_sel_hi:[1,0,1]
	s_waitcnt vmcnt(20)
	v_cvt_pk_f32_fp8_e32 v[144:145], v92
	v_cvt_pk_f32_fp8_sdwa v[146:147], v92 src0_sel:WORD_1
	v_cvt_pk_f32_fp8_e32 v[148:149], v93
	v_cvt_pk_f32_fp8_sdwa v[150:151], v93 src0_sel:WORD_1
	v_cvt_pk_f32_fp8_e32 v[152:153], v94
	v_cvt_pk_f32_fp8_sdwa v[154:155], v94 src0_sel:WORD_1
	v_cvt_pk_f32_fp8_e32 v[156:157], v95
	v_cvt_pk_f32_fp8_sdwa v[158:159], v95 src0_sel:WORD_1
	v_pk_fma_f32 v[112:113], v[144:145], v[34:35], v[112:113] op_sel_hi:[1,0,1]
	v_pk_fma_f32 v[114:115], v[146:147], v[34:35], v[114:115] op_sel_hi:[1,0,1]
	v_pk_fma_f32 v[116:117], v[148:149], v[34:35], v[116:117] op_sel_hi:[1,0,1]
	v_pk_fma_f32 v[118:119], v[150:151], v[34:35], v[118:119] op_sel_hi:[1,0,1]
	v_pk_fma_f32 v[120:121], v[152:153], v[34:35], v[120:121] op_sel_hi:[1,0,1]
	v_pk_fma_f32 v[122:123], v[154:155], v[34:35], v[122:123] op_sel_hi:[1,0,1]
	v_pk_fma_f32 v[124:125], v[156:157], v[34:35], v[124:125] op_sel_hi:[1,0,1]
	v_pk_fma_f32 v[126:127], v[158:159], v[34:35], v[126:127] op_sel_hi:[1,0,1]
	s_waitcnt vmcnt(19)
	v_cvt_pk_f32_fp8_e32 v[144:145], v96
	v_cvt_pk_f32_fp8_sdwa v[146:147], v96 src0_sel:WORD_1
	v_cvt_pk_f32_fp8_e32 v[148:149], v97
	v_cvt_pk_f32_fp8_sdwa v[150:151], v97 src0_sel:WORD_1
	v_cvt_pk_f32_fp8_e32 v[152:153], v98
	v_cvt_pk_f32_fp8_sdwa v[154:155], v98 src0_sel:WORD_1
	v_cvt_pk_f32_fp8_e32 v[156:157], v99
	v_cvt_pk_f32_fp8_sdwa v[158:159], v99 src0_sel:WORD_1
	v_pk_fma_f32 v[112:113], v[144:145], v[36:37], v[112:113] op_sel_hi:[1,0,1]
	v_pk_fma_f32 v[114:115], v[146:147], v[36:37], v[114:115] op_sel_hi:[1,0,1]
	v_pk_fma_f32 v[116:117], v[148:149], v[36:37], v[116:117] op_sel_hi:[1,0,1]
	v_pk_fma_f32 v[118:119], v[150:151], v[36:37], v[118:119] op_sel_hi:[1,0,1]
	v_pk_fma_f32 v[120:121], v[152:153], v[36:37], v[120:121] op_sel_hi:[1,0,1]
	v_pk_fma_f32 v[122:123], v[154:155], v[36:37], v[122:123] op_sel_hi:[1,0,1]
	v_pk_fma_f32 v[124:125], v[156:157], v[36:37], v[124:125] op_sel_hi:[1,0,1]
	v_pk_fma_f32 v[126:127], v[158:159], v[36:37], v[126:127] op_sel_hi:[1,0,1]
	s_waitcnt vmcnt(18)
	v_cvt_pk_f32_fp8_e32 v[144:145], v100
	v_cvt_pk_f32_fp8_sdwa v[146:147], v100 src0_sel:WORD_1
	v_cvt_pk_f32_fp8_e32 v[148:149], v101
	v_cvt_pk_f32_fp8_sdwa v[150:151], v101 src0_sel:WORD_1
	v_cvt_pk_f32_fp8_e32 v[152:153], v102
	v_cvt_pk_f32_fp8_sdwa v[154:155], v102 src0_sel:WORD_1
	v_cvt_pk_f32_fp8_e32 v[156:157], v103
	v_cvt_pk_f32_fp8_sdwa v[158:159], v103 src0_sel:WORD_1
	v_pk_fma_f32 v[112:113], v[144:145], v[38:39], v[112:113] op_sel_hi:[1,0,1]
	v_pk_fma_f32 v[114:115], v[146:147], v[38:39], v[114:115] op_sel_hi:[1,0,1]
	v_pk_fma_f32 v[116:117], v[148:149], v[38:39], v[116:117] op_sel_hi:[1,0,1]
	v_pk_fma_f32 v[118:119], v[150:151], v[38:39], v[118:119] op_sel_hi:[1,0,1]
	v_pk_fma_f32 v[120:121], v[152:153], v[38:39], v[120:121] op_sel_hi:[1,0,1]
	v_pk_fma_f32 v[122:123], v[154:155], v[38:39], v[122:123] op_sel_hi:[1,0,1]
	v_pk_fma_f32 v[124:125], v[156:157], v[38:39], v[124:125] op_sel_hi:[1,0,1]
	v_pk_fma_f32 v[126:127], v[158:159], v[38:39], v[126:127] op_sel_hi:[1,0,1]
	s_waitcnt vmcnt(17)
	v_cvt_pk_f32_fp8_e32 v[144:145], v104
	v_cvt_pk_f32_fp8_sdwa v[146:147], v104 src0_sel:WORD_1
	v_cvt_pk_f32_fp8_e32 v[148:149], v105
	v_cvt_pk_f32_fp8_sdwa v[150:151], v105 src0_sel:WORD_1
	v_cvt_pk_f32_fp8_e32 v[152:153], v106
	v_cvt_pk_f32_fp8_sdwa v[154:155], v106 src0_sel:WORD_1
	v_cvt_pk_f32_fp8_e32 v[156:157], v107
	v_cvt_pk_f32_fp8_sdwa v[158:159], v107 src0_sel:WORD_1
	v_pk_fma_f32 v[112:113], v[144:145], v[40:41], v[112:113] op_sel_hi:[1,0,1]
	v_pk_fma_f32 v[114:115], v[146:147], v[40:41], v[114:115] op_sel_hi:[1,0,1]
	v_pk_fma_f32 v[116:117], v[148:149], v[40:41], v[116:117] op_sel_hi:[1,0,1]
	v_pk_fma_f32 v[118:119], v[150:151], v[40:41], v[118:119] op_sel_hi:[1,0,1]
	v_pk_fma_f32 v[120:121], v[152:153], v[40:41], v[120:121] op_sel_hi:[1,0,1]
	v_pk_fma_f32 v[122:123], v[154:155], v[40:41], v[122:123] op_sel_hi:[1,0,1]
	v_pk_fma_f32 v[124:125], v[156:157], v[40:41], v[124:125] op_sel_hi:[1,0,1]
	v_pk_fma_f32 v[126:127], v[158:159], v[40:41], v[126:127] op_sel_hi:[1,0,1]
	s_waitcnt vmcnt(16)
; __device__ __forceinline__ void peer_up_phase(const Ctx& C, const unsigned char* EU, bf16* XBN, float* RSS, float* xio, const float* gfinal, bool last, const float* SELG, const int* SELI) {
;     ...
;             for (int grp = 0; grp < 16; grp += 2) { USTEP(upA, grp); USTEP(upB, grp + 1); }
;     ...
;             f32x4 x0 = (f32x4){bflo(xw0[0]), bfhi(xw0[0]), bflo(xw0[1]), bfhi(xw0[1])}, x1 = (f32x4){bflo(xw0[2]), bfhi(xw0[2]), bflo(xw0[3]), bfhi(xw0[3])};
;             f32x4 x2 = (f32x4){bflo(xw1[0]), bfhi(xw1[0]), bflo(xw1[1]), bfhi(xw1[1])}, x3 = (f32x4){bflo(xw1[2]), bfhi(xw1[2]), bflo(xw1[3]), bfhi(xw1[3])};
;             x0 += (f32x4){y[0].x, y[0].y, y[1].x, y[1].y}; x1 += (f32x4){y[2].x, y[2].y, y[3].x, y[3].y}; x2 += (f32x4){y[4].x, y[4].y, y[5].x, y[5].y}; x3 += (f32x4){y[6].x, y[6].y, y[7].x, y[7].y};
;             if (last) {
;                 const float ss = (x0.x * x0.x + x0.y * x0.y) + (x0.z * x0.z + x0.w * x0.w) + (x1.x * x1.x + x1.y * x1.y) + (x1.z * x1.z + x1.w * x1.w)
;                                + (x2.x * x2.x + x2.y * x2.y) + (x2.z * x2.z + x2.w * x2.w) + (x3.x * x3.x + x3.y * x3.y) + (x3.z * x3.z + x3.w * x3.w);
;                 const float rstd = 1.0f / sqrtf(wave_sum(ss) * (1.f / DM) + RMS_EPS);
;                 float* xr = xio + tok * DM + 16 * gl;
;                 const float* gp = gfinal + 16 * gl;
;                 const f32x4 g0 = *(const f32x4*)gp, g1 = *(const f32x4*)(gp + 4), g2 = *(const f32x4*)(gp + 8), g3 = *(const f32x4*)(gp + 12);
;                 __builtin_nontemporal_store(x0 * rstd * g0, (f32x4*)xr); __builtin_nontemporal_store(x1 * rstd * g1, (f32x4*)(xr + 4)); __builtin_nontemporal_store(x2 * rstd * g2, (f32x4*)(xr + 8)); __builtin_nontemporal_store(x3 * rstd * g3, (f32x4*)(xr + 12));
;             } else {
;                 v4u w0, w1; w0.x = pk2(x0.x, x0.y); w0.y = pk2(x0.z, x0.w); w0.z = pk2(x1.x, x1.y); w0.w = pk2(x1.z, x1.w);
;                 w1.x = pk2(x2.x, x2.y); w1.y = pk2(x2.z, x2.w); w1.z = pk2(x3.x, x3.y); w1.w = pk2(x3.z, x3.w);
;                 float ss = 0.f;
; #pragma unroll
;                 for (int w = 0; w < 4; ++w) { const float a0 = bflo(w0[w]), a1 = bfhi(w0[w]), b0 = bflo(w1[w]), b1 = bfhi(w1[w]); ss += (a0 * a0 + a1 * a1) + (b0 * b0 + b1 * b1); }
;                 const float sst = wave_sum(ss);
;                 *(v4u*)xr16 = w0; *(v4u*)(xr16 + 8) = w1;
	v_cvt_pk_f32_fp8_e32 v[144:145], v108
	v_cvt_pk_f32_fp8_sdwa v[146:147], v108 src0_sel:WORD_1
	v_cvt_pk_f32_fp8_e32 v[148:149], v109
	v_cvt_pk_f32_fp8_sdwa v[150:151], v109 src0_sel:WORD_1
	v_cvt_pk_f32_fp8_e32 v[152:153], v110
	v_cvt_pk_f32_fp8_sdwa v[154:155], v110 src0_sel:WORD_1
	v_cvt_pk_f32_fp8_e32 v[156:157], v111
	v_cvt_pk_f32_fp8_sdwa v[158:159], v111 src0_sel:WORD_1
	v_pk_fma_f32 v[112:113], v[144:145], v[42:43], v[112:113] op_sel_hi:[1,0,1]
	v_pk_fma_f32 v[114:115], v[146:147], v[42:43], v[114:115] op_sel_hi:[1,0,1]
	v_pk_fma_f32 v[116:117], v[148:149], v[42:43], v[116:117] op_sel_hi:[1,0,1]
	v_pk_fma_f32 v[118:119], v[150:151], v[42:43], v[118:119] op_sel_hi:[1,0,1]
	v_pk_fma_f32 v[120:121], v[152:153], v[42:43], v[120:121] op_sel_hi:[1,0,1]
	v_pk_fma_f32 v[122:123], v[154:155], v[42:43], v[122:123] op_sel_hi:[1,0,1]
	v_pk_fma_f32 v[124:125], v[156:157], v[42:43], v[124:125] op_sel_hi:[1,0,1]
	v_pk_fma_f32 v[126:127], v[158:159], v[42:43], v[126:127] op_sel_hi:[1,0,1]
	v_add_u32_e32 v162, s16, v2
	ds_read_b64 v[28:29], v162 offset:512
	ds_read_b64 v[30:31], v162 offset:576
	ds_read_b64 v[32:33], v162 offset:640
	ds_read_b64 v[34:35], v162 offset:704
	ds_read_b64 v[36:37], v162 offset:768
	ds_read_b64 v[38:39], v162 offset:832
	ds_read_b64 v[40:41], v162 offset:896
	ds_read_b64 v[42:43], v162 offset:960
	s_waitcnt lgkmcnt(4)
	v_lshl_add_u32 v29, v29, 7, v1
	global_load_dwordx4 v[80:83], v29, s[8:9]
	v_lshl_add_u32 v31, v31, 7, v1
	global_load_dwordx4 v[84:87], v31, s[8:9]
	v_lshl_add_u32 v33, v33, 7, v1
	global_load_dwordx4 v[88:91], v33, s[8:9]
	v_lshl_add_u32 v35, v35, 7, v1
	global_load_dwordx4 v[92:95], v35, s[8:9]
	s_waitcnt lgkmcnt(0)
	v_lshl_add_u32 v37, v37, 7, v1
	global_load_dwordx4 v[96:99], v37, s[8:9]
	v_lshl_add_u32 v39, v39, 7, v1
	global_load_dwordx4 v[100:103], v39, s[8:9]
	v_lshl_add_u32 v41, v41, 7, v1
	global_load_dwordx4 v[104:107], v41, s[8:9]
	v_lshl_add_u32 v43, v43, 7, v1
	global_load_dwordx4 v[108:111], v43, s[8:9]
	s_nop 1
	v_permlane32_swap_b32_e32 v112, v120
	v_permlane32_swap_b32_e32 v113, v121
	v_permlane32_swap_b32_e32 v114, v122
	v_permlane32_swap_b32_e32 v115, v123
	v_permlane32_swap_b32_e32 v116, v124
	v_permlane32_swap_b32_e32 v117, v125
	v_permlane32_swap_b32_e32 v118, v126
	v_permlane32_swap_b32_e32 v119, v127
	v_add_f32_e32 v112, v112, v120
	v_add_f32_e32 v113, v113, v121
	v_add_f32_e32 v114, v114, v122
	v_add_f32_e32 v115, v115, v123
	v_add_f32_e32 v116, v116, v124
	v_add_f32_e32 v117, v117, v125
	v_add_f32_e32 v118, v118, v126
	v_add_f32_e32 v119, v119, v127
	s_nop 1
	v_permlane16_swap_b32_e32 v112, v116
	v_permlane16_swap_b32_e32 v113, v117
	v_permlane16_swap_b32_e32 v114, v118
	v_permlane16_swap_b32_e32 v115, v119
	v_add_f32_e32 v112, v112, v116
	v_add_f32_e32 v113, v113, v117
	v_add_f32_e32 v114, v114, v118
	v_add_f32_e32 v115, v115, v119
	s_nop 1
	v_add_f32_dpp v112, v112, v112 row_ror:8 row_mask:0xf bank_mask:0xf
	v_add_f32_dpp v113, v113, v113 row_ror:8 row_mask:0xf bank_mask:0xf
	v_add_f32_dpp v114, v114, v114 row_ror:8 row_mask:0xf bank_mask:0xf
	v_add_f32_dpp v115, v115, v115 row_ror:8 row_mask:0xf bank_mask:0xf
	s_lshl_b32 s2, s20, 8
	s_add_i32 s2, s2, s14
	s_lshl_b32 s2, s2, 11
	s_add_u32 s18, s10, s2
	s_addc_u32 s19, s11, 0
	s_waitcnt vmcnt(20)
	v_lshlrev_b32_e32 v44, 16, v10
	v_and_b32_e32 v45, 0xffff0000, v10
	v_lshlrev_b32_e32 v46, 16, v11
	v_and_b32_e32 v47, 0xffff0000, v11
	v_add_f32_e32 v44, v44, v112
	v_add_f32_e32 v45, v45, v113
	v_add_f32_e32 v46, v46, v114
	v_add_f32_e32 v47, v47, v115
	v_cvt_pk_bf16_f32 v164, v44, v45
	v_cvt_pk_bf16_f32 v165, v46, v47
	global_store_dwordx2 v5, v[164:165], s[18:19]
	v_lshlrev_b32_e32 v44, 16, v164
	v_and_b32_e32 v45, 0xffff0000, v164
	v_lshlrev_b32_e32 v46, 16, v165
	v_and_b32_e32 v47, 0xffff0000, v165
	v_mul_f32_e32 v44, v44, v44
	v_fmac_f32_e32 v44, v45, v45
	v_fmac_f32_e32 v44, v46, v46
	v_fmac_f32_e32 v44, v47, v47
	s_nop 1
	v_add_f32_dpp v44, v44, v44 quad_perm:[1,0,3,2] row_mask:0xf bank_mask:0xf
	s_nop 1
	v_add_f32_dpp v44, v44, v44 quad_perm:[2,3,0,1] row_mask:0xf bank_mask:0xf
	s_nop 1
	v_add_f32_dpp v44, v44, v44 row_half_mirror row_mask:0xf bank_mask:0xf
	v_mov_b32_e32 v45, v44
	s_nop 1
	v_permlane16_swap_b32_e32 v44, v45
	v_add_f32_e32 v44, v44, v45
	v_mov_b32_e32 v45, v44
	s_nop 1
	v_permlane32_swap_b32_e32 v44, v45
	v_add_f32_e32 v44, v44, v45
	s_lshl_b32 s2, s20, 8
	s_add_i32 s2, s2, s14
	s_lshl_b32 s2, s2, 6
	s_add_u32 s0, s12, s2
	s_addc_u32 s1, s13, 0
	s_mov_b64 exec, 1
	global_store_dword v160, v44, s[0:1]
	global_store_dword v160, v160, s[0:1] offset:32
	s_mov_b64 exec, -1
	s_add_i32 s17, s20, 1
	s_min_u32 s17, s17, 0xff
	s_lshl_b32 s2, s17, 8
	s_add_i32 s2, s2, s14
	s_lshl_b32 s2, s2, 11
	s_add_u32 s18, s10, s2
	s_addc_u32 s19, s11, 0
	global_load_dwordx2 v[10:11], v5, s[18:19]
	s_waitcnt vmcnt(20)
	v_add_u32_e32 v161, s15, v3
	ds_write_b64 v161, v[6:7]
	ds_write_b64 v161, v[8:9] offset:512
	s_add_i32 s17, s20, 3
	s_min_u32 s17, s17, 0xff
	s_lshl_b32 s2, s17, 8
	s_add_i32 s2, s2, s14
	s_lshl_b32 s2, s2, 9
	s_add_u32 s0, s6, s2
	s_addc_u32 s1, s7, 0
	global_load_dword v6, v4, s[0:1]
	global_load_dword v8, v4, s[0:1] offset:256
	s_add_u32 s0, s4, s2
	s_addc_u32 s1, s5, 0
	global_load_dword v7, v4, s[0:1]
	global_load_dword v9, v4, s[0:1] offset:256
	s_mov_b32 s15, s16
	s_add_i32 s20, s20, 1
	s_cmp_lt_u32 s20, 0x100
	s_cbranch_scc1 .Lupp_tok
	s_waitcnt vmcnt(0)
	s_branch .Lup_done
; __device__ __forceinline__ void peer_up_phase(const Ctx& C, const unsigned char* EU, bf16* XBN, float* RSS, float* xio, const float* gfinal, bool last, const float* SELG, const int* SELI) {
;     ...
; #pragma unroll 1
;             for (int grp = 0; grp < 16; grp += 2) { USTEP(upA, grp); USTEP(upB, grp + 1); }
.Lupl_new:
	v_readlane_b32 s0, v247, 53
	v_readlane_b32 s4, v249, 8
	v_readlane_b32 s5, v249, 9
	s_and_b32 s2, s0, 7
	s_lshl_b32 s14, s0, 5
	s_lshl_b32 s16, s2, 11
	s_lshl_b32 s17, s2, 8
	s_add_i32 s17, s17, 0x4000
	s_add_u32 s6, s4, 0x2b600000
	s_addc_u32 s7, s5, 0
	s_add_u32 s18, s4, 0x6600000
	s_addc_u32 s19, s5, 0
	s_add_u32 s4, s4, 0x2d600000
	s_addc_u32 s5, s5, 0
	v_and_b32_e32 v1, 7, v177
	v_lshlrev_b32_e32 v1, 4, v1
	v_lshrrev_b32_e32 v2, 3, v177
	v_lshlrev_b32_e32 v3, 3, v177
	v_add_u32_e32 v3, s16, v3
	v_lshl_add_u32 v2, v2, 3, s16
	v_lshlrev_b32_e32 v4, 2, v177
	v_and_b32_e32 v5, 7, v177
	v_lshlrev_b32_e32 v5, 5, v5
	v_bfe_u32 v44, v177, 5, 1
	v_lshl_or_b32 v5, v44, 4, v5
	v_bfe_u32 v44, v177, 4, 1
	v_lshl_or_b32 v5, v44, 3, v5
	v_lshlrev_b32_e32 v161, 1, v5
	v_mov_b32_e32 v160, 0
	v_add_u32_e32 v162, s17, v4
	ds_write_b32 v162, v160
	s_mov_b32 s15, 0
.Lupl_pass:
	s_lshl_b32 s0, s15, 21
	s_add_u32 s8, s18, s0
	s_addc_u32 s9, s19, 0
	s_lshl_b32 s0, s15, 8
	s_add_u32 s10, s60, s0
	s_addc_u32 s11, s61, 0
	v_readlane_b32 s12, v249, 6
	v_readlane_b32 s13, v249, 7
	s_lshl_b32 s0, s15, 9
	s_add_u32 s12, s12, s0
	s_addc_u32 s13, s13, 0
	s_mov_b32 s20, 0
	s_lshl_b32 s2, s14, 9
	s_add_u32 s0, s6, s2
	s_addc_u32 s1, s7, 0
	global_load_dword v6, v4, s[0:1]
	global_load_dword v8, v4, s[0:1] offset:256
	s_add_u32 s0, s4, s2
	s_addc_u32 s1, s5, 0
	global_load_dword v7, v4, s[0:1]
	global_load_dword v9, v4, s[0:1] offset:256
.Lupl_tok:
	s_add_i32 s2, s14, s20
	s_lshl_b32 s2, s2, 11
	s_add_u32 s16, s10, s2
	s_addc_u32 s17, s11, 0
	s_waitcnt vmcnt(0)
	ds_write_b64 v3, v[6:7]
	ds_write_b64 v3, v[8:9] offset:512
	global_load_dwordx2 v[10:11], v5, s[16:17]
	s_add_i32 s2, s20, 1
	s_and_b32 s2, s2, 31
	s_add_i32 s2, s2, s14
	s_lshl_b32 s2, s2, 9
	s_add_u32 s0, s6, s2
	s_addc_u32 s1, s7, 0
	global_load_dword v6, v4, s[0:1]
	global_load_dword v8, v4, s[0:1] offset:256
	s_add_u32 s0, s4, s2
	s_addc_u32 s1, s5, 0
	global_load_dword v7, v4, s[0:1]
	global_load_dword v9, v4, s[0:1] offset:256
	ds_read_b64 v[12:13], v2
	ds_read_b64 v[14:15], v2 offset:64
	ds_read_b64 v[16:17], v2 offset:128
	ds_read_b64 v[18:19], v2 offset:192
	ds_read_b64 v[20:21], v2 offset:256
	ds_read_b64 v[22:23], v2 offset:320
	ds_read_b64 v[24:25], v2 offset:384
	ds_read_b64 v[26:27], v2 offset:448
	ds_read_b64 v[28:29], v2 offset:512
	ds_read_b64 v[30:31], v2 offset:576
	ds_read_b64 v[32:33], v2 offset:640
	ds_read_b64 v[34:35], v2 offset:704
	ds_read_b64 v[36:37], v2 offset:768
	ds_read_b64 v[38:39], v2 offset:832
	ds_read_b64 v[40:41], v2 offset:896
	ds_read_b64 v[42:43], v2 offset:960
	v_mov_b64_e32 v[112:113], 0
	v_mov_b64_e32 v[114:115], 0
	v_mov_b64_e32 v[116:117], 0
	v_mov_b64_e32 v[118:119], 0
	v_mov_b64_e32 v[120:121], 0
	v_mov_b64_e32 v[122:123], 0
	v_mov_b64_e32 v[124:125], 0
	v_mov_b64_e32 v[126:127], 0
	s_waitcnt lgkmcnt(8)
	v_lshl_add_u32 v13, v13, 7, v1
	global_load_dwordx4 v[48:51], v13, s[8:9]
	v_lshl_add_u32 v15, v15, 7, v1
	global_load_dwordx4 v[52:55], v15, s[8:9]
	v_lshl_add_u32 v17, v17, 7, v1
	global_load_dwordx4 v[56:59], v17, s[8:9]
	v_lshl_add_u32 v19, v19, 7, v1
	global_load_dwordx4 v[60:63], v19, s[8:9]
	v_lshl_add_u32 v21, v21, 7, v1
	global_load_dwordx4 v[64:67], v21, s[8:9]
	v_lshl_add_u32 v23, v23, 7, v1
	global_load_dwordx4 v[68:71], v23, s[8:9]
	v_lshl_add_u32 v25, v25, 7, v1
	global_load_dwordx4 v[72:75], v25, s[8:9]
	v_lshl_add_u32 v27, v27, 7, v1
	global_load_dwordx4 v[76:79], v27, s[8:9]
	s_waitcnt lgkmcnt(0)
	v_lshl_add_u32 v29, v29, 7, v1
	global_load_dwordx4 v[80:83], v29, s[8:9]
	v_lshl_add_u32 v31, v31, 7, v1
	global_load_dwordx4 v[84:87], v31, s[8:9]
	v_lshl_add_u32 v33, v33, 7, v1
	global_load_dwordx4 v[88:91], v33, s[8:9]
	v_lshl_add_u32 v35, v35, 7, v1
	global_load_dwordx4 v[92:95], v35, s[8:9]
	v_lshl_add_u32 v37, v37, 7, v1
	global_load_dwordx4 v[96:99], v37, s[8:9]
	v_lshl_add_u32 v39, v39, 7, v1
	global_load_dwordx4 v[100:103], v39, s[8:9]
	v_lshl_add_u32 v41, v41, 7, v1
	global_load_dwordx4 v[104:107], v41, s[8:9]
	v_lshl_add_u32 v43, v43, 7, v1
	global_load_dwordx4 v[108:111], v43, s[8:9]
	s_waitcnt vmcnt(15)
	v_cvt_pk_f32_fp8_e32 v[144:145], v48
	v_cvt_pk_f32_fp8_sdwa v[146:147], v48 src0_sel:WORD_1
	v_cvt_pk_f32_fp8_e32 v[148:149], v49
	v_cvt_pk_f32_fp8_sdwa v[150:151], v49 src0_sel:WORD_1
	v_cvt_pk_f32_fp8_e32 v[152:153], v50
	v_cvt_pk_f32_fp8_sdwa v[154:155], v50 src0_sel:WORD_1
	v_cvt_pk_f32_fp8_e32 v[156:157], v51
	v_cvt_pk_f32_fp8_sdwa v[158:159], v51 src0_sel:WORD_1
	v_pk_fma_f32 v[112:113], v[144:145], v[12:13], v[112:113] op_sel_hi:[1,0,1]
	v_pk_fma_f32 v[114:115], v[146:147], v[12:13], v[114:115] op_sel_hi:[1,0,1]
	v_pk_fma_f32 v[116:117], v[148:149], v[12:13], v[116:117] op_sel_hi:[1,0,1]
	v_pk_fma_f32 v[118:119], v[150:151], v[12:13], v[118:119] op_sel_hi:[1,0,1]
	v_pk_fma_f32 v[120:121], v[152:153], v[12:13], v[120:121] op_sel_hi:[1,0,1]
	v_pk_fma_f32 v[122:123], v[154:155], v[12:13], v[122:123] op_sel_hi:[1,0,1]
	v_pk_fma_f32 v[124:125], v[156:157], v[12:13], v[124:125] op_sel_hi:[1,0,1]
	v_pk_fma_f32 v[126:127], v[158:159], v[12:13], v[126:127] op_sel_hi:[1,0,1]
	s_waitcnt vmcnt(14)
	v_cvt_pk_f32_fp8_e32 v[144:145], v52
	v_cvt_pk_f32_fp8_sdwa v[146:147], v52 src0_sel:WORD_1
	v_cvt_pk_f32_fp8_e32 v[148:149], v53
	v_cvt_pk_f32_fp8_sdwa v[150:151], v53 src0_sel:WORD_1
	v_cvt_pk_f32_fp8_e32 v[152:153], v54
	v_cvt_pk_f32_fp8_sdwa v[154:155], v54 src0_sel:WORD_1
	v_cvt_pk_f32_fp8_e32 v[156:157], v55
	v_cvt_pk_f32_fp8_sdwa v[158:159], v55 src0_sel:WORD_1
	v_pk_fma_f32 v[112:113], v[144:145], v[14:15], v[112:113] op_sel_hi:[1,0,1]
	v_pk_fma_f32 v[114:115], v[146:147], v[14:15], v[114:115] op_sel_hi:[1,0,1]
	v_pk_fma_f32 v[116:117], v[148:149], v[14:15], v[116:117] op_sel_hi:[1,0,1]
	v_pk_fma_f32 v[118:119], v[150:151], v[14:15], v[118:119] op_sel_hi:[1,0,1]
	v_pk_fma_f32 v[120:121], v[152:153], v[14:15], v[120:121] op_sel_hi:[1,0,1]
	v_pk_fma_f32 v[122:123], v[154:155], v[14:15], v[122:123] op_sel_hi:[1,0,1]
	v_pk_fma_f32 v[124:125], v[156:157], v[14:15], v[124:125] op_sel_hi:[1,0,1]
	v_pk_fma_f32 v[126:127], v[158:159], v[14:15], v[126:127] op_sel_hi:[1,0,1]
	s_waitcnt vmcnt(13)
; __device__ __forceinline__ void peer_up_phase(const Ctx& C, const unsigned char* EU, bf16* XBN, float* RSS, float* xio, const float* gfinal, bool last, const float* SELG, const int* SELI) {
;     ...
; #pragma unroll 1
;             for (int grp = 0; grp < 16; grp += 2) { USTEP(upA, grp); USTEP(upB, grp + 1); }
	v_cvt_pk_f32_fp8_e32 v[144:145], v56
	v_cvt_pk_f32_fp8_sdwa v[146:147], v56 src0_sel:WORD_1
	v_cvt_pk_f32_fp8_e32 v[148:149], v57
	v_cvt_pk_f32_fp8_sdwa v[150:151], v57 src0_sel:WORD_1
	v_cvt_pk_f32_fp8_e32 v[152:153], v58
	v_cvt_pk_f32_fp8_sdwa v[154:155], v58 src0_sel:WORD_1
	v_cvt_pk_f32_fp8_e32 v[156:157], v59
	v_cvt_pk_f32_fp8_sdwa v[158:159], v59 src0_sel:WORD_1
	v_pk_fma_f32 v[112:113], v[144:145], v[16:17], v[112:113] op_sel_hi:[1,0,1]
	v_pk_fma_f32 v[114:115], v[146:147], v[16:17], v[114:115] op_sel_hi:[1,0,1]
	v_pk_fma_f32 v[116:117], v[148:149], v[16:17], v[116:117] op_sel_hi:[1,0,1]
	v_pk_fma_f32 v[118:119], v[150:151], v[16:17], v[118:119] op_sel_hi:[1,0,1]
	v_pk_fma_f32 v[120:121], v[152:153], v[16:17], v[120:121] op_sel_hi:[1,0,1]
	v_pk_fma_f32 v[122:123], v[154:155], v[16:17], v[122:123] op_sel_hi:[1,0,1]
	v_pk_fma_f32 v[124:125], v[156:157], v[16:17], v[124:125] op_sel_hi:[1,0,1]
	v_pk_fma_f32 v[126:127], v[158:159], v[16:17], v[126:127] op_sel_hi:[1,0,1]
	s_waitcnt vmcnt(12)
	v_cvt_pk_f32_fp8_e32 v[144:145], v60
	v_cvt_pk_f32_fp8_sdwa v[146:147], v60 src0_sel:WORD_1
	v_cvt_pk_f32_fp8_e32 v[148:149], v61
	v_cvt_pk_f32_fp8_sdwa v[150:151], v61 src0_sel:WORD_1
	v_cvt_pk_f32_fp8_e32 v[152:153], v62
	v_cvt_pk_f32_fp8_sdwa v[154:155], v62 src0_sel:WORD_1
	v_cvt_pk_f32_fp8_e32 v[156:157], v63
	v_cvt_pk_f32_fp8_sdwa v[158:159], v63 src0_sel:WORD_1
	v_pk_fma_f32 v[112:113], v[144:145], v[18:19], v[112:113] op_sel_hi:[1,0,1]
	v_pk_fma_f32 v[114:115], v[146:147], v[18:19], v[114:115] op_sel_hi:[1,0,1]
	v_pk_fma_f32 v[116:117], v[148:149], v[18:19], v[116:117] op_sel_hi:[1,0,1]
	v_pk_fma_f32 v[118:119], v[150:151], v[18:19], v[118:119] op_sel_hi:[1,0,1]
	v_pk_fma_f32 v[120:121], v[152:153], v[18:19], v[120:121] op_sel_hi:[1,0,1]
	v_pk_fma_f32 v[122:123], v[154:155], v[18:19], v[122:123] op_sel_hi:[1,0,1]
	v_pk_fma_f32 v[124:125], v[156:157], v[18:19], v[124:125] op_sel_hi:[1,0,1]
	v_pk_fma_f32 v[126:127], v[158:159], v[18:19], v[126:127] op_sel_hi:[1,0,1]
	s_waitcnt vmcnt(11)
	v_cvt_pk_f32_fp8_e32 v[144:145], v64
	v_cvt_pk_f32_fp8_sdwa v[146:147], v64 src0_sel:WORD_1
	v_cvt_pk_f32_fp8_e32 v[148:149], v65
	v_cvt_pk_f32_fp8_sdwa v[150:151], v65 src0_sel:WORD_1
	v_cvt_pk_f32_fp8_e32 v[152:153], v66
	v_cvt_pk_f32_fp8_sdwa v[154:155], v66 src0_sel:WORD_1
	v_cvt_pk_f32_fp8_e32 v[156:157], v67
	v_cvt_pk_f32_fp8_sdwa v[158:159], v67 src0_sel:WORD_1
	v_pk_fma_f32 v[112:113], v[144:145], v[20:21], v[112:113] op_sel_hi:[1,0,1]
	v_pk_fma_f32 v[114:115], v[146:147], v[20:21], v[114:115] op_sel_hi:[1,0,1]
	v_pk_fma_f32 v[116:117], v[148:149], v[20:21], v[116:117] op_sel_hi:[1,0,1]
	v_pk_fma_f32 v[118:119], v[150:151], v[20:21], v[118:119] op_sel_hi:[1,0,1]
	v_pk_fma_f32 v[120:121], v[152:153], v[20:21], v[120:121] op_sel_hi:[1,0,1]
	v_pk_fma_f32 v[122:123], v[154:155], v[20:21], v[122:123] op_sel_hi:[1,0,1]
	v_pk_fma_f32 v[124:125], v[156:157], v[20:21], v[124:125] op_sel_hi:[1,0,1]
	v_pk_fma_f32 v[126:127], v[158:159], v[20:21], v[126:127] op_sel_hi:[1,0,1]
	s_waitcnt vmcnt(10)
	v_cvt_pk_f32_fp8_e32 v[144:145], v68
	v_cvt_pk_f32_fp8_sdwa v[146:147], v68 src0_sel:WORD_1
	v_cvt_pk_f32_fp8_e32 v[148:149], v69
	v_cvt_pk_f32_fp8_sdwa v[150:151], v69 src0_sel:WORD_1
	v_cvt_pk_f32_fp8_e32 v[152:153], v70
	v_cvt_pk_f32_fp8_sdwa v[154:155], v70 src0_sel:WORD_1
	v_cvt_pk_f32_fp8_e32 v[156:157], v71
	v_cvt_pk_f32_fp8_sdwa v[158:159], v71 src0_sel:WORD_1
	v_pk_fma_f32 v[112:113], v[144:145], v[22:23], v[112:113] op_sel_hi:[1,0,1]
	v_pk_fma_f32 v[114:115], v[146:147], v[22:23], v[114:115] op_sel_hi:[1,0,1]
	v_pk_fma_f32 v[116:117], v[148:149], v[22:23], v[116:117] op_sel_hi:[1,0,1]
	v_pk_fma_f32 v[118:119], v[150:151], v[22:23], v[118:119] op_sel_hi:[1,0,1]
	v_pk_fma_f32 v[120:121], v[152:153], v[22:23], v[120:121] op_sel_hi:[1,0,1]
	v_pk_fma_f32 v[122:123], v[154:155], v[22:23], v[122:123] op_sel_hi:[1,0,1]
	v_pk_fma_f32 v[124:125], v[156:157], v[22:23], v[124:125] op_sel_hi:[1,0,1]
	v_pk_fma_f32 v[126:127], v[158:159], v[22:23], v[126:127] op_sel_hi:[1,0,1]
	s_waitcnt vmcnt(9)
	v_cvt_pk_f32_fp8_e32 v[144:145], v72
	v_cvt_pk_f32_fp8_sdwa v[146:147], v72 src0_sel:WORD_1
	v_cvt_pk_f32_fp8_e32 v[148:149], v73
	v_cvt_pk_f32_fp8_sdwa v[150:151], v73 src0_sel:WORD_1
	v_cvt_pk_f32_fp8_e32 v[152:153], v74
	v_cvt_pk_f32_fp8_sdwa v[154:155], v74 src0_sel:WORD_1
	v_cvt_pk_f32_fp8_e32 v[156:157], v75
	v_cvt_pk_f32_fp8_sdwa v[158:159], v75 src0_sel:WORD_1
	v_pk_fma_f32 v[112:113], v[144:145], v[24:25], v[112:113] op_sel_hi:[1,0,1]
	v_pk_fma_f32 v[114:115], v[146:147], v[24:25], v[114:115] op_sel_hi:[1,0,1]
	v_pk_fma_f32 v[116:117], v[148:149], v[24:25], v[116:117] op_sel_hi:[1,0,1]
	v_pk_fma_f32 v[118:119], v[150:151], v[24:25], v[118:119] op_sel_hi:[1,0,1]
	v_pk_fma_f32 v[120:121], v[152:153], v[24:25], v[120:121] op_sel_hi:[1,0,1]
	v_pk_fma_f32 v[122:123], v[154:155], v[24:25], v[122:123] op_sel_hi:[1,0,1]
	v_pk_fma_f32 v[124:125], v[156:157], v[24:25], v[124:125] op_sel_hi:[1,0,1]
	v_pk_fma_f32 v[126:127], v[158:159], v[24:25], v[126:127] op_sel_hi:[1,0,1]
	s_waitcnt vmcnt(8)
	v_cvt_pk_f32_fp8_e32 v[144:145], v76
	v_cvt_pk_f32_fp8_sdwa v[146:147], v76 src0_sel:WORD_1
	v_cvt_pk_f32_fp8_e32 v[148:149], v77
	v_cvt_pk_f32_fp8_sdwa v[150:151], v77 src0_sel:WORD_1
	v_cvt_pk_f32_fp8_e32 v[152:153], v78
	v_cvt_pk_f32_fp8_sdwa v[154:155], v78 src0_sel:WORD_1
	v_cvt_pk_f32_fp8_e32 v[156:157], v79
	v_cvt_pk_f32_fp8_sdwa v[158:159], v79 src0_sel:WORD_1
	v_pk_fma_f32 v[112:113], v[144:145], v[26:27], v[112:113] op_sel_hi:[1,0,1]
	v_pk_fma_f32 v[114:115], v[146:147], v[26:27], v[114:115] op_sel_hi:[1,0,1]
	v_pk_fma_f32 v[116:117], v[148:149], v[26:27], v[116:117] op_sel_hi:[1,0,1]
	v_pk_fma_f32 v[118:119], v[150:151], v[26:27], v[118:119] op_sel_hi:[1,0,1]
	v_pk_fma_f32 v[120:121], v[152:153], v[26:27], v[120:121] op_sel_hi:[1,0,1]
	v_pk_fma_f32 v[122:123], v[154:155], v[26:27], v[122:123] op_sel_hi:[1,0,1]
	v_pk_fma_f32 v[124:125], v[156:157], v[26:27], v[124:125] op_sel_hi:[1,0,1]
	v_pk_fma_f32 v[126:127], v[158:159], v[26:27], v[126:127] op_sel_hi:[1,0,1]
	s_waitcnt vmcnt(7)
; __device__ __forceinline__ void peer_up_phase(const Ctx& C, const unsigned char* EU, bf16* XBN, float* RSS, float* xio, const float* gfinal, bool last, const float* SELG, const int* SELI) {
;     ...
; #pragma unroll 1
;             for (int grp = 0; grp < 16; grp += 2) { USTEP(upA, grp); USTEP(upB, grp + 1); }
	v_cvt_pk_f32_fp8_e32 v[144:145], v80
	v_cvt_pk_f32_fp8_sdwa v[146:147], v80 src0_sel:WORD_1
	v_cvt_pk_f32_fp8_e32 v[148:149], v81
	v_cvt_pk_f32_fp8_sdwa v[150:151], v81 src0_sel:WORD_1
	v_cvt_pk_f32_fp8_e32 v[152:153], v82
	v_cvt_pk_f32_fp8_sdwa v[154:155], v82 src0_sel:WORD_1
	v_cvt_pk_f32_fp8_e32 v[156:157], v83
	v_cvt_pk_f32_fp8_sdwa v[158:159], v83 src0_sel:WORD_1
	v_pk_fma_f32 v[112:113], v[144:145], v[28:29], v[112:113] op_sel_hi:[1,0,1]
	v_pk_fma_f32 v[114:115], v[146:147], v[28:29], v[114:115] op_sel_hi:[1,0,1]
	v_pk_fma_f32 v[116:117], v[148:149], v[28:29], v[116:117] op_sel_hi:[1,0,1]
	v_pk_fma_f32 v[118:119], v[150:151], v[28:29], v[118:119] op_sel_hi:[1,0,1]
	v_pk_fma_f32 v[120:121], v[152:153], v[28:29], v[120:121] op_sel_hi:[1,0,1]
	v_pk_fma_f32 v[122:123], v[154:155], v[28:29], v[122:123] op_sel_hi:[1,0,1]
	v_pk_fma_f32 v[124:125], v[156:157], v[28:29], v[124:125] op_sel_hi:[1,0,1]
	v_pk_fma_f32 v[126:127], v[158:159], v[28:29], v[126:127] op_sel_hi:[1,0,1]
	s_waitcnt vmcnt(6)
	v_cvt_pk_f32_fp8_e32 v[144:145], v84
	v_cvt_pk_f32_fp8_sdwa v[146:147], v84 src0_sel:WORD_1
	v_cvt_pk_f32_fp8_e32 v[148:149], v85
	v_cvt_pk_f32_fp8_sdwa v[150:151], v85 src0_sel:WORD_1
	v_cvt_pk_f32_fp8_e32 v[152:153], v86
	v_cvt_pk_f32_fp8_sdwa v[154:155], v86 src0_sel:WORD_1
	v_cvt_pk_f32_fp8_e32 v[156:157], v87
	v_cvt_pk_f32_fp8_sdwa v[158:159], v87 src0_sel:WORD_1
	v_pk_fma_f32 v[112:113], v[144:145], v[30:31], v[112:113] op_sel_hi:[1,0,1]
	v_pk_fma_f32 v[114:115], v[146:147], v[30:31], v[114:115] op_sel_hi:[1,0,1]
	v_pk_fma_f32 v[116:117], v[148:149], v[30:31], v[116:117] op_sel_hi:[1,0,1]
	v_pk_fma_f32 v[118:119], v[150:151], v[30:31], v[118:119] op_sel_hi:[1,0,1]
	v_pk_fma_f32 v[120:121], v[152:153], v[30:31], v[120:121] op_sel_hi:[1,0,1]
	v_pk_fma_f32 v[122:123], v[154:155], v[30:31], v[122:123] op_sel_hi:[1,0,1]
	v_pk_fma_f32 v[124:125], v[156:157], v[30:31], v[124:125] op_sel_hi:[1,0,1]
	v_pk_fma_f32 v[126:127], v[158:159], v[30:31], v[126:127] op_sel_hi:[1,0,1]
	s_waitcnt vmcnt(5)
	v_cvt_pk_f32_fp8_e32 v[144:145], v88
	v_cvt_pk_f32_fp8_sdwa v[146:147], v88 src0_sel:WORD_1
	v_cvt_pk_f32_fp8_e32 v[148:149], v89
	v_cvt_pk_f32_fp8_sdwa v[150:151], v89 src0_sel:WORD_1
	v_cvt_pk_f32_fp8_e32 v[152:153], v90
	v_cvt_pk_f32_fp8_sdwa v[154:155], v90 src0_sel:WORD_1
	v_cvt_pk_f32_fp8_e32 v[156:157], v91
	v_cvt_pk_f32_fp8_sdwa v[158:159], v91 src0_sel:WORD_1
	v_pk_fma_f32 v[112:113], v[144:145], v[32:33], v[112:113] op_sel_hi:[1,0,1]
	v_pk_fma_f32 v[114:115], v[146:147], v[32:33], v[114:115] op_sel_hi:[1,0,1]
	v_pk_fma_f32 v[116:117], v[148:149], v[32:33], v[116:117] op_sel_hi:[1,0,1]
	v_pk_fma_f32 v[118:119], v[150:151], v[32:33], v[118:119] op_sel_hi:[1,0,1]
	v_pk_fma_f32 v[120:121], v[152:153], v[32:33], v[120:121] op_sel_hi:[1,0,1]
	v_pk_fma_f32 v[122:123], v[154:155], v[32:33], v[122:123] op_sel_hi:[1,0,1]
	v_pk_fma_f32 v[124:125], v[156:157], v[32:33], v[124:125] op_sel_hi:[1,0,1]
	v_pk_fma_f32 v[126:127], v[158:159], v[32:33], v[126:127] op_sel_hi:[1,0,1]
	s_waitcnt vmcnt(4)
	v_cvt_pk_f32_fp8_e32 v[144:145], v92
	v_cvt_pk_f32_fp8_sdwa v[146:147], v92 src0_sel:WORD_1
	v_cvt_pk_f32_fp8_e32 v[148:149], v93
	v_cvt_pk_f32_fp8_sdwa v[150:151], v93 src0_sel:WORD_1
	v_cvt_pk_f32_fp8_e32 v[152:153], v94
	v_cvt_pk_f32_fp8_sdwa v[154:155], v94 src0_sel:WORD_1
	v_cvt_pk_f32_fp8_e32 v[156:157], v95
	v_cvt_pk_f32_fp8_sdwa v[158:159], v95 src0_sel:WORD_1
	v_pk_fma_f32 v[112:113], v[144:145], v[34:35], v[112:113] op_sel_hi:[1,0,1]
	v_pk_fma_f32 v[114:115], v[146:147], v[34:35], v[114:115] op_sel_hi:[1,0,1]
	v_pk_fma_f32 v[116:117], v[148:149], v[34:35], v[116:117] op_sel_hi:[1,0,1]
	v_pk_fma_f32 v[118:119], v[150:151], v[34:35], v[118:119] op_sel_hi:[1,0,1]
	v_pk_fma_f32 v[120:121], v[152:153], v[34:35], v[120:121] op_sel_hi:[1,0,1]
	v_pk_fma_f32 v[122:123], v[154:155], v[34:35], v[122:123] op_sel_hi:[1,0,1]
	v_pk_fma_f32 v[124:125], v[156:157], v[34:35], v[124:125] op_sel_hi:[1,0,1]
	v_pk_fma_f32 v[126:127], v[158:159], v[34:35], v[126:127] op_sel_hi:[1,0,1]
	s_waitcnt vmcnt(3)
	v_cvt_pk_f32_fp8_e32 v[144:145], v96
	v_cvt_pk_f32_fp8_sdwa v[146:147], v96 src0_sel:WORD_1
	v_cvt_pk_f32_fp8_e32 v[148:149], v97
	v_cvt_pk_f32_fp8_sdwa v[150:151], v97 src0_sel:WORD_1
	v_cvt_pk_f32_fp8_e32 v[152:153], v98
	v_cvt_pk_f32_fp8_sdwa v[154:155], v98 src0_sel:WORD_1
	v_cvt_pk_f32_fp8_e32 v[156:157], v99
	v_cvt_pk_f32_fp8_sdwa v[158:159], v99 src0_sel:WORD_1
	v_pk_fma_f32 v[112:113], v[144:145], v[36:37], v[112:113] op_sel_hi:[1,0,1]
	v_pk_fma_f32 v[114:115], v[146:147], v[36:37], v[114:115] op_sel_hi:[1,0,1]
	v_pk_fma_f32 v[116:117], v[148:149], v[36:37], v[116:117] op_sel_hi:[1,0,1]
	v_pk_fma_f32 v[118:119], v[150:151], v[36:37], v[118:119] op_sel_hi:[1,0,1]
	v_pk_fma_f32 v[120:121], v[152:153], v[36:37], v[120:121] op_sel_hi:[1,0,1]
	v_pk_fma_f32 v[122:123], v[154:155], v[36:37], v[122:123] op_sel_hi:[1,0,1]
	v_pk_fma_f32 v[124:125], v[156:157], v[36:37], v[124:125] op_sel_hi:[1,0,1]
	v_pk_fma_f32 v[126:127], v[158:159], v[36:37], v[126:127] op_sel_hi:[1,0,1]
	s_waitcnt vmcnt(2)
	v_cvt_pk_f32_fp8_e32 v[144:145], v100
	v_cvt_pk_f32_fp8_sdwa v[146:147], v100 src0_sel:WORD_1
	v_cvt_pk_f32_fp8_e32 v[148:149], v101
	v_cvt_pk_f32_fp8_sdwa v[150:151], v101 src0_sel:WORD_1
	v_cvt_pk_f32_fp8_e32 v[152:153], v102
	v_cvt_pk_f32_fp8_sdwa v[154:155], v102 src0_sel:WORD_1
	v_cvt_pk_f32_fp8_e32 v[156:157], v103
	v_cvt_pk_f32_fp8_sdwa v[158:159], v103 src0_sel:WORD_1
	v_pk_fma_f32 v[112:113], v[144:145], v[38:39], v[112:113] op_sel_hi:[1,0,1]
	v_pk_fma_f32 v[114:115], v[146:147], v[38:39], v[114:115] op_sel_hi:[1,0,1]
	v_pk_fma_f32 v[116:117], v[148:149], v[38:39], v[116:117] op_sel_hi:[1,0,1]
	v_pk_fma_f32 v[118:119], v[150:151], v[38:39], v[118:119] op_sel_hi:[1,0,1]
	v_pk_fma_f32 v[120:121], v[152:153], v[38:39], v[120:121] op_sel_hi:[1,0,1]
	v_pk_fma_f32 v[122:123], v[154:155], v[38:39], v[122:123] op_sel_hi:[1,0,1]
	v_pk_fma_f32 v[124:125], v[156:157], v[38:39], v[124:125] op_sel_hi:[1,0,1]
	v_pk_fma_f32 v[126:127], v[158:159], v[38:39], v[126:127] op_sel_hi:[1,0,1]
	s_waitcnt vmcnt(1)
; __device__ __forceinline__ void peer_up_phase(const Ctx& C, const unsigned char* EU, bf16* XBN, float* RSS, float* xio, const float* gfinal, bool last, const float* SELG, const int* SELI) {
;     ...
; #pragma unroll 1
;             for (int grp = 0; grp < 16; grp += 2) { USTEP(upA, grp); USTEP(upB, grp + 1); }
;     ...
;             f32x4 x0 = (f32x4){bflo(xw0[0]), bfhi(xw0[0]), bflo(xw0[1]), bfhi(xw0[1])}, x1 = (f32x4){bflo(xw0[2]), bfhi(xw0[2]), bflo(xw0[3]), bfhi(xw0[3])};
;             f32x4 x2 = (f32x4){bflo(xw1[0]), bfhi(xw1[0]), bflo(xw1[1]), bfhi(xw1[1])}, x3 = (f32x4){bflo(xw1[2]), bfhi(xw1[2]), bflo(xw1[3]), bfhi(xw1[3])};
;             x0 += (f32x4){y[0].x, y[0].y, y[1].x, y[1].y}; x1 += (f32x4){y[2].x, y[2].y, y[3].x, y[3].y}; x2 += (f32x4){y[4].x, y[4].y, y[5].x, y[5].y}; x3 += (f32x4){y[6].x, y[6].y, y[7].x, y[7].y};
;             if (last) {
;                 const float ss = (x0.x * x0.x + x0.y * x0.y) + (x0.z * x0.z + x0.w * x0.w) + (x1.x * x1.x + x1.y * x1.y) + (x1.z * x1.z + x1.w * x1.w)
;                                + (x2.x * x2.x + x2.y * x2.y) + (x2.z * x2.z + x2.w * x2.w) + (x3.x * x3.x + x3.y * x3.y) + (x3.z * x3.z + x3.w * x3.w);
;                 const float rstd = 1.0f / sqrtf(wave_sum(ss) * (1.f / DM) + RMS_EPS);
;                 float* xr = xio + tok * DM + 16 * gl;
;                 const float* gp = gfinal + 16 * gl;
;                 const f32x4 g0 = *(const f32x4*)gp, g1 = *(const f32x4*)(gp + 4), g2 = *(const f32x4*)(gp + 8), g3 = *(const f32x4*)(gp + 12);
;                 __builtin_nontemporal_store(x0 * rstd * g0, (f32x4*)xr); __builtin_nontemporal_store(x1 * rstd * g1, (f32x4*)(xr + 4)); __builtin_nontemporal_store(x2 * rstd * g2, (f32x4*)(xr + 8)); __builtin_nontemporal_store(x3 * rstd * g3, (f32x4*)(xr + 12));
	v_cvt_pk_f32_fp8_e32 v[144:145], v104
	v_cvt_pk_f32_fp8_sdwa v[146:147], v104 src0_sel:WORD_1
	v_cvt_pk_f32_fp8_e32 v[148:149], v105
	v_cvt_pk_f32_fp8_sdwa v[150:151], v105 src0_sel:WORD_1
	v_cvt_pk_f32_fp8_e32 v[152:153], v106
	v_cvt_pk_f32_fp8_sdwa v[154:155], v106 src0_sel:WORD_1
	v_cvt_pk_f32_fp8_e32 v[156:157], v107
	v_cvt_pk_f32_fp8_sdwa v[158:159], v107 src0_sel:WORD_1
	v_pk_fma_f32 v[112:113], v[144:145], v[40:41], v[112:113] op_sel_hi:[1,0,1]
	v_pk_fma_f32 v[114:115], v[146:147], v[40:41], v[114:115] op_sel_hi:[1,0,1]
	v_pk_fma_f32 v[116:117], v[148:149], v[40:41], v[116:117] op_sel_hi:[1,0,1]
	v_pk_fma_f32 v[118:119], v[150:151], v[40:41], v[118:119] op_sel_hi:[1,0,1]
	v_pk_fma_f32 v[120:121], v[152:153], v[40:41], v[120:121] op_sel_hi:[1,0,1]
	v_pk_fma_f32 v[122:123], v[154:155], v[40:41], v[122:123] op_sel_hi:[1,0,1]
	v_pk_fma_f32 v[124:125], v[156:157], v[40:41], v[124:125] op_sel_hi:[1,0,1]
	v_pk_fma_f32 v[126:127], v[158:159], v[40:41], v[126:127] op_sel_hi:[1,0,1]
	s_waitcnt vmcnt(0)
	v_cvt_pk_f32_fp8_e32 v[144:145], v108
	v_cvt_pk_f32_fp8_sdwa v[146:147], v108 src0_sel:WORD_1
	v_cvt_pk_f32_fp8_e32 v[148:149], v109
	v_cvt_pk_f32_fp8_sdwa v[150:151], v109 src0_sel:WORD_1
	v_cvt_pk_f32_fp8_e32 v[152:153], v110
	v_cvt_pk_f32_fp8_sdwa v[154:155], v110 src0_sel:WORD_1
	v_cvt_pk_f32_fp8_e32 v[156:157], v111
	v_cvt_pk_f32_fp8_sdwa v[158:159], v111 src0_sel:WORD_1
	v_pk_fma_f32 v[112:113], v[144:145], v[42:43], v[112:113] op_sel_hi:[1,0,1]
	v_pk_fma_f32 v[114:115], v[146:147], v[42:43], v[114:115] op_sel_hi:[1,0,1]
	v_pk_fma_f32 v[116:117], v[148:149], v[42:43], v[116:117] op_sel_hi:[1,0,1]
	v_pk_fma_f32 v[118:119], v[150:151], v[42:43], v[118:119] op_sel_hi:[1,0,1]
	v_pk_fma_f32 v[120:121], v[152:153], v[42:43], v[120:121] op_sel_hi:[1,0,1]
	v_pk_fma_f32 v[122:123], v[154:155], v[42:43], v[122:123] op_sel_hi:[1,0,1]
	v_pk_fma_f32 v[124:125], v[156:157], v[42:43], v[124:125] op_sel_hi:[1,0,1]
	v_pk_fma_f32 v[126:127], v[158:159], v[42:43], v[126:127] op_sel_hi:[1,0,1]
	s_nop 1
	v_permlane32_swap_b32_e32 v112, v120
	v_permlane32_swap_b32_e32 v113, v121
	v_permlane32_swap_b32_e32 v114, v122
	v_permlane32_swap_b32_e32 v115, v123
	v_permlane32_swap_b32_e32 v116, v124
	v_permlane32_swap_b32_e32 v117, v125
	v_permlane32_swap_b32_e32 v118, v126
	v_permlane32_swap_b32_e32 v119, v127
	v_add_f32_e32 v112, v112, v120
	v_add_f32_e32 v113, v113, v121
	v_add_f32_e32 v114, v114, v122
	v_add_f32_e32 v115, v115, v123
	v_add_f32_e32 v116, v116, v124
	v_add_f32_e32 v117, v117, v125
	v_add_f32_e32 v118, v118, v126
	v_add_f32_e32 v119, v119, v127
	s_nop 1
	v_permlane16_swap_b32_e32 v112, v116
	v_permlane16_swap_b32_e32 v113, v117
	v_permlane16_swap_b32_e32 v114, v118
	v_permlane16_swap_b32_e32 v115, v119
	v_add_f32_e32 v112, v112, v116
	v_add_f32_e32 v113, v113, v117
	v_add_f32_e32 v114, v114, v118
	v_add_f32_e32 v115, v115, v119
	s_nop 1
	v_add_f32_dpp v112, v112, v112 row_ror:8 row_mask:0xf bank_mask:0xf
	v_add_f32_dpp v113, v113, v113 row_ror:8 row_mask:0xf bank_mask:0xf
	v_add_f32_dpp v114, v114, v114 row_ror:8 row_mask:0xf bank_mask:0xf
	v_add_f32_dpp v115, v115, v115 row_ror:8 row_mask:0xf bank_mask:0xf
	v_lshlrev_b32_e32 v44, 16, v10
	v_and_b32_e32 v45, 0xffff0000, v10
	v_lshlrev_b32_e32 v46, 16, v11
	v_and_b32_e32 v47, 0xffff0000, v11
	v_add_f32_e32 v44, v44, v112
	v_add_f32_e32 v45, v45, v113
	v_add_f32_e32 v46, v46, v114
	v_add_f32_e32 v47, v47, v115
	s_add_i32 s2, s14, s20
	s_lshl_b32 s2, s2, 12
	s_add_u32 s0, s12, s2
	s_addc_u32 s1, s13, 0
	global_store_dwordx4 v161, v[44:47], s[0:1]
	v_mul_f32_e32 v163, v44, v44
	v_fmac_f32_e32 v163, v45, v45
	v_fmac_f32_e32 v163, v46, v46
	v_fmac_f32_e32 v163, v47, v47
	s_nop 1
	v_add_f32_dpp v163, v163, v163 quad_perm:[1,0,3,2] row_mask:0xf bank_mask:0xf
	s_nop 1
	v_add_f32_dpp v163, v163, v163 quad_perm:[2,3,0,1] row_mask:0xf bank_mask:0xf
	s_nop 1
	v_add_f32_dpp v163, v163, v163 row_half_mirror row_mask:0xf bank_mask:0xf
	v_mov_b32_e32 v164, v163
	s_nop 1
	v_permlane16_swap_b32_e32 v163, v164
	v_add_f32_e32 v163, v163, v164
	v_mov_b32_e32 v164, v163
	s_nop 1
	v_permlane32_swap_b32_e32 v163, v164
	v_add_f32_e32 v163, v163, v164
	s_lshl_b32 s2, s20, 2
	v_add_u32_e32 v164, s2, v162
	s_mov_b64 exec, 1
	ds_add_f32 v164, v163
	s_mov_b64 exec, -1
	s_add_i32 s20, s20, 1
	s_cmp_lt_u32 s20, 32
	s_cbranch_scc1 .Lupl_tok
	s_add_i32 s15, s15, 1
	s_cmp_lt_u32 s15, 8
	s_cbranch_scc1 .Lupl_pass
	v_readlane_b32 s8, v249, 4
	v_readlane_b32 s9, v249, 5
	v_readlane_b32 s12, v249, 6
	v_readlane_b32 s13, v249, 7
	v_lshlrev_b32_e32 v8, 6, v177
	s_nop 0
	global_load_dwordx4 v[16:19], v8, s[8:9]
	global_load_dwordx4 v[20:23], v8, s[8:9] offset:16
	global_load_dwordx4 v[24:27], v8, s[8:9] offset:32
	global_load_dwordx4 v[28:31], v8, s[8:9] offset:48
	v_subrev_u32_e32 v9, v4, v162
	s_mov_b32 s20, 0
	s_waitcnt vmcnt(0)
.Lupl_fin:
	s_add_i32 s2, s14, s20
	s_lshl_b32 s2, s2, 12
	s_add_u32 s0, s12, s2
	s_addc_u32 s1, s13, 0
	global_load_dwordx4 v[32:35], v8, s[0:1] sc1
	global_load_dwordx4 v[36:39], v8, s[0:1] offset:16 sc1
	global_load_dwordx4 v[40:43], v8, s[0:1] offset:32 sc1
	global_load_dwordx4 v[44:47], v8, s[0:1] offset:48 sc1
	s_lshl_b32 s2, s20, 2
	v_add_u32_e32 v10, s2, v9
	ds_read_b32 v11, v10
	s_waitcnt lgkmcnt(0)
	v_mov_b32_e32 v12, 0x358637bd
	v_fmac_f32_e32 v12, 0x3a800000, v11
	v_rsq_f32_e32 v12, v12
	s_waitcnt vmcnt(0)
	v_mul_f32_e32 v32, v32, v12
	v_mul_f32_e32 v33, v33, v12
	v_mul_f32_e32 v34, v34, v12
	v_mul_f32_e32 v35, v35, v12
	v_mul_f32_e32 v36, v36, v12
	v_mul_f32_e32 v37, v37, v12
	v_mul_f32_e32 v38, v38, v12
	v_mul_f32_e32 v39, v39, v12
	v_mul_f32_e32 v40, v40, v12
	v_mul_f32_e32 v41, v41, v12
	v_mul_f32_e32 v42, v42, v12
	v_mul_f32_e32 v43, v43, v12
	v_mul_f32_e32 v44, v44, v12
	v_mul_f32_e32 v45, v45, v12
	v_mul_f32_e32 v46, v46, v12
	v_mul_f32_e32 v47, v47, v12
	v_mul_f32_e32 v32, v32, v16
	v_mul_f32_e32 v33, v33, v17
	v_mul_f32_e32 v34, v34, v18
	v_mul_f32_e32 v35, v35, v19
	v_mul_f32_e32 v36, v36, v20
	v_mul_f32_e32 v37, v37, v21
	v_mul_f32_e32 v38, v38, v22
	v_mul_f32_e32 v39, v39, v23
	v_mul_f32_e32 v40, v40, v24
	v_mul_f32_e32 v41, v41, v25
	v_mul_f32_e32 v42, v42, v26
	v_mul_f32_e32 v43, v43, v27
	v_mul_f32_e32 v44, v44, v28
	v_mul_f32_e32 v45, v45, v29
	v_mul_f32_e32 v46, v46, v30
	v_mul_f32_e32 v47, v47, v31
	global_store_dwordx4 v8, v[32:35], s[0:1]
	global_store_dwordx4 v8, v[36:39], s[0:1] offset:16
	global_store_dwordx4 v8, v[40:43], s[0:1] offset:32
	global_store_dwordx4 v8, v[44:47], s[0:1] offset:48
	s_add_i32 s20, s20, 1
	s_cmp_lt_u32 s20, 32
	s_cbranch_scc1 .Lupl_fin
	s_branch .Lup_done
